# kpair variant: B-fragment-major with boustrophedon A order + dropwaits + rotary
# baseline (speedup 1.0000x reference)
.LBB0_642:
	ds_read_b128 v[148:151], v139
	ds_read_b128 v[152:155], v139 offset:1024
	ds_read_b128 v[156:159], v139 offset:2048
	ds_read_b128 v[160:163], v139 offset:3072
	ds_read_b128 v[164:167], v140
	ds_read_b128 v[168:171], v140 offset:1024
	ds_read_b128 v[172:175], v140 offset:2048
	ds_read_b128 v[176:179], v140 offset:3072
	s_add_i32 s18, s71, 0xffe80080
	s_cmp_eq_u32 s58, s73
	s_cselect_b32 s74, s69, s18
	s_cselect_b32 s76, s70, s72
	s_or_b32 s75, s74, 0x80
	s_add_i32 s18, s71, 0xfff80000
	s_mov_b32 m0, s59
	ds_read_b128 v[180:183], v141
	ds_read_b128 v[184:187], v141 offset:1024
	ds_read_b128 v[188:191], v141 offset:2048
	ds_read_b128 v[192:195], v141 offset:3072
	ds_read_b128 v[196:199], v141 offset:4096
	ds_read_b128 v[200:203], v141 offset:5120
	ds_read_b128 v[204:207], v141 offset:6144
	ds_read_b128 v[208:211], v141 offset:7168
	buffer_load_dwordx4 v137, s[12:15], s18 offen lds
	s_mov_b32 m0, s60
	s_nop 0
	buffer_load_dwordx4 v137, s[12:15], s71 offen lds
	s_waitcnt vmcnt(8)
	s_waitcnt lgkmcnt(0)
	s_setprio 1
	v_mfma_f32_16x16x32_bf16 v[118:121], v[148:151], v[180:183], v[118:121]
	s_barrier
	v_mfma_f32_16x16x32_bf16 v[118:121], v[152:155], v[184:187], v[118:121]
	v_mfma_f32_16x16x32_bf16 v[110:113], v[148:151], v[188:191], v[110:113]
	v_mfma_f32_16x16x32_bf16 v[110:113], v[152:155], v[192:195], v[110:113]
	v_mfma_f32_16x16x32_bf16 v[94:97], v[148:151], v[196:199], v[94:97]
	v_mfma_f32_16x16x32_bf16 v[94:97], v[152:155], v[200:203], v[94:97]
	v_mfma_f32_16x16x32_bf16 v[78:81], v[148:151], v[204:207], v[78:81]
	v_mfma_f32_16x16x32_bf16 v[78:81], v[152:155], v[208:211], v[78:81]
	v_mfma_f32_16x16x32_bf16 v[66:69], v[156:159], v[204:207], v[66:69]
	v_mfma_f32_16x16x32_bf16 v[66:69], v[160:163], v[208:211], v[66:69]
	v_mfma_f32_16x16x32_bf16 v[86:89], v[156:159], v[196:199], v[86:89]
	v_mfma_f32_16x16x32_bf16 v[86:89], v[160:163], v[200:203], v[86:89]
	v_mfma_f32_16x16x32_bf16 v[102:105], v[156:159], v[188:191], v[102:105]
	v_mfma_f32_16x16x32_bf16 v[102:105], v[160:163], v[192:195], v[102:105]
	v_mfma_f32_16x16x32_bf16 v[114:117], v[156:159], v[180:183], v[114:117]
	v_mfma_f32_16x16x32_bf16 v[114:117], v[160:163], v[184:187], v[114:117]
	v_mfma_f32_16x16x32_bf16 v[126:129], v[164:167], v[180:183], v[126:129]
	v_mfma_f32_16x16x32_bf16 v[126:129], v[168:171], v[184:187], v[126:129]
	v_mfma_f32_16x16x32_bf16 v[106:109], v[164:167], v[188:191], v[106:109]
	v_mfma_f32_16x16x32_bf16 v[106:109], v[168:171], v[192:195], v[106:109]
	v_mfma_f32_16x16x32_bf16 v[90:93], v[164:167], v[196:199], v[90:93]
	v_mfma_f32_16x16x32_bf16 v[90:93], v[168:171], v[200:203], v[90:93]
	v_mfma_f32_16x16x32_bf16 v[74:77], v[164:167], v[204:207], v[74:77]
	v_mfma_f32_16x16x32_bf16 v[74:77], v[168:171], v[208:211], v[74:77]
	v_mfma_f32_16x16x32_bf16 v[70:73], v[172:175], v[204:207], v[70:73]
	v_mfma_f32_16x16x32_bf16 v[70:73], v[176:179], v[208:211], v[70:73]
	v_mfma_f32_16x16x32_bf16 v[82:85], v[172:175], v[196:199], v[82:85]
	v_mfma_f32_16x16x32_bf16 v[82:85], v[176:179], v[200:203], v[82:85]
	v_mfma_f32_16x16x32_bf16 v[98:101], v[172:175], v[188:191], v[98:101]
	v_mfma_f32_16x16x32_bf16 v[98:101], v[176:179], v[192:195], v[98:101]
	v_mfma_f32_16x16x32_bf16 v[122:125], v[172:175], v[180:183], v[122:125]
	v_mfma_f32_16x16x32_bf16 v[122:125], v[176:179], v[184:187], v[122:125]
	s_setprio 0
	s_barrier
	s_mov_b32 m0, s30
	s_mov_b32 s18, s14
	s_mov_b32 s19, s15
	ds_read_b128 v[180:183], v141 offset:16384
	ds_read_b128 v[184:187], v141 offset:17408
	ds_read_b128 v[188:191], v141 offset:18432
	ds_read_b128 v[192:195], v141 offset:19456
	ds_read_b128 v[196:199], v141 offset:20480
	ds_read_b128 v[200:203], v141 offset:21504
	ds_read_b128 v[204:207], v141 offset:22528
	ds_read_b128 v[208:211], v141 offset:23552
	buffer_load_dwordx4 v138, s[16:19], s76 offen lds
	s_add_i32 s77, s76, 0x80000
	s_mov_b32 m0, s31
	s_nop 0
	buffer_load_dwordx4 v138, s[16:19], s77 offen lds
	s_add_i32 s77, s76, 0x100000
	s_mov_b32 m0, s44
	s_nop 0
	buffer_load_dwordx4 v138, s[16:19], s77 offen lds
	s_add_i32 s77, s76, 0x180000
	s_mov_b32 m0, s45
	s_nop 0
	buffer_load_dwordx4 v138, s[16:19], s77 offen lds
	s_mov_b32 m0, s27
	s_add_i32 s77, s74, 0x80000
	buffer_load_dwordx4 v137, s[12:15], s74 offen lds
	s_mov_b32 m0, s46
	s_nop 0
	buffer_load_dwordx4 v137, s[12:15], s77 offen lds
	s_waitcnt vmcnt(8)
	s_waitcnt lgkmcnt(0)
	s_setprio 1
	v_mfma_f32_16x16x32_bf16 v[62:65], v[148:151], v[180:183], v[62:65]
	s_barrier
	v_mfma_f32_16x16x32_bf16 v[62:65], v[152:155], v[184:187], v[62:65]
	v_mfma_f32_16x16x32_bf16 v[46:49], v[148:151], v[188:191], v[46:49]
	v_mfma_f32_16x16x32_bf16 v[46:49], v[152:155], v[192:195], v[46:49]
	v_mfma_f32_16x16x32_bf16 v[30:33], v[148:151], v[196:199], v[30:33]
	v_mfma_f32_16x16x32_bf16 v[30:33], v[152:155], v[200:203], v[30:33]
	v_mfma_f32_16x16x32_bf16 v[14:17], v[148:151], v[204:207], v[14:17]
	v_mfma_f32_16x16x32_bf16 v[14:17], v[152:155], v[208:211], v[14:17]
	v_mfma_f32_16x16x32_bf16 v[6:9], v[156:159], v[204:207], v[6:9]
	v_mfma_f32_16x16x32_bf16 v[6:9], v[160:163], v[208:211], v[6:9]
	v_mfma_f32_16x16x32_bf16 v[22:25], v[156:159], v[196:199], v[22:25]
	v_mfma_f32_16x16x32_bf16 v[22:25], v[160:163], v[200:203], v[22:25]
	v_mfma_f32_16x16x32_bf16 v[38:41], v[156:159], v[188:191], v[38:41]
	v_mfma_f32_16x16x32_bf16 v[38:41], v[160:163], v[192:195], v[38:41]
	v_mfma_f32_16x16x32_bf16 v[54:57], v[156:159], v[180:183], v[54:57]
	v_mfma_f32_16x16x32_bf16 v[54:57], v[160:163], v[184:187], v[54:57]
	v_mfma_f32_16x16x32_bf16 v[58:61], v[164:167], v[180:183], v[58:61]
	v_mfma_f32_16x16x32_bf16 v[58:61], v[168:171], v[184:187], v[58:61]
	v_mfma_f32_16x16x32_bf16 v[42:45], v[164:167], v[188:191], v[42:45]
	v_mfma_f32_16x16x32_bf16 v[42:45], v[168:171], v[192:195], v[42:45]
	v_mfma_f32_16x16x32_bf16 v[26:29], v[164:167], v[196:199], v[26:29]
	v_mfma_f32_16x16x32_bf16 v[26:29], v[168:171], v[200:203], v[26:29]
	v_mfma_f32_16x16x32_bf16 v[10:13], v[164:167], v[204:207], v[10:13]
	v_mfma_f32_16x16x32_bf16 v[10:13], v[168:171], v[208:211], v[10:13]
	v_mfma_f32_16x16x32_bf16 v[2:5], v[172:175], v[204:207], v[2:5]
	v_mfma_f32_16x16x32_bf16 v[2:5], v[176:179], v[208:211], v[2:5]
	v_mfma_f32_16x16x32_bf16 v[18:21], v[172:175], v[196:199], v[18:21]
	v_mfma_f32_16x16x32_bf16 v[18:21], v[176:179], v[200:203], v[18:21]
	v_mfma_f32_16x16x32_bf16 v[34:37], v[172:175], v[188:191], v[34:37]
	v_mfma_f32_16x16x32_bf16 v[34:37], v[176:179], v[192:195], v[34:37]
	v_mfma_f32_16x16x32_bf16 v[50:53], v[172:175], v[180:183], v[50:53]
	v_mfma_f32_16x16x32_bf16 v[50:53], v[176:179], v[184:187], v[50:53]
	s_setprio 0
	s_barrier
	ds_read_b128 v[148:151], v142
	ds_read_b128 v[152:155], v142 offset:1024
	ds_read_b128 v[156:159], v142 offset:2048
	ds_read_b128 v[160:163], v142 offset:3072
	ds_read_b128 v[164:167], v143
	ds_read_b128 v[168:171], v143 offset:1024
	ds_read_b128 v[172:175], v143 offset:2048
	ds_read_b128 v[176:179], v143 offset:3072
	s_mov_b32 m0, s47
	s_add_i32 s77, s74, 0x100000
	ds_read_b128 v[180:183], v141 offset:32768
	ds_read_b128 v[184:187], v141 offset:33792
	ds_read_b128 v[188:191], v141 offset:34816
	ds_read_b128 v[192:195], v141 offset:35840
	ds_read_b128 v[196:199], v141 offset:36864
	ds_read_b128 v[200:203], v141 offset:37888
	ds_read_b128 v[204:207], v141 offset:38912
	ds_read_b128 v[208:211], v141 offset:39936
	buffer_load_dwordx4 v137, s[12:15], s77 offen lds
	s_add_i32 s77, s74, 0x180000
	s_mov_b32 m0, s48
	s_nop 0
	buffer_load_dwordx4 v137, s[12:15], s77 offen lds
	s_waitcnt vmcnt(8)
	s_waitcnt lgkmcnt(0)
	s_setprio 1
	v_mfma_f32_16x16x32_bf16 v[118:121], v[148:151], v[180:183], v[118:121]
	s_barrier
	v_mfma_f32_16x16x32_bf16 v[118:121], v[152:155], v[184:187], v[118:121]
	v_mfma_f32_16x16x32_bf16 v[110:113], v[148:151], v[188:191], v[110:113]
	v_mfma_f32_16x16x32_bf16 v[110:113], v[152:155], v[192:195], v[110:113]
	v_mfma_f32_16x16x32_bf16 v[94:97], v[148:151], v[196:199], v[94:97]
	v_mfma_f32_16x16x32_bf16 v[94:97], v[152:155], v[200:203], v[94:97]
	v_mfma_f32_16x16x32_bf16 v[78:81], v[148:151], v[204:207], v[78:81]
	v_mfma_f32_16x16x32_bf16 v[78:81], v[152:155], v[208:211], v[78:81]
	v_mfma_f32_16x16x32_bf16 v[66:69], v[156:159], v[204:207], v[66:69]
	v_mfma_f32_16x16x32_bf16 v[66:69], v[160:163], v[208:211], v[66:69]
	v_mfma_f32_16x16x32_bf16 v[86:89], v[156:159], v[196:199], v[86:89]
	v_mfma_f32_16x16x32_bf16 v[86:89], v[160:163], v[200:203], v[86:89]
	v_mfma_f32_16x16x32_bf16 v[102:105], v[156:159], v[188:191], v[102:105]
	v_mfma_f32_16x16x32_bf16 v[102:105], v[160:163], v[192:195], v[102:105]
	v_mfma_f32_16x16x32_bf16 v[114:117], v[156:159], v[180:183], v[114:117]
	v_mfma_f32_16x16x32_bf16 v[114:117], v[160:163], v[184:187], v[114:117]
	v_mfma_f32_16x16x32_bf16 v[126:129], v[164:167], v[180:183], v[126:129]
	v_mfma_f32_16x16x32_bf16 v[126:129], v[168:171], v[184:187], v[126:129]
	v_mfma_f32_16x16x32_bf16 v[106:109], v[164:167], v[188:191], v[106:109]
	v_mfma_f32_16x16x32_bf16 v[106:109], v[168:171], v[192:195], v[106:109]
	v_mfma_f32_16x16x32_bf16 v[90:93], v[164:167], v[196:199], v[90:93]
	v_mfma_f32_16x16x32_bf16 v[90:93], v[168:171], v[200:203], v[90:93]
	v_mfma_f32_16x16x32_bf16 v[74:77], v[164:167], v[204:207], v[74:77]
	v_mfma_f32_16x16x32_bf16 v[74:77], v[168:171], v[208:211], v[74:77]
	v_mfma_f32_16x16x32_bf16 v[70:73], v[172:175], v[204:207], v[70:73]
	v_mfma_f32_16x16x32_bf16 v[70:73], v[176:179], v[208:211], v[70:73]
	v_mfma_f32_16x16x32_bf16 v[82:85], v[172:175], v[196:199], v[82:85]
	v_mfma_f32_16x16x32_bf16 v[82:85], v[176:179], v[200:203], v[82:85]
	v_mfma_f32_16x16x32_bf16 v[98:101], v[172:175], v[188:191], v[98:101]
	v_mfma_f32_16x16x32_bf16 v[98:101], v[176:179], v[192:195], v[98:101]
	v_mfma_f32_16x16x32_bf16 v[122:125], v[172:175], v[180:183], v[122:125]
	v_mfma_f32_16x16x32_bf16 v[122:125], v[176:179], v[184:187], v[122:125]
	s_setprio 0
	s_barrier
	s_mov_b32 m0, s50
	s_or_b32 s77, s76, 0x80
	ds_read_b128 v[180:183], v141 offset:49152
	ds_read_b128 v[184:187], v141 offset:50176
	ds_read_b128 v[188:191], v141 offset:51200
	ds_read_b128 v[192:195], v141 offset:52224
	ds_read_b128 v[196:199], v141 offset:53248
	ds_read_b128 v[200:203], v141 offset:54272
	ds_read_b128 v[204:207], v141 offset:55296
	ds_read_b128 v[208:211], v141 offset:56320
	buffer_load_dwordx4 v138, s[16:19], s77 offen lds
	s_add_i32 s77, s76, 0x80080
	s_mov_b32 m0, s51
	s_add_i32 s74, s74, 0x80080
	buffer_load_dwordx4 v138, s[16:19], s77 offen lds
	s_add_i32 s77, s76, 0x100080
	s_mov_b32 m0, s54
	s_add_i32 s76, s76, 0x180080
	buffer_load_dwordx4 v138, s[16:19], s77 offen lds
	s_mov_b32 m0, s55
	s_nop 0
	buffer_load_dwordx4 v138, s[16:19], s76 offen lds
	s_mov_b32 m0, s52
	s_nop 0
	buffer_load_dwordx4 v137, s[12:15], s75 offen lds
	s_mov_b32 m0, s53
	s_nop 0
	buffer_load_dwordx4 v137, s[12:15], s74 offen lds
	s_waitcnt vmcnt(8)
	s_waitcnt lgkmcnt(0)
	s_setprio 1
	v_mfma_f32_16x16x32_bf16 v[62:65], v[148:151], v[180:183], v[62:65]
	s_barrier
	v_mfma_f32_16x16x32_bf16 v[62:65], v[152:155], v[184:187], v[62:65]
	v_mfma_f32_16x16x32_bf16 v[46:49], v[148:151], v[188:191], v[46:49]
	v_mfma_f32_16x16x32_bf16 v[46:49], v[152:155], v[192:195], v[46:49]
	v_mfma_f32_16x16x32_bf16 v[30:33], v[148:151], v[196:199], v[30:33]
	v_mfma_f32_16x16x32_bf16 v[30:33], v[152:155], v[200:203], v[30:33]
	v_mfma_f32_16x16x32_bf16 v[14:17], v[148:151], v[204:207], v[14:17]
	v_mfma_f32_16x16x32_bf16 v[14:17], v[152:155], v[208:211], v[14:17]
	v_mfma_f32_16x16x32_bf16 v[6:9], v[156:159], v[204:207], v[6:9]
	v_mfma_f32_16x16x32_bf16 v[6:9], v[160:163], v[208:211], v[6:9]
	v_mfma_f32_16x16x32_bf16 v[22:25], v[156:159], v[196:199], v[22:25]
	v_mfma_f32_16x16x32_bf16 v[22:25], v[160:163], v[200:203], v[22:25]
	v_mfma_f32_16x16x32_bf16 v[38:41], v[156:159], v[188:191], v[38:41]
	v_mfma_f32_16x16x32_bf16 v[38:41], v[160:163], v[192:195], v[38:41]
	v_mfma_f32_16x16x32_bf16 v[54:57], v[156:159], v[180:183], v[54:57]
	v_mfma_f32_16x16x32_bf16 v[54:57], v[160:163], v[184:187], v[54:57]
	v_mfma_f32_16x16x32_bf16 v[58:61], v[164:167], v[180:183], v[58:61]
	v_mfma_f32_16x16x32_bf16 v[58:61], v[168:171], v[184:187], v[58:61]
	v_mfma_f32_16x16x32_bf16 v[42:45], v[164:167], v[188:191], v[42:45]
	v_mfma_f32_16x16x32_bf16 v[42:45], v[168:171], v[192:195], v[42:45]
	v_mfma_f32_16x16x32_bf16 v[26:29], v[164:167], v[196:199], v[26:29]
	v_mfma_f32_16x16x32_bf16 v[26:29], v[168:171], v[200:203], v[26:29]
	v_mfma_f32_16x16x32_bf16 v[10:13], v[164:167], v[204:207], v[10:13]
	v_mfma_f32_16x16x32_bf16 v[10:13], v[168:171], v[208:211], v[10:13]
	v_mfma_f32_16x16x32_bf16 v[2:5], v[172:175], v[204:207], v[2:5]
	v_mfma_f32_16x16x32_bf16 v[2:5], v[176:179], v[208:211], v[2:5]
	v_mfma_f32_16x16x32_bf16 v[18:21], v[172:175], v[196:199], v[18:21]
	v_mfma_f32_16x16x32_bf16 v[18:21], v[176:179], v[200:203], v[18:21]
	v_mfma_f32_16x16x32_bf16 v[34:37], v[172:175], v[188:191], v[34:37]
	v_mfma_f32_16x16x32_bf16 v[34:37], v[176:179], v[192:195], v[34:37]
	v_mfma_f32_16x16x32_bf16 v[50:53], v[172:175], v[180:183], v[50:53]
	v_mfma_f32_16x16x32_bf16 v[50:53], v[176:179], v[184:187], v[50:53]
	s_setprio 0
	s_barrier
	s_add_i32 s73, s73, 2
	s_addk_i32 s71, 0x100
	s_addk_i32 s72, 0x100
	s_cmp_ge_i32 s73, s3
	s_cbranch_scc0 .LBB0_642
	s_and_b64 vcc, exec, s[42:43]
	s_cbranch_vccz .LBB0_645

.LBB0_799:
	ds_read_b128 v[134:137], v210
	ds_read_b128 v[138:141], v210 offset:1024
	ds_read_b128 v[142:145], v210 offset:2048
	ds_read_b128 v[148:151], v210 offset:3072
	ds_read_b128 v[152:155], v211
	ds_read_b128 v[156:159], v211 offset:1024
	ds_read_b128 v[160:163], v211 offset:2048
	ds_read_b128 v[164:167], v211 offset:3072
	s_add_i32 s18, s77, 0xffbf8080
	s_cmp_eq_u32 s62, s79
	s_cselect_b32 s80, s6, s18
	s_cselect_b32 s82, s7, s78
	s_or_b32 s81, s80, 0x80
	s_add_i32 s18, s77, 0xffea8000
	s_mov_b32 m0, s63
	ds_read_b128 v[168:171], v212
	ds_read_b128 v[172:175], v212 offset:1024
	ds_read_b128 v[176:179], v212 offset:2048
	ds_read_b128 v[180:183], v212 offset:3072
	ds_read_b128 v[184:187], v212 offset:4096
	ds_read_b128 v[188:191], v212 offset:5120
	ds_read_b128 v[192:195], v212 offset:6144
	ds_read_b128 v[196:199], v212 offset:7168
	buffer_load_dwordx4 v208, s[12:15], s18 offen lds
	s_mov_b32 m0, s66
	s_nop 0
	buffer_load_dwordx4 v208, s[12:15], s77 offen lds
	s_waitcnt vmcnt(8)
	s_waitcnt lgkmcnt(0)
	s_setprio 1
	v_mfma_f32_16x16x32_bf16 v[126:129], v[134:137], v[168:171], v[126:129]
	s_barrier
	v_mfma_f32_16x16x32_bf16 v[126:129], v[138:141], v[172:175], v[126:129]
	v_mfma_f32_16x16x32_bf16 v[118:121], v[134:137], v[176:179], v[118:121]
	v_mfma_f32_16x16x32_bf16 v[118:121], v[138:141], v[180:183], v[118:121]
	v_mfma_f32_16x16x32_bf16 v[106:109], v[134:137], v[184:187], v[106:109]
	v_mfma_f32_16x16x32_bf16 v[106:109], v[138:141], v[188:191], v[106:109]
	v_mfma_f32_16x16x32_bf16 v[90:93], v[134:137], v[192:195], v[90:93]
	v_mfma_f32_16x16x32_bf16 v[90:93], v[138:141], v[196:199], v[90:93]
	v_mfma_f32_16x16x32_bf16 v[82:85], v[142:145], v[192:195], v[82:85]
	v_mfma_f32_16x16x32_bf16 v[82:85], v[148:151], v[196:199], v[82:85]
	v_mfma_f32_16x16x32_bf16 v[98:101], v[142:145], v[184:187], v[98:101]
	v_mfma_f32_16x16x32_bf16 v[98:101], v[148:151], v[188:191], v[98:101]
	v_mfma_f32_16x16x32_bf16 v[114:117], v[142:145], v[176:179], v[114:117]
	v_mfma_f32_16x16x32_bf16 v[114:117], v[148:151], v[180:183], v[114:117]
	v_mfma_f32_16x16x32_bf16 v[122:125], v[142:145], v[168:171], v[122:125]
	v_mfma_f32_16x16x32_bf16 v[122:125], v[148:151], v[172:175], v[122:125]
	v_mfma_f32_16x16x32_bf16 v[110:113], v[152:155], v[168:171], v[110:113]
	v_mfma_f32_16x16x32_bf16 v[110:113], v[156:159], v[172:175], v[110:113]
	v_mfma_f32_16x16x32_bf16 v[94:97], v[152:155], v[176:179], v[94:97]
	v_mfma_f32_16x16x32_bf16 v[94:97], v[156:159], v[180:183], v[94:97]
	v_mfma_f32_16x16x32_bf16 v[78:81], v[152:155], v[184:187], v[78:81]
	v_mfma_f32_16x16x32_bf16 v[78:81], v[156:159], v[188:191], v[78:81]
	v_mfma_f32_16x16x32_bf16 v[70:73], v[152:155], v[192:195], v[70:73]
	v_mfma_f32_16x16x32_bf16 v[70:73], v[156:159], v[196:199], v[70:73]
	v_mfma_f32_16x16x32_bf16 v[66:69], v[160:163], v[192:195], v[66:69]
	v_mfma_f32_16x16x32_bf16 v[66:69], v[164:167], v[196:199], v[66:69]
	v_mfma_f32_16x16x32_bf16 v[74:77], v[160:163], v[184:187], v[74:77]
	v_mfma_f32_16x16x32_bf16 v[74:77], v[164:167], v[188:191], v[74:77]
	v_mfma_f32_16x16x32_bf16 v[86:89], v[160:163], v[176:179], v[86:89]
	v_mfma_f32_16x16x32_bf16 v[86:89], v[164:167], v[180:183], v[86:89]
	v_mfma_f32_16x16x32_bf16 v[102:105], v[160:163], v[168:171], v[102:105]
	v_mfma_f32_16x16x32_bf16 v[102:105], v[164:167], v[172:175], v[102:105]
	s_setprio 0
	s_barrier
	s_mov_b32 m0, s25
	s_mov_b32 s18, s14
	s_mov_b32 s19, s15
	ds_read_b128 v[168:171], v212 offset:16384
	ds_read_b128 v[172:175], v212 offset:17408
	ds_read_b128 v[176:179], v212 offset:18432
	ds_read_b128 v[180:183], v212 offset:19456
	ds_read_b128 v[184:187], v212 offset:20480
	ds_read_b128 v[188:191], v212 offset:21504
	ds_read_b128 v[192:195], v212 offset:22528
	ds_read_b128 v[196:199], v212 offset:23552
	buffer_load_dwordx4 v209, s[16:19], s82 offen lds
	s_add_i32 s83, s82, 0x158000
	s_mov_b32 m0, s27
	s_nop 0
	buffer_load_dwordx4 v209, s[16:19], s83 offen lds
	s_add_i32 s83, s82, 0x2b0000
	s_mov_b32 m0, s30
	s_nop 0
	buffer_load_dwordx4 v209, s[16:19], s83 offen lds
	s_add_i32 s83, s82, 0x408000
	s_mov_b32 m0, s31
	s_nop 0
	buffer_load_dwordx4 v209, s[16:19], s83 offen lds
	s_mov_b32 m0, s21
	s_add_i32 s83, s80, 0x158000
	buffer_load_dwordx4 v208, s[12:15], s80 offen lds
	s_mov_b32 m0, s48
	s_nop 0
	buffer_load_dwordx4 v208, s[12:15], s83 offen lds
	s_waitcnt vmcnt(8)
	s_waitcnt lgkmcnt(0)
	s_setprio 1
	v_mfma_f32_16x16x32_bf16 v[62:65], v[134:137], v[168:171], v[62:65]
	s_barrier
	v_mfma_f32_16x16x32_bf16 v[62:65], v[138:141], v[172:175], v[62:65]
	v_mfma_f32_16x16x32_bf16 v[54:57], v[134:137], v[176:179], v[54:57]
	v_mfma_f32_16x16x32_bf16 v[54:57], v[138:141], v[180:183], v[54:57]
	v_mfma_f32_16x16x32_bf16 v[42:45], v[134:137], v[184:187], v[42:45]
	v_mfma_f32_16x16x32_bf16 v[42:45], v[138:141], v[188:191], v[42:45]
	v_mfma_f32_16x16x32_bf16 v[26:29], v[134:137], v[192:195], v[26:29]
	v_mfma_f32_16x16x32_bf16 v[26:29], v[138:141], v[196:199], v[26:29]
	v_mfma_f32_16x16x32_bf16 v[18:21], v[142:145], v[192:195], v[18:21]
	v_mfma_f32_16x16x32_bf16 v[18:21], v[148:151], v[196:199], v[18:21]
	v_mfma_f32_16x16x32_bf16 v[34:37], v[142:145], v[184:187], v[34:37]
	v_mfma_f32_16x16x32_bf16 v[34:37], v[148:151], v[188:191], v[34:37]
	v_mfma_f32_16x16x32_bf16 v[50:53], v[142:145], v[176:179], v[50:53]
	v_mfma_f32_16x16x32_bf16 v[50:53], v[148:151], v[180:183], v[50:53]
	v_mfma_f32_16x16x32_bf16 v[58:61], v[142:145], v[168:171], v[58:61]
	v_mfma_f32_16x16x32_bf16 v[58:61], v[148:151], v[172:175], v[58:61]
	v_mfma_f32_16x16x32_bf16 v[46:49], v[152:155], v[168:171], v[46:49]
	v_mfma_f32_16x16x32_bf16 v[46:49], v[156:159], v[172:175], v[46:49]
	v_mfma_f32_16x16x32_bf16 v[30:33], v[152:155], v[176:179], v[30:33]
	v_mfma_f32_16x16x32_bf16 v[30:33], v[156:159], v[180:183], v[30:33]
	v_mfma_f32_16x16x32_bf16 v[14:17], v[152:155], v[184:187], v[14:17]
	v_mfma_f32_16x16x32_bf16 v[14:17], v[156:159], v[188:191], v[14:17]
	v_mfma_f32_16x16x32_bf16 v[6:9], v[152:155], v[192:195], v[6:9]
	v_mfma_f32_16x16x32_bf16 v[6:9], v[156:159], v[196:199], v[6:9]
	v_mfma_f32_16x16x32_bf16 v[2:5], v[160:163], v[192:195], v[2:5]
	v_mfma_f32_16x16x32_bf16 v[2:5], v[164:167], v[196:199], v[2:5]
	v_mfma_f32_16x16x32_bf16 v[10:13], v[160:163], v[184:187], v[10:13]
	v_mfma_f32_16x16x32_bf16 v[10:13], v[164:167], v[188:191], v[10:13]
	v_mfma_f32_16x16x32_bf16 v[22:25], v[160:163], v[176:179], v[22:25]
	v_mfma_f32_16x16x32_bf16 v[22:25], v[164:167], v[180:183], v[22:25]
	v_mfma_f32_16x16x32_bf16 v[38:41], v[160:163], v[168:171], v[38:41]
	v_mfma_f32_16x16x32_bf16 v[38:41], v[164:167], v[172:175], v[38:41]
	s_setprio 0
	s_barrier
	ds_read_b128 v[134:137], v213
	ds_read_b128 v[138:141], v213 offset:1024
	ds_read_b128 v[142:145], v213 offset:2048
	ds_read_b128 v[148:151], v213 offset:3072
	ds_read_b128 v[152:155], v214
	ds_read_b128 v[156:159], v214 offset:1024
	ds_read_b128 v[160:163], v214 offset:2048
	ds_read_b128 v[164:167], v214 offset:3072
	s_mov_b32 m0, s49
	s_add_i32 s83, s80, 0x2b0000
	ds_read_b128 v[168:171], v212 offset:32768
	ds_read_b128 v[172:175], v212 offset:33792
	ds_read_b128 v[176:179], v212 offset:34816
	ds_read_b128 v[180:183], v212 offset:35840
	ds_read_b128 v[184:187], v212 offset:36864
	ds_read_b128 v[188:191], v212 offset:37888
	ds_read_b128 v[192:195], v212 offset:38912
	ds_read_b128 v[196:199], v212 offset:39936
	buffer_load_dwordx4 v208, s[12:15], s83 offen lds
	s_add_i32 s83, s80, 0x408000
	s_mov_b32 m0, s50
	s_nop 0
	buffer_load_dwordx4 v208, s[12:15], s83 offen lds
	s_waitcnt vmcnt(8)
	s_waitcnt lgkmcnt(0)
	s_setprio 1
	v_mfma_f32_16x16x32_bf16 v[126:129], v[134:137], v[168:171], v[126:129]
	s_barrier
	v_mfma_f32_16x16x32_bf16 v[126:129], v[138:141], v[172:175], v[126:129]
	v_mfma_f32_16x16x32_bf16 v[118:121], v[134:137], v[176:179], v[118:121]
	v_mfma_f32_16x16x32_bf16 v[118:121], v[138:141], v[180:183], v[118:121]
	v_mfma_f32_16x16x32_bf16 v[106:109], v[134:137], v[184:187], v[106:109]
	v_mfma_f32_16x16x32_bf16 v[106:109], v[138:141], v[188:191], v[106:109]
	v_mfma_f32_16x16x32_bf16 v[90:93], v[134:137], v[192:195], v[90:93]
	v_mfma_f32_16x16x32_bf16 v[90:93], v[138:141], v[196:199], v[90:93]
	v_mfma_f32_16x16x32_bf16 v[82:85], v[142:145], v[192:195], v[82:85]
	v_mfma_f32_16x16x32_bf16 v[82:85], v[148:151], v[196:199], v[82:85]
	v_mfma_f32_16x16x32_bf16 v[98:101], v[142:145], v[184:187], v[98:101]
	v_mfma_f32_16x16x32_bf16 v[98:101], v[148:151], v[188:191], v[98:101]
	v_mfma_f32_16x16x32_bf16 v[114:117], v[142:145], v[176:179], v[114:117]
	v_mfma_f32_16x16x32_bf16 v[114:117], v[148:151], v[180:183], v[114:117]
	v_mfma_f32_16x16x32_bf16 v[122:125], v[142:145], v[168:171], v[122:125]
	v_mfma_f32_16x16x32_bf16 v[122:125], v[148:151], v[172:175], v[122:125]
	v_mfma_f32_16x16x32_bf16 v[110:113], v[152:155], v[168:171], v[110:113]
	v_mfma_f32_16x16x32_bf16 v[110:113], v[156:159], v[172:175], v[110:113]
	v_mfma_f32_16x16x32_bf16 v[94:97], v[152:155], v[176:179], v[94:97]
	v_mfma_f32_16x16x32_bf16 v[94:97], v[156:159], v[180:183], v[94:97]
	v_mfma_f32_16x16x32_bf16 v[78:81], v[152:155], v[184:187], v[78:81]
	v_mfma_f32_16x16x32_bf16 v[78:81], v[156:159], v[188:191], v[78:81]
	v_mfma_f32_16x16x32_bf16 v[70:73], v[152:155], v[192:195], v[70:73]
	v_mfma_f32_16x16x32_bf16 v[70:73], v[156:159], v[196:199], v[70:73]
	v_mfma_f32_16x16x32_bf16 v[66:69], v[160:163], v[192:195], v[66:69]
	v_mfma_f32_16x16x32_bf16 v[66:69], v[164:167], v[196:199], v[66:69]
	v_mfma_f32_16x16x32_bf16 v[74:77], v[160:163], v[184:187], v[74:77]
	v_mfma_f32_16x16x32_bf16 v[74:77], v[164:167], v[188:191], v[74:77]
	v_mfma_f32_16x16x32_bf16 v[86:89], v[160:163], v[176:179], v[86:89]
	v_mfma_f32_16x16x32_bf16 v[86:89], v[164:167], v[180:183], v[86:89]
	v_mfma_f32_16x16x32_bf16 v[102:105], v[160:163], v[168:171], v[102:105]
	v_mfma_f32_16x16x32_bf16 v[102:105], v[164:167], v[172:175], v[102:105]
	s_setprio 0
	s_barrier
	s_mov_b32 m0, s54
	s_or_b32 s83, s82, 0x80
	ds_read_b128 v[168:171], v212 offset:49152
	ds_read_b128 v[172:175], v212 offset:50176
	ds_read_b128 v[176:179], v212 offset:51200
	ds_read_b128 v[180:183], v212 offset:52224
	ds_read_b128 v[184:187], v212 offset:53248
	ds_read_b128 v[188:191], v212 offset:54272
	ds_read_b128 v[192:195], v212 offset:55296
	ds_read_b128 v[196:199], v212 offset:56320
	buffer_load_dwordx4 v209, s[16:19], s83 offen lds
	s_add_i32 s83, s82, 0x158080
	s_mov_b32 m0, s55
	s_add_i32 s80, s80, 0x158080
	buffer_load_dwordx4 v209, s[16:19], s83 offen lds
	s_add_i32 s83, s82, 0x2b0080
	s_mov_b32 m0, s58
	s_add_i32 s82, s82, 0x408080
	buffer_load_dwordx4 v209, s[16:19], s83 offen lds
	s_mov_b32 m0, s59
	s_nop 0
	buffer_load_dwordx4 v209, s[16:19], s82 offen lds
	s_mov_b32 m0, s56
	s_nop 0
	buffer_load_dwordx4 v208, s[12:15], s81 offen lds
	s_mov_b32 m0, s57
	s_nop 0
	buffer_load_dwordx4 v208, s[12:15], s80 offen lds
	s_waitcnt vmcnt(8)
	s_waitcnt lgkmcnt(0)
	s_setprio 1
	v_mfma_f32_16x16x32_bf16 v[62:65], v[134:137], v[168:171], v[62:65]
	s_barrier
	v_mfma_f32_16x16x32_bf16 v[62:65], v[138:141], v[172:175], v[62:65]
	v_mfma_f32_16x16x32_bf16 v[54:57], v[134:137], v[176:179], v[54:57]
	v_mfma_f32_16x16x32_bf16 v[54:57], v[138:141], v[180:183], v[54:57]
	v_mfma_f32_16x16x32_bf16 v[42:45], v[134:137], v[184:187], v[42:45]
	v_mfma_f32_16x16x32_bf16 v[42:45], v[138:141], v[188:191], v[42:45]
	v_mfma_f32_16x16x32_bf16 v[26:29], v[134:137], v[192:195], v[26:29]
	v_mfma_f32_16x16x32_bf16 v[26:29], v[138:141], v[196:199], v[26:29]
	v_mfma_f32_16x16x32_bf16 v[18:21], v[142:145], v[192:195], v[18:21]
	v_mfma_f32_16x16x32_bf16 v[18:21], v[148:151], v[196:199], v[18:21]
	v_mfma_f32_16x16x32_bf16 v[34:37], v[142:145], v[184:187], v[34:37]
	v_mfma_f32_16x16x32_bf16 v[34:37], v[148:151], v[188:191], v[34:37]
	v_mfma_f32_16x16x32_bf16 v[50:53], v[142:145], v[176:179], v[50:53]
	v_mfma_f32_16x16x32_bf16 v[50:53], v[148:151], v[180:183], v[50:53]
	v_mfma_f32_16x16x32_bf16 v[58:61], v[142:145], v[168:171], v[58:61]
	v_mfma_f32_16x16x32_bf16 v[58:61], v[148:151], v[172:175], v[58:61]
	v_mfma_f32_16x16x32_bf16 v[46:49], v[152:155], v[168:171], v[46:49]
	v_mfma_f32_16x16x32_bf16 v[46:49], v[156:159], v[172:175], v[46:49]
	v_mfma_f32_16x16x32_bf16 v[30:33], v[152:155], v[176:179], v[30:33]
	v_mfma_f32_16x16x32_bf16 v[30:33], v[156:159], v[180:183], v[30:33]
	v_mfma_f32_16x16x32_bf16 v[14:17], v[152:155], v[184:187], v[14:17]
	v_mfma_f32_16x16x32_bf16 v[14:17], v[156:159], v[188:191], v[14:17]
	v_mfma_f32_16x16x32_bf16 v[6:9], v[152:155], v[192:195], v[6:9]
	v_mfma_f32_16x16x32_bf16 v[6:9], v[156:159], v[196:199], v[6:9]
	v_mfma_f32_16x16x32_bf16 v[2:5], v[160:163], v[192:195], v[2:5]
	v_mfma_f32_16x16x32_bf16 v[2:5], v[164:167], v[196:199], v[2:5]
	v_mfma_f32_16x16x32_bf16 v[10:13], v[160:163], v[184:187], v[10:13]
	v_mfma_f32_16x16x32_bf16 v[10:13], v[164:167], v[188:191], v[10:13]
	v_mfma_f32_16x16x32_bf16 v[22:25], v[160:163], v[176:179], v[22:25]
	v_mfma_f32_16x16x32_bf16 v[22:25], v[164:167], v[180:183], v[22:25]
	v_mfma_f32_16x16x32_bf16 v[38:41], v[160:163], v[168:171], v[38:41]
	v_mfma_f32_16x16x32_bf16 v[38:41], v[164:167], v[172:175], v[38:41]
	s_setprio 0
	s_barrier
	s_add_i32 s79, s79, 2
	s_addk_i32 s77, 0x100
	s_addk_i32 s78, 0x100
	s_cmp_ge_i32 s79, s3
	s_cbranch_scc0 .LBB0_799
	v_pk_mul_f32 v[184:185], v[128:129], 0.5 op_sel_hi:[1,0]
	v_pk_mul_f32 v[186:187], v[126:127], 0.5 op_sel_hi:[1,0]
	v_pk_mul_f32 v[188:189], v[124:125], 0.5 op_sel_hi:[1,0]
	v_pk_mul_f32 v[190:191], v[122:123], 0.5 op_sel_hi:[1,0]
	v_pk_mul_f32 v[198:199], v[112:113], 0.5 op_sel_hi:[1,0]
	v_pk_mul_f32 v[196:197], v[110:111], 0.5 op_sel_hi:[1,0]
	v_pk_mul_f32 v[194:195], v[104:105], 0.5 op_sel_hi:[1,0]
	v_pk_mul_f32 v[192:193], v[102:103], 0.5 op_sel_hi:[1,0]
	v_pk_mul_f32 v[182:183], v[120:121], 0.5 op_sel_hi:[1,0]
	v_pk_mul_f32 v[180:181], v[118:119], 0.5 op_sel_hi:[1,0]
	v_pk_mul_f32 v[178:179], v[116:117], 0.5 op_sel_hi:[1,0]
	v_pk_mul_f32 v[176:177], v[114:115], 0.5 op_sel_hi:[1,0]
	v_pk_mul_f32 v[172:173], v[96:97], 0.5 op_sel_hi:[1,0]
	v_pk_mul_f32 v[170:171], v[94:95], 0.5 op_sel_hi:[1,0]
	v_pk_mul_f32 v[168:169], v[88:89], 0.5 op_sel_hi:[1,0]
	v_pk_mul_f32 v[166:167], v[86:87], 0.5 op_sel_hi:[1,0]
	v_pk_mul_f32 v[164:165], v[108:109], 0.5 op_sel_hi:[1,0]
	v_pk_mul_f32 v[162:163], v[106:107], 0.5 op_sel_hi:[1,0]
	v_pk_mul_f32 v[160:161], v[100:101], 0.5 op_sel_hi:[1,0]
	v_pk_mul_f32 v[158:159], v[98:99], 0.5 op_sel_hi:[1,0]
	v_pk_mul_f32 v[156:157], v[80:81], 0.5 op_sel_hi:[1,0]
	v_pk_mul_f32 v[154:155], v[78:79], 0.5 op_sel_hi:[1,0]
	v_pk_mul_f32 v[152:153], v[76:77], 0.5 op_sel_hi:[1,0]
	v_pk_mul_f32 v[150:151], v[74:75], 0.5 op_sel_hi:[1,0]
	v_pk_mul_f32 v[144:145], v[92:93], 0.5 op_sel_hi:[1,0]
	v_pk_mul_f32 v[142:143], v[90:91], 0.5 op_sel_hi:[1,0]
	v_pk_mul_f32 v[140:141], v[84:85], 0.5 op_sel_hi:[1,0]
	v_pk_mul_f32 v[138:139], v[82:83], 0.5 op_sel_hi:[1,0]
	v_pk_mul_f32 v[136:137], v[72:73], 0.5 op_sel_hi:[1,0]
	v_pk_mul_f32 v[134:135], v[70:71], 0.5 op_sel_hi:[1,0]
	v_pk_mul_f32 v[128:129], v[68:69], 0.5 op_sel_hi:[1,0]
	v_pk_mul_f32 v[126:127], v[66:67], 0.5 op_sel_hi:[1,0]
	v_pk_mul_f32 v[122:123], v[64:65], 0.5 op_sel_hi:[1,0]
	v_pk_mul_f32 v[120:121], v[62:63], 0.5 op_sel_hi:[1,0]
	v_pk_mul_f32 v[118:119], v[60:61], 0.5 op_sel_hi:[1,0]
	v_pk_mul_f32 v[116:117], v[58:59], 0.5 op_sel_hi:[1,0]
	v_pk_mul_f32 v[112:113], v[48:49], 0.5 op_sel_hi:[1,0]
	v_pk_mul_f32 v[110:111], v[46:47], 0.5 op_sel_hi:[1,0]
	v_pk_mul_f32 v[108:109], v[40:41], 0.5 op_sel_hi:[1,0]
	v_pk_mul_f32 v[106:107], v[38:39], 0.5 op_sel_hi:[1,0]
	v_pk_mul_f32 v[104:105], v[56:57], 0.5 op_sel_hi:[1,0]
	v_pk_mul_f32 v[102:103], v[54:55], 0.5 op_sel_hi:[1,0]
	v_pk_mul_f32 v[100:101], v[52:53], 0.5 op_sel_hi:[1,0]
	v_pk_mul_f32 v[98:99], v[50:51], 0.5 op_sel_hi:[1,0]
	v_pk_mul_f32 v[96:97], v[32:33], 0.5 op_sel_hi:[1,0]
	v_pk_mul_f32 v[94:95], v[30:31], 0.5 op_sel_hi:[1,0]
	v_pk_mul_f32 v[92:93], v[24:25], 0.5 op_sel_hi:[1,0]
	v_pk_mul_f32 v[90:91], v[22:23], 0.5 op_sel_hi:[1,0]
	v_pk_mul_f32 v[88:89], v[44:45], 0.5 op_sel_hi:[1,0]
	v_pk_mul_f32 v[86:87], v[42:43], 0.5 op_sel_hi:[1,0]
	v_pk_mul_f32 v[84:85], v[36:37], 0.5 op_sel_hi:[1,0]
	v_pk_mul_f32 v[82:83], v[34:35], 0.5 op_sel_hi:[1,0]
	v_pk_mul_f32 v[80:81], v[16:17], 0.5 op_sel_hi:[1,0]
	v_pk_mul_f32 v[78:79], v[14:15], 0.5 op_sel_hi:[1,0]
	v_pk_mul_f32 v[76:77], v[12:13], 0.5 op_sel_hi:[1,0]
	v_pk_mul_f32 v[74:75], v[10:11], 0.5 op_sel_hi:[1,0]
	v_pk_mul_f32 v[72:73], v[28:29], 0.5 op_sel_hi:[1,0]
	v_pk_mul_f32 v[70:71], v[26:27], 0.5 op_sel_hi:[1,0]
	v_pk_mul_f32 v[68:69], v[20:21], 0.5 op_sel_hi:[1,0]
	v_pk_mul_f32 v[66:67], v[18:19], 0.5 op_sel_hi:[1,0]
	v_pk_mul_f32 v[64:65], v[8:9], 0.5 op_sel_hi:[1,0]
	v_pk_mul_f32 v[62:63], v[6:7], 0.5 op_sel_hi:[1,0]
	v_pk_mul_f32 v[60:61], v[4:5], 0.5 op_sel_hi:[1,0]
	v_pk_mul_f32 v[58:59], v[2:3], 0.5 op_sel_hi:[1,0]
	s_and_b64 vcc, exec, s[38:39]
	s_cbranch_vccz .LBB0_802

.LBB0_892:
	ds_read_b128 v[130:133], v172
	ds_read_b128 v[134:137], v172 offset:1024
	ds_read_b128 v[148:151], v172 offset:2048
	ds_read_b128 v[152:155], v172 offset:3072
	ds_read_b128 v[156:159], v173
	ds_read_b128 v[160:163], v173 offset:1024
	ds_read_b128 v[164:167], v173 offset:2048
	ds_read_b128 v[180:183], v173 offset:3072
	s_add_i32 s18, s8, 0xffe80080
	s_cmp_eq_u32 s77, s52
	s_cselect_b32 s53, s6, s18
	s_cselect_b32 s58, s7, s9
	s_or_b32 s57, s53, 0x80
	s_add_i32 s18, s8, 0xfff80000
	s_mov_b32 m0, s78
	ds_read_b128 v[184:187], v174
	ds_read_b128 v[188:191], v174 offset:1024
	ds_read_b128 v[192:195], v174 offset:2048
	ds_read_b128 v[196:199], v174 offset:3072
	ds_read_b128 v[200:203], v174 offset:4096
	ds_read_b128 v[204:207], v174 offset:5120
	ds_read_b128 v[208:211], v174 offset:6144
	ds_read_b128 v[212:215], v174 offset:7168
	buffer_load_dwordx4 v170, s[12:15], s18 offen lds
	s_mov_b32 m0, s79
	s_nop 0
	buffer_load_dwordx4 v170, s[12:15], s8 offen lds
	s_waitcnt vmcnt(8)
	s_waitcnt lgkmcnt(0)
	s_setprio 1
	v_mfma_f32_16x16x32_bf16 v[126:129], v[130:133], v[184:187], v[126:129]
	s_barrier
	v_mfma_f32_16x16x32_bf16 v[126:129], v[134:137], v[188:191], v[126:129]
	v_mfma_f32_16x16x32_bf16 v[110:113], v[130:133], v[192:195], v[110:113]
	v_mfma_f32_16x16x32_bf16 v[110:113], v[134:137], v[196:199], v[110:113]
	v_mfma_f32_16x16x32_bf16 v[94:97], v[130:133], v[200:203], v[94:97]
	v_mfma_f32_16x16x32_bf16 v[94:97], v[134:137], v[204:207], v[94:97]
	v_mfma_f32_16x16x32_bf16 v[78:81], v[130:133], v[208:211], v[78:81]
	v_mfma_f32_16x16x32_bf16 v[78:81], v[134:137], v[212:215], v[78:81]
	v_mfma_f32_16x16x32_bf16 v[70:73], v[148:151], v[208:211], v[70:73]
	v_mfma_f32_16x16x32_bf16 v[70:73], v[152:155], v[212:215], v[70:73]
	v_mfma_f32_16x16x32_bf16 v[90:93], v[148:151], v[200:203], v[90:93]
	v_mfma_f32_16x16x32_bf16 v[90:93], v[152:155], v[204:207], v[90:93]
	v_mfma_f32_16x16x32_bf16 v[102:105], v[148:151], v[192:195], v[102:105]
	v_mfma_f32_16x16x32_bf16 v[102:105], v[152:155], v[196:199], v[102:105]
	v_mfma_f32_16x16x32_bf16 v[118:121], v[148:151], v[184:187], v[118:121]
	v_mfma_f32_16x16x32_bf16 v[118:121], v[152:155], v[188:191], v[118:121]
	v_mfma_f32_16x16x32_bf16 v[122:125], v[156:159], v[184:187], v[122:125]
	v_mfma_f32_16x16x32_bf16 v[122:125], v[160:163], v[188:191], v[122:125]
	v_mfma_f32_16x16x32_bf16 v[106:109], v[156:159], v[192:195], v[106:109]
	v_mfma_f32_16x16x32_bf16 v[106:109], v[160:163], v[196:199], v[106:109]
	v_mfma_f32_16x16x32_bf16 v[86:89], v[156:159], v[200:203], v[86:89]
	v_mfma_f32_16x16x32_bf16 v[86:89], v[160:163], v[204:207], v[86:89]
	v_mfma_f32_16x16x32_bf16 v[74:77], v[156:159], v[208:211], v[74:77]
	v_mfma_f32_16x16x32_bf16 v[74:77], v[160:163], v[212:215], v[74:77]
	v_mfma_f32_16x16x32_bf16 v[66:69], v[164:167], v[208:211], v[66:69]
	v_mfma_f32_16x16x32_bf16 v[66:69], v[180:183], v[212:215], v[66:69]
	v_mfma_f32_16x16x32_bf16 v[82:85], v[164:167], v[200:203], v[82:85]
	v_mfma_f32_16x16x32_bf16 v[82:85], v[180:183], v[204:207], v[82:85]
	v_mfma_f32_16x16x32_bf16 v[98:101], v[164:167], v[192:195], v[98:101]
	v_mfma_f32_16x16x32_bf16 v[98:101], v[180:183], v[196:199], v[98:101]
	v_mfma_f32_16x16x32_bf16 v[114:117], v[164:167], v[184:187], v[114:117]
	v_mfma_f32_16x16x32_bf16 v[114:117], v[180:183], v[188:191], v[114:117]
	s_setprio 0
	s_barrier
	s_mov_b32 m0, s27
	s_mov_b32 s18, s14
	s_mov_b32 s19, s15
	ds_read_b128 v[184:187], v174 offset:16384
	ds_read_b128 v[188:191], v174 offset:17408
	ds_read_b128 v[192:195], v174 offset:18432
	ds_read_b128 v[196:199], v174 offset:19456
	ds_read_b128 v[200:203], v174 offset:20480
	ds_read_b128 v[204:207], v174 offset:21504
	ds_read_b128 v[208:211], v174 offset:22528
	ds_read_b128 v[212:215], v174 offset:23552
	buffer_load_dwordx4 v171, s[16:19], s58 offen lds
	s_add_i32 s59, s58, 0x80000
	s_mov_b32 m0, s60
	s_nop 0
	buffer_load_dwordx4 v171, s[16:19], s59 offen lds
	s_add_i32 s59, s58, 0x100000
	s_mov_b32 m0, s61
	s_nop 0
	buffer_load_dwordx4 v171, s[16:19], s59 offen lds
	s_add_i32 s59, s58, 0x180000
	s_mov_b32 m0, s62
	s_nop 0
	buffer_load_dwordx4 v171, s[16:19], s59 offen lds
	s_mov_b32 m0, s25
	s_add_i32 s59, s53, 0x80000
	buffer_load_dwordx4 v170, s[12:15], s53 offen lds
	s_mov_b32 m0, s63
	s_nop 0
	buffer_load_dwordx4 v170, s[12:15], s59 offen lds
	s_waitcnt vmcnt(8)
	s_waitcnt lgkmcnt(0)
	s_setprio 1
	v_mfma_f32_16x16x32_bf16 v[62:65], v[130:133], v[184:187], v[62:65]
	s_barrier
	v_mfma_f32_16x16x32_bf16 v[62:65], v[134:137], v[188:191], v[62:65]
	v_mfma_f32_16x16x32_bf16 v[46:49], v[130:133], v[192:195], v[46:49]
	v_mfma_f32_16x16x32_bf16 v[46:49], v[134:137], v[196:199], v[46:49]
	v_mfma_f32_16x16x32_bf16 v[30:33], v[130:133], v[200:203], v[30:33]
	v_mfma_f32_16x16x32_bf16 v[30:33], v[134:137], v[204:207], v[30:33]
	v_mfma_f32_16x16x32_bf16 v[14:17], v[130:133], v[208:211], v[14:17]
	v_mfma_f32_16x16x32_bf16 v[14:17], v[134:137], v[212:215], v[14:17]
	v_mfma_f32_16x16x32_bf16 v[6:9], v[148:151], v[208:211], v[6:9]
	v_mfma_f32_16x16x32_bf16 v[6:9], v[152:155], v[212:215], v[6:9]
	v_mfma_f32_16x16x32_bf16 v[22:25], v[148:151], v[200:203], v[22:25]
	v_mfma_f32_16x16x32_bf16 v[22:25], v[152:155], v[204:207], v[22:25]
	v_mfma_f32_16x16x32_bf16 v[38:41], v[148:151], v[192:195], v[38:41]
	v_mfma_f32_16x16x32_bf16 v[38:41], v[152:155], v[196:199], v[38:41]
	v_mfma_f32_16x16x32_bf16 v[54:57], v[148:151], v[184:187], v[54:57]
	v_mfma_f32_16x16x32_bf16 v[54:57], v[152:155], v[188:191], v[54:57]
	v_mfma_f32_16x16x32_bf16 v[58:61], v[156:159], v[184:187], v[58:61]
	v_mfma_f32_16x16x32_bf16 v[58:61], v[160:163], v[188:191], v[58:61]
	v_mfma_f32_16x16x32_bf16 v[42:45], v[156:159], v[192:195], v[42:45]
	v_mfma_f32_16x16x32_bf16 v[42:45], v[160:163], v[196:199], v[42:45]
	v_mfma_f32_16x16x32_bf16 v[26:29], v[156:159], v[200:203], v[26:29]
	v_mfma_f32_16x16x32_bf16 v[26:29], v[160:163], v[204:207], v[26:29]
	v_mfma_f32_16x16x32_bf16 v[10:13], v[156:159], v[208:211], v[10:13]
	v_mfma_f32_16x16x32_bf16 v[10:13], v[160:163], v[212:215], v[10:13]
	v_mfma_f32_16x16x32_bf16 v[2:5], v[164:167], v[208:211], v[2:5]
	v_mfma_f32_16x16x32_bf16 v[2:5], v[180:183], v[212:215], v[2:5]
	v_mfma_f32_16x16x32_bf16 v[18:21], v[164:167], v[200:203], v[18:21]
	v_mfma_f32_16x16x32_bf16 v[18:21], v[180:183], v[204:207], v[18:21]
	v_mfma_f32_16x16x32_bf16 v[34:37], v[164:167], v[192:195], v[34:37]
	v_mfma_f32_16x16x32_bf16 v[34:37], v[180:183], v[196:199], v[34:37]
	v_mfma_f32_16x16x32_bf16 v[50:53], v[164:167], v[184:187], v[50:53]
	v_mfma_f32_16x16x32_bf16 v[50:53], v[180:183], v[188:191], v[50:53]
	s_setprio 0
	s_barrier
	ds_read_b128 v[130:133], v175
	ds_read_b128 v[134:137], v175 offset:1024
	ds_read_b128 v[148:151], v175 offset:2048
	ds_read_b128 v[152:155], v175 offset:3072
	ds_read_b128 v[156:159], v176
	ds_read_b128 v[160:163], v176 offset:1024
	ds_read_b128 v[164:167], v176 offset:2048
	ds_read_b128 v[180:183], v176 offset:3072
	s_mov_b32 m0, s64
	s_add_i32 s59, s53, 0x100000
	ds_read_b128 v[184:187], v174 offset:32768
	ds_read_b128 v[188:191], v174 offset:33792
	ds_read_b128 v[192:195], v174 offset:34816
	ds_read_b128 v[196:199], v174 offset:35840
	ds_read_b128 v[200:203], v174 offset:36864
	ds_read_b128 v[204:207], v174 offset:37888
	ds_read_b128 v[208:211], v174 offset:38912
	ds_read_b128 v[212:215], v174 offset:39936
	buffer_load_dwordx4 v170, s[12:15], s59 offen lds
	s_add_i32 s59, s53, 0x180000
	s_mov_b32 m0, s65
	s_nop 0
	buffer_load_dwordx4 v170, s[12:15], s59 offen lds
	s_waitcnt vmcnt(8)
	s_waitcnt lgkmcnt(0)
	s_setprio 1
	v_mfma_f32_16x16x32_bf16 v[126:129], v[130:133], v[184:187], v[126:129]
	s_barrier
	v_mfma_f32_16x16x32_bf16 v[126:129], v[134:137], v[188:191], v[126:129]
	v_mfma_f32_16x16x32_bf16 v[110:113], v[130:133], v[192:195], v[110:113]
	v_mfma_f32_16x16x32_bf16 v[110:113], v[134:137], v[196:199], v[110:113]
	v_mfma_f32_16x16x32_bf16 v[94:97], v[130:133], v[200:203], v[94:97]
	v_mfma_f32_16x16x32_bf16 v[94:97], v[134:137], v[204:207], v[94:97]
	v_mfma_f32_16x16x32_bf16 v[78:81], v[130:133], v[208:211], v[78:81]
	v_mfma_f32_16x16x32_bf16 v[78:81], v[134:137], v[212:215], v[78:81]
	v_mfma_f32_16x16x32_bf16 v[70:73], v[148:151], v[208:211], v[70:73]
	v_mfma_f32_16x16x32_bf16 v[70:73], v[152:155], v[212:215], v[70:73]
	v_mfma_f32_16x16x32_bf16 v[90:93], v[148:151], v[200:203], v[90:93]
	v_mfma_f32_16x16x32_bf16 v[90:93], v[152:155], v[204:207], v[90:93]
	v_mfma_f32_16x16x32_bf16 v[102:105], v[148:151], v[192:195], v[102:105]
	v_mfma_f32_16x16x32_bf16 v[102:105], v[152:155], v[196:199], v[102:105]
	v_mfma_f32_16x16x32_bf16 v[118:121], v[148:151], v[184:187], v[118:121]
	v_mfma_f32_16x16x32_bf16 v[118:121], v[152:155], v[188:191], v[118:121]
	v_mfma_f32_16x16x32_bf16 v[122:125], v[156:159], v[184:187], v[122:125]
	v_mfma_f32_16x16x32_bf16 v[122:125], v[160:163], v[188:191], v[122:125]
	v_mfma_f32_16x16x32_bf16 v[106:109], v[156:159], v[192:195], v[106:109]
	v_mfma_f32_16x16x32_bf16 v[106:109], v[160:163], v[196:199], v[106:109]
	v_mfma_f32_16x16x32_bf16 v[86:89], v[156:159], v[200:203], v[86:89]
	v_mfma_f32_16x16x32_bf16 v[86:89], v[160:163], v[204:207], v[86:89]
	v_mfma_f32_16x16x32_bf16 v[74:77], v[156:159], v[208:211], v[74:77]
	v_mfma_f32_16x16x32_bf16 v[74:77], v[160:163], v[212:215], v[74:77]
	v_mfma_f32_16x16x32_bf16 v[66:69], v[164:167], v[208:211], v[66:69]
	v_mfma_f32_16x16x32_bf16 v[66:69], v[180:183], v[212:215], v[66:69]
	v_mfma_f32_16x16x32_bf16 v[82:85], v[164:167], v[200:203], v[82:85]
	v_mfma_f32_16x16x32_bf16 v[82:85], v[180:183], v[204:207], v[82:85]
	v_mfma_f32_16x16x32_bf16 v[98:101], v[164:167], v[192:195], v[98:101]
	v_mfma_f32_16x16x32_bf16 v[98:101], v[180:183], v[196:199], v[98:101]
	v_mfma_f32_16x16x32_bf16 v[114:117], v[164:167], v[184:187], v[114:117]
	v_mfma_f32_16x16x32_bf16 v[114:117], v[180:183], v[188:191], v[114:117]
	s_setprio 0
	s_barrier
	s_mov_b32 m0, s70
	s_or_b32 s59, s58, 0x80
	ds_read_b128 v[184:187], v174 offset:49152
	ds_read_b128 v[188:191], v174 offset:50176
	ds_read_b128 v[192:195], v174 offset:51200
	ds_read_b128 v[196:199], v174 offset:52224
	ds_read_b128 v[200:203], v174 offset:53248
	ds_read_b128 v[204:207], v174 offset:54272
	ds_read_b128 v[208:211], v174 offset:55296
	ds_read_b128 v[212:215], v174 offset:56320
	buffer_load_dwordx4 v171, s[16:19], s59 offen lds
	s_add_i32 s59, s58, 0x80080
	s_mov_b32 m0, s71
	s_add_i32 s53, s53, 0x80080
	buffer_load_dwordx4 v171, s[16:19], s59 offen lds
	s_add_i32 s59, s58, 0x100080
	s_mov_b32 m0, s74
	s_add_i32 s58, s58, 0x180080
	buffer_load_dwordx4 v171, s[16:19], s59 offen lds
	s_mov_b32 m0, s75
	s_nop 0
	buffer_load_dwordx4 v171, s[16:19], s58 offen lds
	s_mov_b32 m0, s72
	s_nop 0
	buffer_load_dwordx4 v170, s[12:15], s57 offen lds
	s_mov_b32 m0, s73
	s_nop 0
	buffer_load_dwordx4 v170, s[12:15], s53 offen lds
	s_waitcnt vmcnt(8)
	s_waitcnt lgkmcnt(0)
	s_setprio 1
	v_mfma_f32_16x16x32_bf16 v[62:65], v[130:133], v[184:187], v[62:65]
	s_barrier
	v_mfma_f32_16x16x32_bf16 v[62:65], v[134:137], v[188:191], v[62:65]
	v_mfma_f32_16x16x32_bf16 v[46:49], v[130:133], v[192:195], v[46:49]
	v_mfma_f32_16x16x32_bf16 v[46:49], v[134:137], v[196:199], v[46:49]
	v_mfma_f32_16x16x32_bf16 v[30:33], v[130:133], v[200:203], v[30:33]
	v_mfma_f32_16x16x32_bf16 v[30:33], v[134:137], v[204:207], v[30:33]
	v_mfma_f32_16x16x32_bf16 v[14:17], v[130:133], v[208:211], v[14:17]
	v_mfma_f32_16x16x32_bf16 v[14:17], v[134:137], v[212:215], v[14:17]
	v_mfma_f32_16x16x32_bf16 v[6:9], v[148:151], v[208:211], v[6:9]
	v_mfma_f32_16x16x32_bf16 v[6:9], v[152:155], v[212:215], v[6:9]
	v_mfma_f32_16x16x32_bf16 v[22:25], v[148:151], v[200:203], v[22:25]
	v_mfma_f32_16x16x32_bf16 v[22:25], v[152:155], v[204:207], v[22:25]
	v_mfma_f32_16x16x32_bf16 v[38:41], v[148:151], v[192:195], v[38:41]
	v_mfma_f32_16x16x32_bf16 v[38:41], v[152:155], v[196:199], v[38:41]
	v_mfma_f32_16x16x32_bf16 v[54:57], v[148:151], v[184:187], v[54:57]
	v_mfma_f32_16x16x32_bf16 v[54:57], v[152:155], v[188:191], v[54:57]
	v_mfma_f32_16x16x32_bf16 v[58:61], v[156:159], v[184:187], v[58:61]
	v_mfma_f32_16x16x32_bf16 v[58:61], v[160:163], v[188:191], v[58:61]
	v_mfma_f32_16x16x32_bf16 v[42:45], v[156:159], v[192:195], v[42:45]
	v_mfma_f32_16x16x32_bf16 v[42:45], v[160:163], v[196:199], v[42:45]
	v_mfma_f32_16x16x32_bf16 v[26:29], v[156:159], v[200:203], v[26:29]
	v_mfma_f32_16x16x32_bf16 v[26:29], v[160:163], v[204:207], v[26:29]
	v_mfma_f32_16x16x32_bf16 v[10:13], v[156:159], v[208:211], v[10:13]
	v_mfma_f32_16x16x32_bf16 v[10:13], v[160:163], v[212:215], v[10:13]
	v_mfma_f32_16x16x32_bf16 v[2:5], v[164:167], v[208:211], v[2:5]
	v_mfma_f32_16x16x32_bf16 v[2:5], v[180:183], v[212:215], v[2:5]
	v_mfma_f32_16x16x32_bf16 v[18:21], v[164:167], v[200:203], v[18:21]
	v_mfma_f32_16x16x32_bf16 v[18:21], v[180:183], v[204:207], v[18:21]
	v_mfma_f32_16x16x32_bf16 v[34:37], v[164:167], v[192:195], v[34:37]
	v_mfma_f32_16x16x32_bf16 v[34:37], v[180:183], v[196:199], v[34:37]
	v_mfma_f32_16x16x32_bf16 v[50:53], v[164:167], v[184:187], v[50:53]
	v_mfma_f32_16x16x32_bf16 v[50:53], v[180:183], v[188:191], v[50:53]
	s_setprio 0
	s_barrier
	s_add_i32 s52, s52, 2
	s_addk_i32 s8, 0x100
	s_addk_i32 s9, 0x100
	s_cmp_ge_i32 s52, s21
	s_cbranch_scc0 .LBB0_892
	s_and_b64 vcc, exec, s[48:49]
	s_cbranch_vccz .LBB0_895

.LBB0_1020:
	v_add_u32_e32 v142, 0x10000, v162
	v_add_u32_e32 v150, 0x14000, v162
	ds_read_b128 v[130:133], v142
	ds_read_b128 v[134:137], v142 offset:1024
	ds_read_b128 v[138:141], v142 offset:2048
	ds_read_b128 v[142:145], v142 offset:3072
	ds_read_b128 v[154:157], v150
	ds_read_b128 v[164:167], v150 offset:1024
	ds_read_b128 v[168:171], v150 offset:2048
	ds_read_b128 v[172:175], v150 offset:3072
	s_add_i32 s90, s6, 0x100
	s_add_i32 s7, s88, s6
	s_cmp_eq_u32 s81, s89
	s_cselect_b32 s91, 0, s90
	s_cselect_b32 s93, s87, s7
	s_add_i32 s91, s91, s70
	s_or_b32 s92, s91, 0x80
	s_add_i32 s6, s3, s6
	s_mov_b32 m0, s82
	s_add_i32 s7, s6, 0x20080
	ds_read_b128 v[176:179], v163
	ds_read_b128 v[180:183], v163 offset:1024
	ds_read_b128 v[184:187], v163 offset:2048
	ds_read_b128 v[188:191], v163 offset:3072
	ds_read_b128 v[192:195], v163 offset:4096
	ds_read_b128 v[196:199], v163 offset:5120
	ds_read_b128 v[200:203], v163 offset:6144
	ds_read_b128 v[204:207], v163 offset:7168
	buffer_load_dwordx4 v161, s[12:15], s7 offen lds
	s_add_i32 s6, s6, 0x30080
	s_mov_b32 m0, s83
	s_nop 0
	buffer_load_dwordx4 v161, s[12:15], s6 offen lds
	s_waitcnt vmcnt(8)
	s_waitcnt lgkmcnt(0)
	s_setprio 1
	v_mfma_f32_16x16x32_bf16 v[126:129], v[130:133], v[176:179], v[126:129]
	s_barrier
	v_mfma_f32_16x16x32_bf16 v[126:129], v[134:137], v[180:183], v[126:129]
	v_mfma_f32_16x16x32_bf16 v[110:113], v[130:133], v[184:187], v[110:113]
	v_mfma_f32_16x16x32_bf16 v[110:113], v[134:137], v[188:191], v[110:113]
	v_mfma_f32_16x16x32_bf16 v[94:97], v[130:133], v[192:195], v[94:97]
	v_mfma_f32_16x16x32_bf16 v[94:97], v[134:137], v[196:199], v[94:97]
	v_mfma_f32_16x16x32_bf16 v[78:81], v[130:133], v[200:203], v[78:81]
	v_mfma_f32_16x16x32_bf16 v[78:81], v[134:137], v[204:207], v[78:81]
	v_mfma_f32_16x16x32_bf16 v[74:77], v[138:141], v[200:203], v[74:77]
	v_mfma_f32_16x16x32_bf16 v[74:77], v[142:145], v[204:207], v[74:77]
	v_mfma_f32_16x16x32_bf16 v[90:93], v[138:141], v[192:195], v[90:93]
	v_mfma_f32_16x16x32_bf16 v[90:93], v[142:145], v[196:199], v[90:93]
	v_mfma_f32_16x16x32_bf16 v[106:109], v[138:141], v[184:187], v[106:109]
	v_mfma_f32_16x16x32_bf16 v[106:109], v[142:145], v[188:191], v[106:109]
	v_mfma_f32_16x16x32_bf16 v[122:125], v[138:141], v[176:179], v[122:125]
	v_mfma_f32_16x16x32_bf16 v[122:125], v[142:145], v[180:183], v[122:125]
	v_mfma_f32_16x16x32_bf16 v[118:121], v[154:157], v[176:179], v[118:121]
	v_mfma_f32_16x16x32_bf16 v[118:121], v[164:167], v[180:183], v[118:121]
	v_mfma_f32_16x16x32_bf16 v[102:105], v[154:157], v[184:187], v[102:105]
	v_mfma_f32_16x16x32_bf16 v[102:105], v[164:167], v[188:191], v[102:105]
	v_mfma_f32_16x16x32_bf16 v[86:89], v[154:157], v[192:195], v[86:89]
	v_mfma_f32_16x16x32_bf16 v[86:89], v[164:167], v[196:199], v[86:89]
	v_mfma_f32_16x16x32_bf16 v[70:73], v[154:157], v[200:203], v[70:73]
	v_mfma_f32_16x16x32_bf16 v[70:73], v[164:167], v[204:207], v[70:73]
	v_mfma_f32_16x16x32_bf16 v[66:69], v[168:171], v[200:203], v[66:69]
	v_mfma_f32_16x16x32_bf16 v[66:69], v[172:175], v[204:207], v[66:69]
	v_mfma_f32_16x16x32_bf16 v[82:85], v[168:171], v[192:195], v[82:85]
	v_mfma_f32_16x16x32_bf16 v[82:85], v[172:175], v[196:199], v[82:85]
	v_mfma_f32_16x16x32_bf16 v[98:101], v[168:171], v[184:187], v[98:101]
	v_mfma_f32_16x16x32_bf16 v[98:101], v[172:175], v[188:191], v[98:101]
	v_mfma_f32_16x16x32_bf16 v[114:117], v[168:171], v[176:179], v[114:117]
	v_mfma_f32_16x16x32_bf16 v[114:117], v[172:175], v[180:183], v[114:117]
	s_setprio 0
	s_barrier
	s_mov_b32 m0, s66
	s_mov_b32 s6, s14
	s_mov_b32 s7, s15
	ds_read_b128 v[176:179], v163 offset:16384
	ds_read_b128 v[180:183], v163 offset:17408
	ds_read_b128 v[184:187], v163 offset:18432
	ds_read_b128 v[188:191], v163 offset:19456
	ds_read_b128 v[192:195], v163 offset:20480
	ds_read_b128 v[196:199], v163 offset:21504
	ds_read_b128 v[200:203], v163 offset:22528
	ds_read_b128 v[204:207], v163 offset:23552
	buffer_load_dwordx4 v160, s[4:7], s93 offen lds
	s_add_i32 s94, s93, 0x10000
	s_mov_b32 m0, s67
	s_nop 0
	buffer_load_dwordx4 v160, s[4:7], s94 offen lds
	s_add_i32 s94, s93, 0x20000
	s_mov_b32 m0, s68
	s_nop 0
	buffer_load_dwordx4 v160, s[4:7], s94 offen lds
	s_add_i32 s94, s93, 0x30000
	s_mov_b32 m0, s69
	s_nop 0
	buffer_load_dwordx4 v160, s[4:7], s94 offen lds
	s_mov_b32 m0, s65
	s_add_i32 s94, s91, 0x10000
	buffer_load_dwordx4 v161, s[12:15], s91 offen lds
	s_mov_b32 m0, s71
	s_nop 0
	buffer_load_dwordx4 v161, s[12:15], s94 offen lds
	s_waitcnt vmcnt(8)
	s_waitcnt lgkmcnt(0)
	s_setprio 1
	v_mfma_f32_16x16x32_bf16 v[62:65], v[130:133], v[176:179], v[62:65]
	s_barrier
	v_mfma_f32_16x16x32_bf16 v[62:65], v[134:137], v[180:183], v[62:65]
	v_mfma_f32_16x16x32_bf16 v[46:49], v[130:133], v[184:187], v[46:49]
	v_mfma_f32_16x16x32_bf16 v[46:49], v[134:137], v[188:191], v[46:49]
	v_mfma_f32_16x16x32_bf16 v[30:33], v[130:133], v[192:195], v[30:33]
	v_mfma_f32_16x16x32_bf16 v[30:33], v[134:137], v[196:199], v[30:33]
	v_mfma_f32_16x16x32_bf16 v[14:17], v[130:133], v[200:203], v[14:17]
	v_mfma_f32_16x16x32_bf16 v[14:17], v[134:137], v[204:207], v[14:17]
	v_mfma_f32_16x16x32_bf16 v[10:13], v[138:141], v[200:203], v[10:13]
	v_mfma_f32_16x16x32_bf16 v[10:13], v[142:145], v[204:207], v[10:13]
	v_mfma_f32_16x16x32_bf16 v[26:29], v[138:141], v[192:195], v[26:29]
	v_mfma_f32_16x16x32_bf16 v[26:29], v[142:145], v[196:199], v[26:29]
	v_mfma_f32_16x16x32_bf16 v[42:45], v[138:141], v[184:187], v[42:45]
	v_mfma_f32_16x16x32_bf16 v[42:45], v[142:145], v[188:191], v[42:45]
	v_mfma_f32_16x16x32_bf16 v[58:61], v[138:141], v[176:179], v[58:61]
	v_mfma_f32_16x16x32_bf16 v[58:61], v[142:145], v[180:183], v[58:61]
	v_mfma_f32_16x16x32_bf16 v[54:57], v[154:157], v[176:179], v[54:57]
	v_mfma_f32_16x16x32_bf16 v[54:57], v[164:167], v[180:183], v[54:57]
	v_mfma_f32_16x16x32_bf16 v[38:41], v[154:157], v[184:187], v[38:41]
	v_mfma_f32_16x16x32_bf16 v[38:41], v[164:167], v[188:191], v[38:41]
	v_mfma_f32_16x16x32_bf16 v[22:25], v[154:157], v[192:195], v[22:25]
	v_mfma_f32_16x16x32_bf16 v[22:25], v[164:167], v[196:199], v[22:25]
	v_mfma_f32_16x16x32_bf16 v[6:9], v[154:157], v[200:203], v[6:9]
	v_mfma_f32_16x16x32_bf16 v[6:9], v[164:167], v[204:207], v[6:9]
	v_mfma_f32_16x16x32_bf16 v[2:5], v[168:171], v[200:203], v[2:5]
	v_mfma_f32_16x16x32_bf16 v[2:5], v[172:175], v[204:207], v[2:5]
	v_mfma_f32_16x16x32_bf16 v[18:21], v[168:171], v[192:195], v[18:21]
	v_mfma_f32_16x16x32_bf16 v[18:21], v[172:175], v[196:199], v[18:21]
	v_mfma_f32_16x16x32_bf16 v[34:37], v[168:171], v[184:187], v[34:37]
	v_mfma_f32_16x16x32_bf16 v[34:37], v[172:175], v[188:191], v[34:37]
	v_mfma_f32_16x16x32_bf16 v[50:53], v[168:171], v[176:179], v[50:53]
	v_mfma_f32_16x16x32_bf16 v[50:53], v[172:175], v[180:183], v[50:53]
	s_setprio 0
	s_barrier
	v_add_u32_e32 v142, 0x18000, v162
	v_add_u32_e32 v150, 0x1c000, v162
	ds_read_b128 v[130:133], v142
	ds_read_b128 v[134:137], v142 offset:1024
	ds_read_b128 v[138:141], v142 offset:2048
	ds_read_b128 v[142:145], v142 offset:3072
	ds_read_b128 v[154:157], v150
	ds_read_b128 v[164:167], v150 offset:1024
	ds_read_b128 v[168:171], v150 offset:2048
	ds_read_b128 v[172:175], v150 offset:3072
	s_mov_b32 m0, s72
	s_add_i32 s94, s91, 0x20000
	ds_read_b128 v[176:179], v163 offset:32768
	ds_read_b128 v[180:183], v163 offset:33792
	ds_read_b128 v[184:187], v163 offset:34816
	ds_read_b128 v[188:191], v163 offset:35840
	ds_read_b128 v[192:195], v163 offset:36864
	ds_read_b128 v[196:199], v163 offset:37888
	ds_read_b128 v[200:203], v163 offset:38912
	ds_read_b128 v[204:207], v163 offset:39936
	buffer_load_dwordx4 v161, s[12:15], s94 offen lds
	s_add_i32 s94, s91, 0x30000
	s_mov_b32 m0, s73
	s_nop 0
	buffer_load_dwordx4 v161, s[12:15], s94 offen lds
	s_waitcnt vmcnt(8)
	s_waitcnt lgkmcnt(0)
	s_setprio 1
	v_mfma_f32_16x16x32_bf16 v[126:129], v[130:133], v[176:179], v[126:129]
	s_barrier
	v_mfma_f32_16x16x32_bf16 v[126:129], v[134:137], v[180:183], v[126:129]
	v_mfma_f32_16x16x32_bf16 v[110:113], v[130:133], v[184:187], v[110:113]
	v_mfma_f32_16x16x32_bf16 v[110:113], v[134:137], v[188:191], v[110:113]
	v_mfma_f32_16x16x32_bf16 v[94:97], v[130:133], v[192:195], v[94:97]
	v_mfma_f32_16x16x32_bf16 v[94:97], v[134:137], v[196:199], v[94:97]
	v_mfma_f32_16x16x32_bf16 v[78:81], v[130:133], v[200:203], v[78:81]
	v_mfma_f32_16x16x32_bf16 v[78:81], v[134:137], v[204:207], v[78:81]
	v_mfma_f32_16x16x32_bf16 v[74:77], v[138:141], v[200:203], v[74:77]
	v_mfma_f32_16x16x32_bf16 v[74:77], v[142:145], v[204:207], v[74:77]
	v_mfma_f32_16x16x32_bf16 v[90:93], v[138:141], v[192:195], v[90:93]
	v_mfma_f32_16x16x32_bf16 v[90:93], v[142:145], v[196:199], v[90:93]
	v_mfma_f32_16x16x32_bf16 v[106:109], v[138:141], v[184:187], v[106:109]
	v_mfma_f32_16x16x32_bf16 v[106:109], v[142:145], v[188:191], v[106:109]
	v_mfma_f32_16x16x32_bf16 v[122:125], v[138:141], v[176:179], v[122:125]
	v_mfma_f32_16x16x32_bf16 v[122:125], v[142:145], v[180:183], v[122:125]
	v_mfma_f32_16x16x32_bf16 v[118:121], v[154:157], v[176:179], v[118:121]
	v_mfma_f32_16x16x32_bf16 v[118:121], v[164:167], v[180:183], v[118:121]
	v_mfma_f32_16x16x32_bf16 v[102:105], v[154:157], v[184:187], v[102:105]
	v_mfma_f32_16x16x32_bf16 v[102:105], v[164:167], v[188:191], v[102:105]
	v_mfma_f32_16x16x32_bf16 v[86:89], v[154:157], v[192:195], v[86:89]
	v_mfma_f32_16x16x32_bf16 v[86:89], v[164:167], v[196:199], v[86:89]
	v_mfma_f32_16x16x32_bf16 v[70:73], v[154:157], v[200:203], v[70:73]
	v_mfma_f32_16x16x32_bf16 v[70:73], v[164:167], v[204:207], v[70:73]
	v_mfma_f32_16x16x32_bf16 v[66:69], v[168:171], v[200:203], v[66:69]
	v_mfma_f32_16x16x32_bf16 v[66:69], v[172:175], v[204:207], v[66:69]
	v_mfma_f32_16x16x32_bf16 v[82:85], v[168:171], v[192:195], v[82:85]
	v_mfma_f32_16x16x32_bf16 v[82:85], v[172:175], v[196:199], v[82:85]
	v_mfma_f32_16x16x32_bf16 v[98:101], v[168:171], v[184:187], v[98:101]
	v_mfma_f32_16x16x32_bf16 v[98:101], v[172:175], v[188:191], v[98:101]
	v_mfma_f32_16x16x32_bf16 v[114:117], v[168:171], v[176:179], v[114:117]
	v_mfma_f32_16x16x32_bf16 v[114:117], v[172:175], v[180:183], v[114:117]
	s_setprio 0
	s_barrier
	s_mov_b32 m0, s74
	s_or_b32 s94, s93, 0x80
	ds_read_b128 v[176:179], v163 offset:49152
	ds_read_b128 v[180:183], v163 offset:50176
	ds_read_b128 v[184:187], v163 offset:51200
	ds_read_b128 v[188:191], v163 offset:52224
	ds_read_b128 v[192:195], v163 offset:53248
	ds_read_b128 v[196:199], v163 offset:54272
	ds_read_b128 v[200:203], v163 offset:55296
	ds_read_b128 v[204:207], v163 offset:56320
	buffer_load_dwordx4 v160, s[4:7], s94 offen lds
	s_add_i32 s94, s93, 0x10080
	s_mov_b32 m0, s75
	s_add_i32 s91, s91, 0x10080
	buffer_load_dwordx4 v160, s[4:7], s94 offen lds
	s_add_i32 s94, s93, 0x20080
	s_mov_b32 m0, s78
	s_add_i32 s93, s93, 0x30080
	buffer_load_dwordx4 v160, s[4:7], s94 offen lds
	s_mov_b32 m0, s79
	s_nop 0
	buffer_load_dwordx4 v160, s[4:7], s93 offen lds
	s_mov_b32 m0, s76
	s_nop 0
	buffer_load_dwordx4 v161, s[12:15], s92 offen lds
	s_mov_b32 m0, s77
	s_nop 0
	buffer_load_dwordx4 v161, s[12:15], s91 offen lds
	s_waitcnt vmcnt(8)
	s_waitcnt lgkmcnt(0)
	s_setprio 1
	v_mfma_f32_16x16x32_bf16 v[62:65], v[130:133], v[176:179], v[62:65]
	s_barrier
	v_mfma_f32_16x16x32_bf16 v[62:65], v[134:137], v[180:183], v[62:65]
	v_mfma_f32_16x16x32_bf16 v[46:49], v[130:133], v[184:187], v[46:49]
	v_mfma_f32_16x16x32_bf16 v[46:49], v[134:137], v[188:191], v[46:49]
	v_mfma_f32_16x16x32_bf16 v[30:33], v[130:133], v[192:195], v[30:33]
	v_mfma_f32_16x16x32_bf16 v[30:33], v[134:137], v[196:199], v[30:33]
	v_mfma_f32_16x16x32_bf16 v[14:17], v[130:133], v[200:203], v[14:17]
	v_mfma_f32_16x16x32_bf16 v[14:17], v[134:137], v[204:207], v[14:17]
	v_mfma_f32_16x16x32_bf16 v[10:13], v[138:141], v[200:203], v[10:13]
	v_mfma_f32_16x16x32_bf16 v[10:13], v[142:145], v[204:207], v[10:13]
	v_mfma_f32_16x16x32_bf16 v[26:29], v[138:141], v[192:195], v[26:29]
	v_mfma_f32_16x16x32_bf16 v[26:29], v[142:145], v[196:199], v[26:29]
	v_mfma_f32_16x16x32_bf16 v[42:45], v[138:141], v[184:187], v[42:45]
	v_mfma_f32_16x16x32_bf16 v[42:45], v[142:145], v[188:191], v[42:45]
	v_mfma_f32_16x16x32_bf16 v[58:61], v[138:141], v[176:179], v[58:61]
	v_mfma_f32_16x16x32_bf16 v[58:61], v[142:145], v[180:183], v[58:61]
	v_mfma_f32_16x16x32_bf16 v[54:57], v[154:157], v[176:179], v[54:57]
	v_mfma_f32_16x16x32_bf16 v[54:57], v[164:167], v[180:183], v[54:57]
	v_mfma_f32_16x16x32_bf16 v[38:41], v[154:157], v[184:187], v[38:41]
	v_mfma_f32_16x16x32_bf16 v[38:41], v[164:167], v[188:191], v[38:41]
	v_mfma_f32_16x16x32_bf16 v[22:25], v[154:157], v[192:195], v[22:25]
	v_mfma_f32_16x16x32_bf16 v[22:25], v[164:167], v[196:199], v[22:25]
	v_mfma_f32_16x16x32_bf16 v[6:9], v[154:157], v[200:203], v[6:9]
	v_mfma_f32_16x16x32_bf16 v[6:9], v[164:167], v[204:207], v[6:9]
	v_mfma_f32_16x16x32_bf16 v[2:5], v[168:171], v[200:203], v[2:5]
	v_mfma_f32_16x16x32_bf16 v[2:5], v[172:175], v[204:207], v[2:5]
	v_mfma_f32_16x16x32_bf16 v[18:21], v[168:171], v[192:195], v[18:21]
	v_mfma_f32_16x16x32_bf16 v[18:21], v[172:175], v[196:199], v[18:21]
	v_mfma_f32_16x16x32_bf16 v[34:37], v[168:171], v[184:187], v[34:37]
	v_mfma_f32_16x16x32_bf16 v[34:37], v[172:175], v[188:191], v[34:37]
	v_mfma_f32_16x16x32_bf16 v[50:53], v[168:171], v[176:179], v[50:53]
	v_mfma_f32_16x16x32_bf16 v[50:53], v[172:175], v[180:183], v[50:53]
	s_setprio 0
	s_barrier
	s_add_i32 s89, s89, 2
	s_cmp_ge_i32 s89, s63
	s_mov_b32 s6, s90
	s_cbranch_scc0 .LBB0_1020
	s_and_b64 vcc, exec, s[54:55]
	s_cbranch_vccz .LBB0_1023

.LBB0_1035:
	ds_read_b128 v[140:143], v134
	ds_read_b128 v[148:151], v134 offset:1024
	ds_read_b128 v[152:155], v134 offset:2048
	ds_read_b128 v[156:159], v134 offset:3072
	ds_read_b128 v[160:163], v135
	ds_read_b128 v[164:167], v135 offset:1024
	ds_read_b128 v[168:171], v135 offset:2048
	ds_read_b128 v[172:175], v135 offset:3072
	s_add_i32 s73, s70, 0xfffb8080
	s_cmp_eq_u32 s53, s72
	s_cselect_b32 s73, s68, s73
	s_cselect_b32 s75, s69, s71
	s_add_i32 s74, s73, 0x80
	s_add_i32 s76, s70, 0xfffe8000
	s_mov_b32 m0, s54
	ds_read_b128 v[176:179], v136
	ds_read_b128 v[180:183], v136 offset:1024
	ds_read_b128 v[184:187], v136 offset:2048
	ds_read_b128 v[188:191], v136 offset:3072
	ds_read_b128 v[192:195], v136 offset:4096
	ds_read_b128 v[196:199], v136 offset:5120
	ds_read_b128 v[200:203], v136 offset:6144
	ds_read_b128 v[204:207], v136 offset:7168
	buffer_load_dwordx4 v132, s[12:15], s76 offen lds
	s_mov_b32 m0, s55
	s_nop 0
	buffer_load_dwordx4 v132, s[12:15], s70 offen lds
	s_waitcnt vmcnt(8)
	s_waitcnt lgkmcnt(0)
	s_setprio 1
	v_mfma_f32_16x16x32_bf16 v[126:129], v[140:143], v[176:179], v[126:129]
	s_barrier
	v_mfma_f32_16x16x32_bf16 v[126:129], v[148:151], v[180:183], v[126:129]
	v_mfma_f32_16x16x32_bf16 v[110:113], v[140:143], v[184:187], v[110:113]
	v_mfma_f32_16x16x32_bf16 v[110:113], v[148:151], v[188:191], v[110:113]
	v_mfma_f32_16x16x32_bf16 v[94:97], v[140:143], v[192:195], v[94:97]
	v_mfma_f32_16x16x32_bf16 v[94:97], v[148:151], v[196:199], v[94:97]
	v_mfma_f32_16x16x32_bf16 v[78:81], v[140:143], v[200:203], v[78:81]
	v_mfma_f32_16x16x32_bf16 v[78:81], v[148:151], v[204:207], v[78:81]
	v_mfma_f32_16x16x32_bf16 v[74:77], v[152:155], v[200:203], v[74:77]
	v_mfma_f32_16x16x32_bf16 v[74:77], v[156:159], v[204:207], v[74:77]
	v_mfma_f32_16x16x32_bf16 v[90:93], v[152:155], v[192:195], v[90:93]
	v_mfma_f32_16x16x32_bf16 v[90:93], v[156:159], v[196:199], v[90:93]
	v_mfma_f32_16x16x32_bf16 v[106:109], v[152:155], v[184:187], v[106:109]
	v_mfma_f32_16x16x32_bf16 v[106:109], v[156:159], v[188:191], v[106:109]
	v_mfma_f32_16x16x32_bf16 v[122:125], v[152:155], v[176:179], v[122:125]
	v_mfma_f32_16x16x32_bf16 v[122:125], v[156:159], v[180:183], v[122:125]
	v_mfma_f32_16x16x32_bf16 v[118:121], v[160:163], v[176:179], v[118:121]
	v_mfma_f32_16x16x32_bf16 v[118:121], v[164:167], v[180:183], v[118:121]
	v_mfma_f32_16x16x32_bf16 v[102:105], v[160:163], v[184:187], v[102:105]
	v_mfma_f32_16x16x32_bf16 v[102:105], v[164:167], v[188:191], v[102:105]
	v_mfma_f32_16x16x32_bf16 v[86:89], v[160:163], v[192:195], v[86:89]
	v_mfma_f32_16x16x32_bf16 v[86:89], v[164:167], v[196:199], v[86:89]
	v_mfma_f32_16x16x32_bf16 v[70:73], v[160:163], v[200:203], v[70:73]
	v_mfma_f32_16x16x32_bf16 v[70:73], v[164:167], v[204:207], v[70:73]
	v_mfma_f32_16x16x32_bf16 v[66:69], v[168:171], v[200:203], v[66:69]
	v_mfma_f32_16x16x32_bf16 v[66:69], v[172:175], v[204:207], v[66:69]
	v_mfma_f32_16x16x32_bf16 v[82:85], v[168:171], v[192:195], v[82:85]
	v_mfma_f32_16x16x32_bf16 v[82:85], v[172:175], v[196:199], v[82:85]
	v_mfma_f32_16x16x32_bf16 v[98:101], v[168:171], v[184:187], v[98:101]
	v_mfma_f32_16x16x32_bf16 v[98:101], v[172:175], v[188:191], v[98:101]
	v_mfma_f32_16x16x32_bf16 v[114:117], v[168:171], v[176:179], v[114:117]
	v_mfma_f32_16x16x32_bf16 v[114:117], v[172:175], v[180:183], v[114:117]
	s_setprio 0
	s_barrier
	s_mov_b32 m0, s30
	ds_read_b128 v[176:179], v136 offset:16384
	ds_read_b128 v[180:183], v136 offset:17408
	ds_read_b128 v[184:187], v136 offset:18432
	ds_read_b128 v[188:191], v136 offset:19456
	ds_read_b128 v[192:195], v136 offset:20480
	ds_read_b128 v[196:199], v136 offset:21504
	ds_read_b128 v[200:203], v136 offset:22528
	ds_read_b128 v[204:207], v136 offset:23552
	buffer_load_dwordx4 v133, s[16:19], s75 offen lds
	s_add_i32 s76, s75, 0x200000
	s_mov_b32 m0, s31
	s_nop 0
	buffer_load_dwordx4 v133, s[16:19], s76 offen lds
	s_add_i32 s76, s75, 0x400000
	s_mov_b32 m0, s35
	s_nop 0
	buffer_load_dwordx4 v133, s[16:19], s76 offen lds
	s_add_i32 s76, s75, 0x600000
	s_mov_b32 m0, s42
	s_nop 0
	buffer_load_dwordx4 v133, s[16:19], s76 offen lds
	s_mov_b32 m0, s27
	s_add_i32 s76, s73, 0x18000
	buffer_load_dwordx4 v132, s[12:15], s73 offen lds
	s_mov_b32 m0, s43
	s_nop 0
	buffer_load_dwordx4 v132, s[12:15], s76 offen lds
	s_waitcnt vmcnt(8)
	s_waitcnt lgkmcnt(0)
	s_setprio 1
	v_mfma_f32_16x16x32_bf16 v[62:65], v[140:143], v[176:179], v[62:65]
	s_barrier
	v_mfma_f32_16x16x32_bf16 v[62:65], v[148:151], v[180:183], v[62:65]
	v_mfma_f32_16x16x32_bf16 v[46:49], v[140:143], v[184:187], v[46:49]
	v_mfma_f32_16x16x32_bf16 v[46:49], v[148:151], v[188:191], v[46:49]
	v_mfma_f32_16x16x32_bf16 v[30:33], v[140:143], v[192:195], v[30:33]
	v_mfma_f32_16x16x32_bf16 v[30:33], v[148:151], v[196:199], v[30:33]
	v_mfma_f32_16x16x32_bf16 v[14:17], v[140:143], v[200:203], v[14:17]
	v_mfma_f32_16x16x32_bf16 v[14:17], v[148:151], v[204:207], v[14:17]
	v_mfma_f32_16x16x32_bf16 v[10:13], v[152:155], v[200:203], v[10:13]
	v_mfma_f32_16x16x32_bf16 v[10:13], v[156:159], v[204:207], v[10:13]
	v_mfma_f32_16x16x32_bf16 v[26:29], v[152:155], v[192:195], v[26:29]
	v_mfma_f32_16x16x32_bf16 v[26:29], v[156:159], v[196:199], v[26:29]
	v_mfma_f32_16x16x32_bf16 v[42:45], v[152:155], v[184:187], v[42:45]
	v_mfma_f32_16x16x32_bf16 v[42:45], v[156:159], v[188:191], v[42:45]
	v_mfma_f32_16x16x32_bf16 v[58:61], v[152:155], v[176:179], v[58:61]
	v_mfma_f32_16x16x32_bf16 v[58:61], v[156:159], v[180:183], v[58:61]
	v_mfma_f32_16x16x32_bf16 v[54:57], v[160:163], v[176:179], v[54:57]
	v_mfma_f32_16x16x32_bf16 v[54:57], v[164:167], v[180:183], v[54:57]
	v_mfma_f32_16x16x32_bf16 v[38:41], v[160:163], v[184:187], v[38:41]
	v_mfma_f32_16x16x32_bf16 v[38:41], v[164:167], v[188:191], v[38:41]
	v_mfma_f32_16x16x32_bf16 v[22:25], v[160:163], v[192:195], v[22:25]
	v_mfma_f32_16x16x32_bf16 v[22:25], v[164:167], v[196:199], v[22:25]
	v_mfma_f32_16x16x32_bf16 v[6:9], v[160:163], v[200:203], v[6:9]
	v_mfma_f32_16x16x32_bf16 v[6:9], v[164:167], v[204:207], v[6:9]
	v_mfma_f32_16x16x32_bf16 v[2:5], v[168:171], v[200:203], v[2:5]
	v_mfma_f32_16x16x32_bf16 v[2:5], v[172:175], v[204:207], v[2:5]
	v_mfma_f32_16x16x32_bf16 v[18:21], v[168:171], v[192:195], v[18:21]
	v_mfma_f32_16x16x32_bf16 v[18:21], v[172:175], v[196:199], v[18:21]
	v_mfma_f32_16x16x32_bf16 v[34:37], v[168:171], v[184:187], v[34:37]
	v_mfma_f32_16x16x32_bf16 v[34:37], v[172:175], v[188:191], v[34:37]
	v_mfma_f32_16x16x32_bf16 v[50:53], v[168:171], v[176:179], v[50:53]
	v_mfma_f32_16x16x32_bf16 v[50:53], v[172:175], v[180:183], v[50:53]
	s_setprio 0
	s_barrier
	ds_read_b128 v[140:143], v137
	ds_read_b128 v[148:151], v137 offset:1024
	ds_read_b128 v[152:155], v137 offset:2048
	ds_read_b128 v[156:159], v137 offset:3072
	ds_read_b128 v[160:163], v138
	ds_read_b128 v[164:167], v138 offset:1024
	ds_read_b128 v[168:171], v138 offset:2048
	ds_read_b128 v[172:175], v138 offset:3072
	s_mov_b32 m0, s44
	s_add_i32 s76, s73, 0x30000
	ds_read_b128 v[176:179], v136 offset:32768
	ds_read_b128 v[180:183], v136 offset:33792
	ds_read_b128 v[184:187], v136 offset:34816
	ds_read_b128 v[188:191], v136 offset:35840
	ds_read_b128 v[192:195], v136 offset:36864
	ds_read_b128 v[196:199], v136 offset:37888
	ds_read_b128 v[200:203], v136 offset:38912
	ds_read_b128 v[204:207], v136 offset:39936
	buffer_load_dwordx4 v132, s[12:15], s76 offen lds
	s_add_i32 s76, s73, 0x48000
	s_mov_b32 m0, s45
	s_nop 0
	buffer_load_dwordx4 v132, s[12:15], s76 offen lds
	s_waitcnt vmcnt(8)
	s_waitcnt lgkmcnt(0)
	s_setprio 1
	v_mfma_f32_16x16x32_bf16 v[126:129], v[140:143], v[176:179], v[126:129]
	s_barrier
	v_mfma_f32_16x16x32_bf16 v[126:129], v[148:151], v[180:183], v[126:129]
	v_mfma_f32_16x16x32_bf16 v[110:113], v[140:143], v[184:187], v[110:113]
	v_mfma_f32_16x16x32_bf16 v[110:113], v[148:151], v[188:191], v[110:113]
	v_mfma_f32_16x16x32_bf16 v[94:97], v[140:143], v[192:195], v[94:97]
	v_mfma_f32_16x16x32_bf16 v[94:97], v[148:151], v[196:199], v[94:97]
	v_mfma_f32_16x16x32_bf16 v[78:81], v[140:143], v[200:203], v[78:81]
	v_mfma_f32_16x16x32_bf16 v[78:81], v[148:151], v[204:207], v[78:81]
	v_mfma_f32_16x16x32_bf16 v[74:77], v[152:155], v[200:203], v[74:77]
	v_mfma_f32_16x16x32_bf16 v[74:77], v[156:159], v[204:207], v[74:77]
	v_mfma_f32_16x16x32_bf16 v[90:93], v[152:155], v[192:195], v[90:93]
	v_mfma_f32_16x16x32_bf16 v[90:93], v[156:159], v[196:199], v[90:93]
	v_mfma_f32_16x16x32_bf16 v[106:109], v[152:155], v[184:187], v[106:109]
	v_mfma_f32_16x16x32_bf16 v[106:109], v[156:159], v[188:191], v[106:109]
	v_mfma_f32_16x16x32_bf16 v[122:125], v[152:155], v[176:179], v[122:125]
	v_mfma_f32_16x16x32_bf16 v[122:125], v[156:159], v[180:183], v[122:125]
	v_mfma_f32_16x16x32_bf16 v[118:121], v[160:163], v[176:179], v[118:121]
	v_mfma_f32_16x16x32_bf16 v[118:121], v[164:167], v[180:183], v[118:121]
	v_mfma_f32_16x16x32_bf16 v[102:105], v[160:163], v[184:187], v[102:105]
	v_mfma_f32_16x16x32_bf16 v[102:105], v[164:167], v[188:191], v[102:105]
	v_mfma_f32_16x16x32_bf16 v[86:89], v[160:163], v[192:195], v[86:89]
	v_mfma_f32_16x16x32_bf16 v[86:89], v[164:167], v[196:199], v[86:89]
	v_mfma_f32_16x16x32_bf16 v[70:73], v[160:163], v[200:203], v[70:73]
	v_mfma_f32_16x16x32_bf16 v[70:73], v[164:167], v[204:207], v[70:73]
	v_mfma_f32_16x16x32_bf16 v[66:69], v[168:171], v[200:203], v[66:69]
	v_mfma_f32_16x16x32_bf16 v[66:69], v[172:175], v[204:207], v[66:69]
	v_mfma_f32_16x16x32_bf16 v[82:85], v[168:171], v[192:195], v[82:85]
	v_mfma_f32_16x16x32_bf16 v[82:85], v[172:175], v[196:199], v[82:85]
	v_mfma_f32_16x16x32_bf16 v[98:101], v[168:171], v[184:187], v[98:101]
	v_mfma_f32_16x16x32_bf16 v[98:101], v[172:175], v[188:191], v[98:101]
	v_mfma_f32_16x16x32_bf16 v[114:117], v[168:171], v[176:179], v[114:117]
	v_mfma_f32_16x16x32_bf16 v[114:117], v[172:175], v[180:183], v[114:117]
	s_setprio 0
	s_barrier
	s_mov_b32 m0, s46
	s_add_i32 s76, s75, 0x80
	ds_read_b128 v[176:179], v136 offset:49152
	ds_read_b128 v[180:183], v136 offset:50176
	ds_read_b128 v[184:187], v136 offset:51200
	ds_read_b128 v[188:191], v136 offset:52224
	ds_read_b128 v[192:195], v136 offset:53248
	ds_read_b128 v[196:199], v136 offset:54272
	ds_read_b128 v[200:203], v136 offset:55296
	ds_read_b128 v[204:207], v136 offset:56320
	buffer_load_dwordx4 v133, s[16:19], s76 offen lds
	s_add_i32 s76, s75, 0x200080
	s_mov_b32 m0, s47
	s_add_i32 s73, s73, 0x18080
	buffer_load_dwordx4 v133, s[16:19], s76 offen lds
	s_add_i32 s76, s75, 0x400080
	s_mov_b32 m0, s50
	s_add_i32 s75, s75, 0x600080
	buffer_load_dwordx4 v133, s[16:19], s76 offen lds
	s_mov_b32 m0, s51
	s_nop 0
	buffer_load_dwordx4 v133, s[16:19], s75 offen lds
	s_mov_b32 m0, s48
	s_nop 0
	buffer_load_dwordx4 v132, s[12:15], s74 offen lds
	s_mov_b32 m0, s49
	s_nop 0
	buffer_load_dwordx4 v132, s[12:15], s73 offen lds
	s_waitcnt vmcnt(8)
	s_waitcnt lgkmcnt(0)
	s_setprio 1
	v_mfma_f32_16x16x32_bf16 v[62:65], v[140:143], v[176:179], v[62:65]
	s_barrier
	v_mfma_f32_16x16x32_bf16 v[62:65], v[148:151], v[180:183], v[62:65]
	v_mfma_f32_16x16x32_bf16 v[46:49], v[140:143], v[184:187], v[46:49]
	v_mfma_f32_16x16x32_bf16 v[46:49], v[148:151], v[188:191], v[46:49]
	v_mfma_f32_16x16x32_bf16 v[30:33], v[140:143], v[192:195], v[30:33]
	v_mfma_f32_16x16x32_bf16 v[30:33], v[148:151], v[196:199], v[30:33]
	v_mfma_f32_16x16x32_bf16 v[14:17], v[140:143], v[200:203], v[14:17]
	v_mfma_f32_16x16x32_bf16 v[14:17], v[148:151], v[204:207], v[14:17]
	v_mfma_f32_16x16x32_bf16 v[10:13], v[152:155], v[200:203], v[10:13]
	v_mfma_f32_16x16x32_bf16 v[10:13], v[156:159], v[204:207], v[10:13]
	v_mfma_f32_16x16x32_bf16 v[26:29], v[152:155], v[192:195], v[26:29]
	v_mfma_f32_16x16x32_bf16 v[26:29], v[156:159], v[196:199], v[26:29]
	v_mfma_f32_16x16x32_bf16 v[42:45], v[152:155], v[184:187], v[42:45]
	v_mfma_f32_16x16x32_bf16 v[42:45], v[156:159], v[188:191], v[42:45]
	v_mfma_f32_16x16x32_bf16 v[58:61], v[152:155], v[176:179], v[58:61]
	v_mfma_f32_16x16x32_bf16 v[58:61], v[156:159], v[180:183], v[58:61]
	v_mfma_f32_16x16x32_bf16 v[54:57], v[160:163], v[176:179], v[54:57]
	v_mfma_f32_16x16x32_bf16 v[54:57], v[164:167], v[180:183], v[54:57]
	v_mfma_f32_16x16x32_bf16 v[38:41], v[160:163], v[184:187], v[38:41]
	v_mfma_f32_16x16x32_bf16 v[38:41], v[164:167], v[188:191], v[38:41]
	v_mfma_f32_16x16x32_bf16 v[22:25], v[160:163], v[192:195], v[22:25]
	v_mfma_f32_16x16x32_bf16 v[22:25], v[164:167], v[196:199], v[22:25]
	v_mfma_f32_16x16x32_bf16 v[6:9], v[160:163], v[200:203], v[6:9]
	v_mfma_f32_16x16x32_bf16 v[6:9], v[164:167], v[204:207], v[6:9]
	v_mfma_f32_16x16x32_bf16 v[2:5], v[168:171], v[200:203], v[2:5]
	v_mfma_f32_16x16x32_bf16 v[2:5], v[172:175], v[204:207], v[2:5]
	v_mfma_f32_16x16x32_bf16 v[18:21], v[168:171], v[192:195], v[18:21]
	v_mfma_f32_16x16x32_bf16 v[18:21], v[172:175], v[196:199], v[18:21]
	v_mfma_f32_16x16x32_bf16 v[34:37], v[168:171], v[184:187], v[34:37]
	v_mfma_f32_16x16x32_bf16 v[34:37], v[172:175], v[188:191], v[34:37]
	v_mfma_f32_16x16x32_bf16 v[50:53], v[168:171], v[176:179], v[50:53]
	v_mfma_f32_16x16x32_bf16 v[50:53], v[172:175], v[180:183], v[50:53]
	s_setprio 0
	s_barrier
	s_add_i32 s72, s72, 2
	s_addk_i32 s70, 0x100
	s_addk_i32 s71, 0x100
	s_cmp_ge_i32 s72, s21
	s_cbranch_scc0 .LBB0_1035

.LBB0_1050:
	ds_read_b128 v[132:135], v142
	ds_read_b128 v[136:139], v142 offset:1024
	ds_read_b128 v[148:151], v142 offset:2048
	ds_read_b128 v[152:155], v142 offset:3072
	ds_read_b128 v[156:159], v143
	ds_read_b128 v[160:163], v143 offset:1024
	ds_read_b128 v[164:167], v143 offset:2048
	ds_read_b128 v[168:171], v143 offset:3072
	s_add_i32 s18, s61, 0xfff40080
	s_cmp_eq_u32 s54, s62
	s_cselect_b32 s64, s35, s18
	s_add_i32 s63, s64, 0x80
	s_add_i32 s18, s61, 0xfffc0000
	s_mov_b32 m0, s55
	ds_read_b128 v[172:175], v144
	ds_read_b128 v[176:179], v144 offset:1024
	ds_read_b128 v[180:183], v144 offset:2048
	ds_read_b128 v[184:187], v144 offset:3072
	ds_read_b128 v[188:191], v144 offset:4096
	ds_read_b128 v[192:195], v144 offset:5120
	ds_read_b128 v[196:199], v144 offset:6144
	ds_read_b128 v[200:203], v144 offset:7168
	buffer_load_dwordx4 v140, s[12:15], s18 offen lds
	s_mov_b32 m0, s56
	s_nop 0
	buffer_load_dwordx4 v140, s[12:15], s61 offen lds
	s_waitcnt vmcnt(8)
	s_waitcnt lgkmcnt(0)
	s_setprio 1
	v_mfma_f32_16x16x32_bf16 v[126:129], v[132:135], v[172:175], v[126:129]
	s_barrier
	v_mfma_f32_16x16x32_bf16 v[126:129], v[136:139], v[176:179], v[126:129]
	v_mfma_f32_16x16x32_bf16 v[110:113], v[132:135], v[180:183], v[110:113]
	v_mfma_f32_16x16x32_bf16 v[110:113], v[136:139], v[184:187], v[110:113]
	v_mfma_f32_16x16x32_bf16 v[94:97], v[132:135], v[188:191], v[94:97]
	v_mfma_f32_16x16x32_bf16 v[94:97], v[136:139], v[192:195], v[94:97]
	v_mfma_f32_16x16x32_bf16 v[78:81], v[132:135], v[196:199], v[78:81]
	v_mfma_f32_16x16x32_bf16 v[78:81], v[136:139], v[200:203], v[78:81]
	v_mfma_f32_16x16x32_bf16 v[74:77], v[148:151], v[196:199], v[74:77]
	v_mfma_f32_16x16x32_bf16 v[74:77], v[152:155], v[200:203], v[74:77]
	v_mfma_f32_16x16x32_bf16 v[90:93], v[148:151], v[188:191], v[90:93]
	v_mfma_f32_16x16x32_bf16 v[90:93], v[152:155], v[192:195], v[90:93]
	v_mfma_f32_16x16x32_bf16 v[106:109], v[148:151], v[180:183], v[106:109]
	v_mfma_f32_16x16x32_bf16 v[106:109], v[152:155], v[184:187], v[106:109]
	v_mfma_f32_16x16x32_bf16 v[122:125], v[148:151], v[172:175], v[122:125]
	v_mfma_f32_16x16x32_bf16 v[122:125], v[152:155], v[176:179], v[122:125]
	v_mfma_f32_16x16x32_bf16 v[118:121], v[156:159], v[172:175], v[118:121]
	v_mfma_f32_16x16x32_bf16 v[118:121], v[160:163], v[176:179], v[118:121]
	v_mfma_f32_16x16x32_bf16 v[102:105], v[156:159], v[180:183], v[102:105]
	v_mfma_f32_16x16x32_bf16 v[102:105], v[160:163], v[184:187], v[102:105]
	v_mfma_f32_16x16x32_bf16 v[86:89], v[156:159], v[188:191], v[86:89]
	v_mfma_f32_16x16x32_bf16 v[86:89], v[160:163], v[192:195], v[86:89]
	v_mfma_f32_16x16x32_bf16 v[70:73], v[156:159], v[196:199], v[70:73]
	v_mfma_f32_16x16x32_bf16 v[70:73], v[160:163], v[200:203], v[70:73]
	v_mfma_f32_16x16x32_bf16 v[66:69], v[164:167], v[196:199], v[66:69]
	v_mfma_f32_16x16x32_bf16 v[66:69], v[168:171], v[200:203], v[66:69]
	v_mfma_f32_16x16x32_bf16 v[82:85], v[164:167], v[188:191], v[82:85]
	v_mfma_f32_16x16x32_bf16 v[82:85], v[168:171], v[192:195], v[82:85]
	v_mfma_f32_16x16x32_bf16 v[98:101], v[164:167], v[180:183], v[98:101]
	v_mfma_f32_16x16x32_bf16 v[98:101], v[168:171], v[184:187], v[98:101]
	v_mfma_f32_16x16x32_bf16 v[114:117], v[164:167], v[172:175], v[114:117]
	v_mfma_f32_16x16x32_bf16 v[114:117], v[168:171], v[176:179], v[114:117]
	s_setprio 0
	s_barrier
	s_mov_b32 m0, s25
	s_mov_b32 s18, s14
	s_mov_b32 s19, s15
	ds_read_b128 v[172:175], v144 offset:16384
	ds_read_b128 v[176:179], v144 offset:17408
	ds_read_b128 v[180:183], v144 offset:18432
	ds_read_b128 v[184:187], v144 offset:19456
	ds_read_b128 v[188:191], v144 offset:20480
	ds_read_b128 v[192:195], v144 offset:21504
	ds_read_b128 v[196:199], v144 offset:22528
	ds_read_b128 v[200:203], v144 offset:23552
	buffer_load_dwordx4 v141, s[16:19], s64 offen lds
	s_add_i32 s65, s64, 0x40000
	s_mov_b32 m0, s27
	s_add_i32 s66, s64, 0x80000
	buffer_load_dwordx4 v141, s[16:19], s65 offen lds
	s_mov_b32 m0, s30
	s_add_i32 s67, s64, 0xc0000
	buffer_load_dwordx4 v141, s[16:19], s66 offen lds
	s_mov_b32 m0, s31
	s_nop 0
	buffer_load_dwordx4 v141, s[16:19], s67 offen lds
	s_mov_b32 m0, s21
	s_nop 0
	buffer_load_dwordx4 v140, s[12:15], s64 offen lds
	s_mov_b32 m0, s38
	s_nop 0
	buffer_load_dwordx4 v140, s[12:15], s65 offen lds
	s_waitcnt vmcnt(8)
	s_waitcnt lgkmcnt(0)
	s_setprio 1
	v_mfma_f32_16x16x32_bf16 v[62:65], v[132:135], v[172:175], v[62:65]
	s_barrier
	v_mfma_f32_16x16x32_bf16 v[62:65], v[136:139], v[176:179], v[62:65]
	v_mfma_f32_16x16x32_bf16 v[46:49], v[132:135], v[180:183], v[46:49]
	v_mfma_f32_16x16x32_bf16 v[46:49], v[136:139], v[184:187], v[46:49]
	v_mfma_f32_16x16x32_bf16 v[30:33], v[132:135], v[188:191], v[30:33]
	v_mfma_f32_16x16x32_bf16 v[30:33], v[136:139], v[192:195], v[30:33]
	v_mfma_f32_16x16x32_bf16 v[14:17], v[132:135], v[196:199], v[14:17]
	v_mfma_f32_16x16x32_bf16 v[14:17], v[136:139], v[200:203], v[14:17]
	v_mfma_f32_16x16x32_bf16 v[10:13], v[148:151], v[196:199], v[10:13]
	v_mfma_f32_16x16x32_bf16 v[10:13], v[152:155], v[200:203], v[10:13]
	v_mfma_f32_16x16x32_bf16 v[26:29], v[148:151], v[188:191], v[26:29]
	v_mfma_f32_16x16x32_bf16 v[26:29], v[152:155], v[192:195], v[26:29]
	v_mfma_f32_16x16x32_bf16 v[42:45], v[148:151], v[180:183], v[42:45]
	v_mfma_f32_16x16x32_bf16 v[42:45], v[152:155], v[184:187], v[42:45]
	v_mfma_f32_16x16x32_bf16 v[58:61], v[148:151], v[172:175], v[58:61]
	v_mfma_f32_16x16x32_bf16 v[58:61], v[152:155], v[176:179], v[58:61]
	v_mfma_f32_16x16x32_bf16 v[54:57], v[156:159], v[172:175], v[54:57]
	v_mfma_f32_16x16x32_bf16 v[54:57], v[160:163], v[176:179], v[54:57]
	v_mfma_f32_16x16x32_bf16 v[38:41], v[156:159], v[180:183], v[38:41]
	v_mfma_f32_16x16x32_bf16 v[38:41], v[160:163], v[184:187], v[38:41]
	v_mfma_f32_16x16x32_bf16 v[22:25], v[156:159], v[188:191], v[22:25]
	v_mfma_f32_16x16x32_bf16 v[22:25], v[160:163], v[192:195], v[22:25]
	v_mfma_f32_16x16x32_bf16 v[6:9], v[156:159], v[196:199], v[6:9]
	v_mfma_f32_16x16x32_bf16 v[6:9], v[160:163], v[200:203], v[6:9]
	v_mfma_f32_16x16x32_bf16 v[2:5], v[164:167], v[196:199], v[2:5]
	v_mfma_f32_16x16x32_bf16 v[2:5], v[168:171], v[200:203], v[2:5]
	v_mfma_f32_16x16x32_bf16 v[18:21], v[164:167], v[188:191], v[18:21]
	v_mfma_f32_16x16x32_bf16 v[18:21], v[168:171], v[192:195], v[18:21]
	v_mfma_f32_16x16x32_bf16 v[34:37], v[164:167], v[180:183], v[34:37]
	v_mfma_f32_16x16x32_bf16 v[34:37], v[168:171], v[184:187], v[34:37]
	v_mfma_f32_16x16x32_bf16 v[50:53], v[164:167], v[172:175], v[50:53]
	v_mfma_f32_16x16x32_bf16 v[50:53], v[168:171], v[176:179], v[50:53]
	s_setprio 0
	s_barrier
	ds_read_b128 v[132:135], v145
	ds_read_b128 v[136:139], v145 offset:1024
	ds_read_b128 v[148:151], v145 offset:2048
	ds_read_b128 v[152:155], v145 offset:3072
	ds_read_b128 v[156:159], v147
	ds_read_b128 v[160:163], v147 offset:1024
	ds_read_b128 v[164:167], v147 offset:2048
	ds_read_b128 v[168:171], v147 offset:3072
	s_mov_b32 m0, s39
	ds_read_b128 v[172:175], v144 offset:32768
	ds_read_b128 v[176:179], v144 offset:33792
	ds_read_b128 v[180:183], v144 offset:34816
	ds_read_b128 v[184:187], v144 offset:35840
	ds_read_b128 v[188:191], v144 offset:36864
	ds_read_b128 v[192:195], v144 offset:37888
	ds_read_b128 v[196:199], v144 offset:38912
	ds_read_b128 v[200:203], v144 offset:39936
	buffer_load_dwordx4 v140, s[12:15], s66 offen lds
	s_mov_b32 m0, s40
	s_nop 0
	buffer_load_dwordx4 v140, s[12:15], s67 offen lds
	s_waitcnt vmcnt(8)
	s_waitcnt lgkmcnt(0)
	s_setprio 1
	v_mfma_f32_16x16x32_bf16 v[126:129], v[132:135], v[172:175], v[126:129]
	s_barrier
	v_mfma_f32_16x16x32_bf16 v[126:129], v[136:139], v[176:179], v[126:129]
	v_mfma_f32_16x16x32_bf16 v[110:113], v[132:135], v[180:183], v[110:113]
	v_mfma_f32_16x16x32_bf16 v[110:113], v[136:139], v[184:187], v[110:113]
	v_mfma_f32_16x16x32_bf16 v[94:97], v[132:135], v[188:191], v[94:97]
	v_mfma_f32_16x16x32_bf16 v[94:97], v[136:139], v[192:195], v[94:97]
	v_mfma_f32_16x16x32_bf16 v[78:81], v[132:135], v[196:199], v[78:81]
	v_mfma_f32_16x16x32_bf16 v[78:81], v[136:139], v[200:203], v[78:81]
	v_mfma_f32_16x16x32_bf16 v[74:77], v[148:151], v[196:199], v[74:77]
	v_mfma_f32_16x16x32_bf16 v[74:77], v[152:155], v[200:203], v[74:77]
	v_mfma_f32_16x16x32_bf16 v[90:93], v[148:151], v[188:191], v[90:93]
	v_mfma_f32_16x16x32_bf16 v[90:93], v[152:155], v[192:195], v[90:93]
	v_mfma_f32_16x16x32_bf16 v[106:109], v[148:151], v[180:183], v[106:109]
	v_mfma_f32_16x16x32_bf16 v[106:109], v[152:155], v[184:187], v[106:109]
	v_mfma_f32_16x16x32_bf16 v[122:125], v[148:151], v[172:175], v[122:125]
	v_mfma_f32_16x16x32_bf16 v[122:125], v[152:155], v[176:179], v[122:125]
	v_mfma_f32_16x16x32_bf16 v[118:121], v[156:159], v[172:175], v[118:121]
	v_mfma_f32_16x16x32_bf16 v[118:121], v[160:163], v[176:179], v[118:121]
	v_mfma_f32_16x16x32_bf16 v[102:105], v[156:159], v[180:183], v[102:105]
	v_mfma_f32_16x16x32_bf16 v[102:105], v[160:163], v[184:187], v[102:105]
	v_mfma_f32_16x16x32_bf16 v[86:89], v[156:159], v[188:191], v[86:89]
	v_mfma_f32_16x16x32_bf16 v[86:89], v[160:163], v[192:195], v[86:89]
	v_mfma_f32_16x16x32_bf16 v[70:73], v[156:159], v[196:199], v[70:73]
	v_mfma_f32_16x16x32_bf16 v[70:73], v[160:163], v[200:203], v[70:73]
	v_mfma_f32_16x16x32_bf16 v[66:69], v[164:167], v[196:199], v[66:69]
	v_mfma_f32_16x16x32_bf16 v[66:69], v[168:171], v[200:203], v[66:69]
	v_mfma_f32_16x16x32_bf16 v[82:85], v[164:167], v[188:191], v[82:85]
	v_mfma_f32_16x16x32_bf16 v[82:85], v[168:171], v[192:195], v[82:85]
	v_mfma_f32_16x16x32_bf16 v[98:101], v[164:167], v[180:183], v[98:101]
	v_mfma_f32_16x16x32_bf16 v[98:101], v[168:171], v[184:187], v[98:101]
	v_mfma_f32_16x16x32_bf16 v[114:117], v[164:167], v[172:175], v[114:117]
	v_mfma_f32_16x16x32_bf16 v[114:117], v[168:171], v[176:179], v[114:117]
	s_setprio 0
	s_barrier
	s_mov_b32 m0, s48
	ds_read_b128 v[172:175], v144 offset:49152
	ds_read_b128 v[176:179], v144 offset:50176
	ds_read_b128 v[180:183], v144 offset:51200
	ds_read_b128 v[184:187], v144 offset:52224
	ds_read_b128 v[188:191], v144 offset:53248
	ds_read_b128 v[192:195], v144 offset:54272
	ds_read_b128 v[196:199], v144 offset:55296
	ds_read_b128 v[200:203], v144 offset:56320
	buffer_load_dwordx4 v141, s[16:19], s63 offen lds
	s_add_i32 s65, s64, 0x40080
	s_mov_b32 m0, s49
	s_add_i32 s66, s64, 0x80080
	buffer_load_dwordx4 v141, s[16:19], s65 offen lds
	s_mov_b32 m0, s52
	s_add_i32 s64, s64, 0xc0080
	buffer_load_dwordx4 v141, s[16:19], s66 offen lds
	s_mov_b32 m0, s53
	s_nop 0
	buffer_load_dwordx4 v141, s[16:19], s64 offen lds
	s_mov_b32 m0, s50
	s_nop 0
	buffer_load_dwordx4 v140, s[12:15], s63 offen lds
	s_mov_b32 m0, s51
	s_nop 0
	buffer_load_dwordx4 v140, s[12:15], s65 offen lds
	s_waitcnt vmcnt(8)
	s_waitcnt lgkmcnt(0)
	s_setprio 1
	v_mfma_f32_16x16x32_bf16 v[62:65], v[132:135], v[172:175], v[62:65]
	s_barrier
	v_mfma_f32_16x16x32_bf16 v[62:65], v[136:139], v[176:179], v[62:65]
	v_mfma_f32_16x16x32_bf16 v[46:49], v[132:135], v[180:183], v[46:49]
	v_mfma_f32_16x16x32_bf16 v[46:49], v[136:139], v[184:187], v[46:49]
	v_mfma_f32_16x16x32_bf16 v[30:33], v[132:135], v[188:191], v[30:33]
	v_mfma_f32_16x16x32_bf16 v[30:33], v[136:139], v[192:195], v[30:33]
	v_mfma_f32_16x16x32_bf16 v[14:17], v[132:135], v[196:199], v[14:17]
	v_mfma_f32_16x16x32_bf16 v[14:17], v[136:139], v[200:203], v[14:17]
	v_mfma_f32_16x16x32_bf16 v[10:13], v[148:151], v[196:199], v[10:13]
	v_mfma_f32_16x16x32_bf16 v[10:13], v[152:155], v[200:203], v[10:13]
	v_mfma_f32_16x16x32_bf16 v[26:29], v[148:151], v[188:191], v[26:29]
	v_mfma_f32_16x16x32_bf16 v[26:29], v[152:155], v[192:195], v[26:29]
	v_mfma_f32_16x16x32_bf16 v[42:45], v[148:151], v[180:183], v[42:45]
	v_mfma_f32_16x16x32_bf16 v[42:45], v[152:155], v[184:187], v[42:45]
	v_mfma_f32_16x16x32_bf16 v[58:61], v[148:151], v[172:175], v[58:61]
	v_mfma_f32_16x16x32_bf16 v[58:61], v[152:155], v[176:179], v[58:61]
	v_mfma_f32_16x16x32_bf16 v[54:57], v[156:159], v[172:175], v[54:57]
	v_mfma_f32_16x16x32_bf16 v[54:57], v[160:163], v[176:179], v[54:57]
	v_mfma_f32_16x16x32_bf16 v[38:41], v[156:159], v[180:183], v[38:41]
	v_mfma_f32_16x16x32_bf16 v[38:41], v[160:163], v[184:187], v[38:41]
	v_mfma_f32_16x16x32_bf16 v[22:25], v[156:159], v[188:191], v[22:25]
	v_mfma_f32_16x16x32_bf16 v[22:25], v[160:163], v[192:195], v[22:25]
	v_mfma_f32_16x16x32_bf16 v[6:9], v[156:159], v[196:199], v[6:9]
	v_mfma_f32_16x16x32_bf16 v[6:9], v[160:163], v[200:203], v[6:9]
	v_mfma_f32_16x16x32_bf16 v[2:5], v[164:167], v[196:199], v[2:5]
	v_mfma_f32_16x16x32_bf16 v[2:5], v[168:171], v[200:203], v[2:5]
	v_mfma_f32_16x16x32_bf16 v[18:21], v[164:167], v[188:191], v[18:21]
	v_mfma_f32_16x16x32_bf16 v[18:21], v[168:171], v[192:195], v[18:21]
	v_mfma_f32_16x16x32_bf16 v[34:37], v[164:167], v[180:183], v[34:37]
	v_mfma_f32_16x16x32_bf16 v[34:37], v[168:171], v[184:187], v[34:37]
	v_mfma_f32_16x16x32_bf16 v[50:53], v[164:167], v[172:175], v[50:53]
	v_mfma_f32_16x16x32_bf16 v[50:53], v[168:171], v[176:179], v[50:53]
	s_setprio 0
	s_barrier
	s_add_i32 s62, s62, 2
	s_addk_i32 s61, 0x100
	s_cmp_ge_i32 s62, s3
	s_cbranch_scc0 .LBB0_1050

.LBB0_1181:
	v_add_u32_e32 v2, 0x10000, v232
	ds_read_b128 v[134:137], v2
	ds_read_b128 v[138:141], v2 offset:1024
	ds_read_b128 v[142:145], v2 offset:2048
	ds_read_b128 v[146:149], v2 offset:3072
	v_add_u32_e32 v2, 0x14000, v232
	ds_read_b128 v[150:153], v2
	ds_read_b128 v[154:157], v2 offset:1024
	ds_read_b128 v[158:161], v2 offset:2048
	ds_read_b128 v[162:165], v2 offset:3072
	s_add_i32 s50, s47, s90
	s_and_b64 s[18:19], exec, s[18:19]
	s_cselect_b32 s51, s88, s50
	s_add_i32 s50, s92, 0x80
	s_or_b32 s52, s51, 0x80
	s_add_i32 s18, s89, s93
	s_add_i32 s94, s94, 0x1bfffc80
	s_cmp_lt_u32 s91, 8
	s_cselect_b32 s18, s18, s94
	s_mov_b32 m0, s74
	s_add_i32 s19, s18, 0x80000
	ds_read_b128 v[166:169], v233
	ds_read_b128 v[170:173], v233 offset:1024
	ds_read_b128 v[174:177], v233 offset:2048
	ds_read_b128 v[178:181], v233 offset:3072
	ds_read_b128 v[182:185], v233 offset:4096
	ds_read_b128 v[186:189], v233 offset:5120
	ds_read_b128 v[190:193], v233 offset:6144
	ds_read_b128 v[194:197], v233 offset:7168
	buffer_load_dwordx4 v230, s[12:15], s19 offen lds
	s_add_i32 s18, s18, 0xc0000
	s_mov_b32 m0, s75
	s_nop 0
	buffer_load_dwordx4 v230, s[12:15], s18 offen lds
	s_waitcnt vmcnt(8)
	s_waitcnt lgkmcnt(0)
	s_setprio 1
	v_mfma_f32_16x16x32_bf16 v[130:133], v[134:137], v[166:169], v[130:133]
	s_barrier
	v_mfma_f32_16x16x32_bf16 v[130:133], v[138:141], v[170:173], v[130:133]
	v_mfma_f32_16x16x32_bf16 v[114:117], v[134:137], v[174:177], v[114:117]
	v_mfma_f32_16x16x32_bf16 v[114:117], v[138:141], v[178:181], v[114:117]
	v_mfma_f32_16x16x32_bf16 v[98:101], v[134:137], v[182:185], v[98:101]
	v_mfma_f32_16x16x32_bf16 v[98:101], v[138:141], v[186:189], v[98:101]
	v_mfma_f32_16x16x32_bf16 v[82:85], v[134:137], v[190:193], v[82:85]
	v_mfma_f32_16x16x32_bf16 v[82:85], v[138:141], v[194:197], v[82:85]
	v_mfma_f32_16x16x32_bf16 v[78:81], v[142:145], v[190:193], v[78:81]
	v_mfma_f32_16x16x32_bf16 v[78:81], v[146:149], v[194:197], v[78:81]
	v_mfma_f32_16x16x32_bf16 v[94:97], v[142:145], v[182:185], v[94:97]
	v_mfma_f32_16x16x32_bf16 v[94:97], v[146:149], v[186:189], v[94:97]
	v_mfma_f32_16x16x32_bf16 v[110:113], v[142:145], v[174:177], v[110:113]
	v_mfma_f32_16x16x32_bf16 v[110:113], v[146:149], v[178:181], v[110:113]
	v_mfma_f32_16x16x32_bf16 v[126:129], v[142:145], v[166:169], v[126:129]
	v_mfma_f32_16x16x32_bf16 v[126:129], v[146:149], v[170:173], v[126:129]
	v_mfma_f32_16x16x32_bf16 v[122:125], v[150:153], v[166:169], v[122:125]
	v_mfma_f32_16x16x32_bf16 v[122:125], v[154:157], v[170:173], v[122:125]
	v_mfma_f32_16x16x32_bf16 v[106:109], v[150:153], v[174:177], v[106:109]
	v_mfma_f32_16x16x32_bf16 v[106:109], v[154:157], v[178:181], v[106:109]
	v_mfma_f32_16x16x32_bf16 v[90:93], v[150:153], v[182:185], v[90:93]
	v_mfma_f32_16x16x32_bf16 v[90:93], v[154:157], v[186:189], v[90:93]
	v_mfma_f32_16x16x32_bf16 v[74:77], v[150:153], v[190:193], v[74:77]
	v_mfma_f32_16x16x32_bf16 v[74:77], v[154:157], v[194:197], v[74:77]
	v_mfma_f32_16x16x32_bf16 v[70:73], v[158:161], v[190:193], v[70:73]
	v_mfma_f32_16x16x32_bf16 v[70:73], v[162:165], v[194:197], v[70:73]
	v_mfma_f32_16x16x32_bf16 v[86:89], v[158:161], v[182:185], v[86:89]
	v_mfma_f32_16x16x32_bf16 v[86:89], v[162:165], v[186:189], v[86:89]
	v_mfma_f32_16x16x32_bf16 v[102:105], v[158:161], v[174:177], v[102:105]
	v_mfma_f32_16x16x32_bf16 v[102:105], v[162:165], v[178:181], v[102:105]
	v_mfma_f32_16x16x32_bf16 v[118:121], v[158:161], v[166:169], v[118:121]
	v_mfma_f32_16x16x32_bf16 v[118:121], v[162:165], v[170:173], v[118:121]
	s_setprio 0
	s_barrier
	s_mov_b32 m0, s27
	s_mov_b32 s18, s14
	s_mov_b32 s19, s15
	ds_read_b128 v[166:169], v233 offset:16384
	ds_read_b128 v[170:173], v233 offset:17408
	ds_read_b128 v[174:177], v233 offset:18432
	ds_read_b128 v[178:181], v233 offset:19456
	ds_read_b128 v[182:185], v233 offset:20480
	ds_read_b128 v[186:189], v233 offset:21504
	ds_read_b128 v[190:193], v233 offset:22528
	ds_read_b128 v[194:197], v233 offset:23552
	buffer_load_dwordx4 v231, s[16:19], s51 offen lds
	s_add_i32 s53, s51, 0x18000
	s_mov_b32 m0, s30
	s_nop 0
	buffer_load_dwordx4 v231, s[16:19], s53 offen lds
	s_add_i32 s53, s51, 0x30000
	s_mov_b32 m0, s31
	s_nop 0
	buffer_load_dwordx4 v231, s[16:19], s53 offen lds
	s_add_i32 s53, s51, 0x48000
	s_mov_b32 m0, s54
	s_nop 0
	buffer_load_dwordx4 v231, s[16:19], s53 offen lds
	s_mov_b32 m0, s25
	s_add_i32 s53, s92, 0x40000
	buffer_load_dwordx4 v230, s[12:15], s92 offen lds
	s_mov_b32 m0, s55
	s_nop 0
	buffer_load_dwordx4 v230, s[12:15], s53 offen lds
	s_waitcnt vmcnt(8)
	s_waitcnt lgkmcnt(0)
	s_setprio 1
	v_mfma_f32_16x16x32_bf16 v[66:69], v[134:137], v[166:169], v[66:69]
	s_barrier
	v_mfma_f32_16x16x32_bf16 v[62:65], v[142:145], v[166:169], v[62:65]
	v_mfma_f32_16x16x32_bf16 v[50:53], v[134:137], v[174:177], v[50:53]
	v_mfma_f32_16x16x32_bf16 v[46:49], v[142:145], v[174:177], v[46:49]
	v_mfma_f32_16x16x32_bf16 v[34:37], v[134:137], v[182:185], v[34:37]
	v_mfma_f32_16x16x32_bf16 v[30:33], v[142:145], v[182:185], v[30:33]
	v_mfma_f32_16x16x32_bf16 v[18:21], v[134:137], v[190:193], v[18:21]
	v_mfma_f32_16x16x32_bf16 v[14:17], v[142:145], v[190:193], v[14:17]
	v_mfma_f32_16x16x32_bf16 v[58:61], v[150:153], v[166:169], v[58:61]
	v_mfma_f32_16x16x32_bf16 v[54:57], v[158:161], v[166:169], v[54:57]
	v_mfma_f32_16x16x32_bf16 v[42:45], v[150:153], v[174:177], v[42:45]
	v_mfma_f32_16x16x32_bf16 v[38:41], v[158:161], v[174:177], v[38:41]
	v_mfma_f32_16x16x32_bf16 v[26:29], v[150:153], v[182:185], v[26:29]
	v_mfma_f32_16x16x32_bf16 v[22:25], v[158:161], v[182:185], v[22:25]
	v_mfma_f32_16x16x32_bf16 v[10:13], v[150:153], v[190:193], v[10:13]
	v_mfma_f32_16x16x32_bf16 v[4:7], v[158:161], v[190:193], v[6:9]
	v_mfma_f32_16x16x32_bf16 v[66:69], v[138:141], v[170:173], v[66:69]
	v_mfma_f32_16x16x32_bf16 v[62:65], v[146:149], v[170:173], v[62:65]
	v_mfma_f32_16x16x32_bf16 v[50:53], v[138:141], v[178:181], v[50:53]
	v_mfma_f32_16x16x32_bf16 v[46:49], v[146:149], v[178:181], v[46:49]
	v_mfma_f32_16x16x32_bf16 v[34:37], v[138:141], v[186:189], v[34:37]
	v_mfma_f32_16x16x32_bf16 v[30:33], v[146:149], v[186:189], v[30:33]
	v_mfma_f32_16x16x32_bf16 v[18:21], v[138:141], v[194:197], v[18:21]
	v_mfma_f32_16x16x32_bf16 v[14:17], v[146:149], v[194:197], v[14:17]
	v_mfma_f32_16x16x32_bf16 v[58:61], v[154:157], v[170:173], v[58:61]
	v_mfma_f32_16x16x32_bf16 v[54:57], v[162:165], v[170:173], v[54:57]
	v_mfma_f32_16x16x32_bf16 v[42:45], v[154:157], v[178:181], v[42:45]
	v_mfma_f32_16x16x32_bf16 v[38:41], v[162:165], v[178:181], v[38:41]
	v_mfma_f32_16x16x32_bf16 v[26:29], v[154:157], v[186:189], v[26:29]
	v_mfma_f32_16x16x32_bf16 v[22:25], v[162:165], v[186:189], v[22:25]
	v_mfma_f32_16x16x32_bf16 v[10:13], v[154:157], v[194:197], v[10:13]
	v_mfma_f32_16x16x32_bf16 v[4:7], v[162:165], v[194:197], v[4:7]
	s_setprio 0
	s_barrier
	v_add_u32_e32 v2, 0x18000, v232
	ds_read_b128 v[134:137], v2
	ds_read_b128 v[138:141], v2 offset:1024
	ds_read_b128 v[142:145], v2 offset:2048
	ds_read_b128 v[146:149], v2 offset:3072
	v_add_u32_e32 v2, 0x1c000, v232
	ds_read_b128 v[150:153], v2
	ds_read_b128 v[154:157], v2 offset:1024
	ds_read_b128 v[158:161], v2 offset:2048
	ds_read_b128 v[162:165], v2 offset:3072
	s_mov_b32 m0, s56
	s_add_i32 s53, s92, 0x80000
	ds_read_b128 v[166:169], v233 offset:32768
	ds_read_b128 v[170:173], v233 offset:33792
	ds_read_b128 v[174:177], v233 offset:34816
	ds_read_b128 v[178:181], v233 offset:35840
	ds_read_b128 v[182:185], v233 offset:36864
	ds_read_b128 v[186:189], v233 offset:37888
	ds_read_b128 v[190:193], v233 offset:38912
	ds_read_b128 v[194:197], v233 offset:39936
	buffer_load_dwordx4 v230, s[12:15], s53 offen lds
	s_add_i32 s53, s92, 0xc0000
	s_mov_b32 m0, s57
	s_nop 0
	buffer_load_dwordx4 v230, s[12:15], s53 offen lds
	s_waitcnt vmcnt(8)
	s_waitcnt lgkmcnt(0)
	s_setprio 1
	v_mfma_f32_16x16x32_bf16 v[130:133], v[134:137], v[166:169], v[130:133]
	s_barrier
	v_mfma_f32_16x16x32_bf16 v[130:133], v[138:141], v[170:173], v[130:133]
	v_mfma_f32_16x16x32_bf16 v[114:117], v[134:137], v[174:177], v[114:117]
	v_mfma_f32_16x16x32_bf16 v[114:117], v[138:141], v[178:181], v[114:117]
	v_mfma_f32_16x16x32_bf16 v[98:101], v[134:137], v[182:185], v[98:101]
	v_mfma_f32_16x16x32_bf16 v[98:101], v[138:141], v[186:189], v[98:101]
	v_mfma_f32_16x16x32_bf16 v[82:85], v[134:137], v[190:193], v[82:85]
	v_mfma_f32_16x16x32_bf16 v[82:85], v[138:141], v[194:197], v[82:85]
	v_mfma_f32_16x16x32_bf16 v[78:81], v[142:145], v[190:193], v[78:81]
	v_mfma_f32_16x16x32_bf16 v[78:81], v[146:149], v[194:197], v[78:81]
	v_mfma_f32_16x16x32_bf16 v[94:97], v[142:145], v[182:185], v[94:97]
	v_mfma_f32_16x16x32_bf16 v[94:97], v[146:149], v[186:189], v[94:97]
	v_mfma_f32_16x16x32_bf16 v[110:113], v[142:145], v[174:177], v[110:113]
	v_mfma_f32_16x16x32_bf16 v[110:113], v[146:149], v[178:181], v[110:113]
	v_mfma_f32_16x16x32_bf16 v[126:129], v[142:145], v[166:169], v[126:129]
	v_mfma_f32_16x16x32_bf16 v[126:129], v[146:149], v[170:173], v[126:129]
	v_mfma_f32_16x16x32_bf16 v[122:125], v[150:153], v[166:169], v[122:125]
	v_mfma_f32_16x16x32_bf16 v[122:125], v[154:157], v[170:173], v[122:125]
	v_mfma_f32_16x16x32_bf16 v[106:109], v[150:153], v[174:177], v[106:109]
	v_mfma_f32_16x16x32_bf16 v[106:109], v[154:157], v[178:181], v[106:109]
	v_mfma_f32_16x16x32_bf16 v[90:93], v[150:153], v[182:185], v[90:93]
	v_mfma_f32_16x16x32_bf16 v[90:93], v[154:157], v[186:189], v[90:93]
	v_mfma_f32_16x16x32_bf16 v[74:77], v[150:153], v[190:193], v[74:77]
	v_mfma_f32_16x16x32_bf16 v[74:77], v[154:157], v[194:197], v[74:77]
	v_mfma_f32_16x16x32_bf16 v[70:73], v[158:161], v[190:193], v[70:73]
	v_mfma_f32_16x16x32_bf16 v[70:73], v[162:165], v[194:197], v[70:73]
	v_mfma_f32_16x16x32_bf16 v[86:89], v[158:161], v[182:185], v[86:89]
	v_mfma_f32_16x16x32_bf16 v[86:89], v[162:165], v[186:189], v[86:89]
	v_mfma_f32_16x16x32_bf16 v[102:105], v[158:161], v[174:177], v[102:105]
	v_mfma_f32_16x16x32_bf16 v[102:105], v[162:165], v[178:181], v[102:105]
	v_mfma_f32_16x16x32_bf16 v[118:121], v[158:161], v[166:169], v[118:121]
	v_mfma_f32_16x16x32_bf16 v[118:121], v[162:165], v[170:173], v[118:121]
	s_setprio 0
	s_barrier
	s_mov_b32 m0, s64
	ds_read_b128 v[166:169], v233 offset:49152
	ds_read_b128 v[170:173], v233 offset:50176
	ds_read_b128 v[174:177], v233 offset:51200
	ds_read_b128 v[178:181], v233 offset:52224
	ds_read_b128 v[182:185], v233 offset:53248
	ds_read_b128 v[186:189], v233 offset:54272
	ds_read_b128 v[190:193], v233 offset:55296
	ds_read_b128 v[194:197], v233 offset:56320
	buffer_load_dwordx4 v231, s[16:19], s52 offen lds
	s_add_i32 s52, s51, 0x18080
	s_mov_b32 m0, s65
	s_nop 0
	buffer_load_dwordx4 v231, s[16:19], s52 offen lds
	s_add_i32 s52, s51, 0x30080
	s_mov_b32 m0, s68
	s_add_i32 s51, s51, 0x48080
	buffer_load_dwordx4 v231, s[16:19], s52 offen lds
	s_mov_b32 m0, s69
	s_nop 0
	buffer_load_dwordx4 v231, s[16:19], s51 offen lds
	s_mov_b32 m0, s66
	s_add_i32 s18, s92, 0x40080
	buffer_load_dwordx4 v230, s[12:15], s50 offen lds
	s_mov_b32 m0, s67
	s_nop 0
	buffer_load_dwordx4 v230, s[12:15], s18 offen lds
	s_waitcnt vmcnt(8)
	s_waitcnt lgkmcnt(0)
	s_setprio 1
	v_mfma_f32_16x16x32_bf16 v[66:69], v[134:137], v[166:169], v[66:69]
	s_barrier
	v_mfma_f32_16x16x32_bf16 v[62:65], v[142:145], v[166:169], v[62:65]
	v_mfma_f32_16x16x32_bf16 v[50:53], v[134:137], v[174:177], v[50:53]
	v_mfma_f32_16x16x32_bf16 v[46:49], v[142:145], v[174:177], v[46:49]
	v_mfma_f32_16x16x32_bf16 v[34:37], v[134:137], v[182:185], v[34:37]
	v_mfma_f32_16x16x32_bf16 v[30:33], v[142:145], v[182:185], v[30:33]
	v_mfma_f32_16x16x32_bf16 v[18:21], v[134:137], v[190:193], v[18:21]
	v_mfma_f32_16x16x32_bf16 v[14:17], v[142:145], v[190:193], v[14:17]
	v_mfma_f32_16x16x32_bf16 v[58:61], v[150:153], v[166:169], v[58:61]
	v_mfma_f32_16x16x32_bf16 v[54:57], v[158:161], v[166:169], v[54:57]
	v_mfma_f32_16x16x32_bf16 v[42:45], v[150:153], v[174:177], v[42:45]
	v_mfma_f32_16x16x32_bf16 v[38:41], v[158:161], v[174:177], v[38:41]
	v_mfma_f32_16x16x32_bf16 v[26:29], v[150:153], v[182:185], v[26:29]
	v_mfma_f32_16x16x32_bf16 v[22:25], v[158:161], v[182:185], v[22:25]
	v_mfma_f32_16x16x32_bf16 v[8:11], v[150:153], v[190:193], v[10:13]
	v_mfma_f32_16x16x32_bf16 v[4:7], v[158:161], v[190:193], v[4:7]
	v_mfma_f32_16x16x32_bf16 v[66:69], v[138:141], v[170:173], v[66:69]
	v_mfma_f32_16x16x32_bf16 v[62:65], v[146:149], v[170:173], v[62:65]
	v_mfma_f32_16x16x32_bf16 v[50:53], v[138:141], v[178:181], v[50:53]
	v_mfma_f32_16x16x32_bf16 v[46:49], v[146:149], v[178:181], v[46:49]
	v_mfma_f32_16x16x32_bf16 v[34:37], v[138:141], v[186:189], v[34:37]
	v_mfma_f32_16x16x32_bf16 v[30:33], v[146:149], v[186:189], v[30:33]
	v_mfma_f32_16x16x32_bf16 v[18:21], v[138:141], v[194:197], v[18:21]
	v_mfma_f32_16x16x32_bf16 v[14:17], v[146:149], v[194:197], v[14:17]
	v_mfma_f32_16x16x32_bf16 v[58:61], v[154:157], v[170:173], v[58:61]
	v_mfma_f32_16x16x32_bf16 v[54:57], v[162:165], v[170:173], v[54:57]
	v_mfma_f32_16x16x32_bf16 v[42:45], v[154:157], v[178:181], v[42:45]
	v_mfma_f32_16x16x32_bf16 v[38:41], v[162:165], v[178:181], v[38:41]
	v_mfma_f32_16x16x32_bf16 v[26:29], v[154:157], v[186:189], v[26:29]
	v_mfma_f32_16x16x32_bf16 v[22:25], v[162:165], v[186:189], v[22:25]
	v_mfma_f32_16x16x32_bf16 v[10:13], v[154:157], v[194:197], v[8:11]
	v_mfma_f32_16x16x32_bf16 v[6:9], v[162:165], v[194:197], v[4:7]
	s_setprio 0
	s_barrier
	s_add_i32 s91, s91, 2
	s_addk_i32 s90, 0x100
	s_cmp_ge_i32 s91, s3
	s_cbranch_scc1 .LBB0_1193

.LBB0_1290:
	ds_read_b128 v[106:109], v224
	ds_read_b128 v[118:121], v224 offset:1024
	ds_read_b128 v[130:133], v224 offset:2048
	ds_read_b128 v[138:141], v224 offset:3072
	ds_read_b128 v[146:149], v225
	ds_read_b128 v[150:153], v225 offset:1024
	ds_read_b128 v[154:157], v225 offset:2048
	ds_read_b128 v[158:161], v225 offset:3072
	s_add_i32 s18, s72, 0xffe80080
	s_cmp_eq_u32 s56, s74
	s_cselect_b32 s75, s6, s18
	s_cselect_b32 s77, s7, s73
	s_or_b32 s76, s75, 0x80
	s_add_i32 s18, s72, 0xfff80000
	s_mov_b32 m0, s57
	ds_read_b128 v[162:165], v226
	ds_read_b128 v[166:169], v226 offset:1024
	ds_read_b128 v[170:173], v226 offset:2048
	ds_read_b128 v[174:177], v226 offset:3072
	ds_read_b128 v[178:181], v226 offset:4096
	ds_read_b128 v[182:185], v226 offset:5120
	ds_read_b128 v[190:193], v226 offset:6144
	ds_read_b128 v[194:197], v226 offset:7168
	buffer_load_dwordx4 v222, s[12:15], s18 offen lds
	s_mov_b32 m0, s60
	s_nop 0
	buffer_load_dwordx4 v222, s[12:15], s72 offen lds
	s_waitcnt vmcnt(8)
	s_waitcnt lgkmcnt(0)
	s_setprio 1
	v_mfma_f32_16x16x32_bf16 v[142:145], v[106:109], v[162:165], v[142:145]
	s_barrier
	v_mfma_f32_16x16x32_bf16 v[142:145], v[118:121], v[166:169], v[142:145]
	v_mfma_f32_16x16x32_bf16 v[114:117], v[106:109], v[170:173], v[114:117]
	v_mfma_f32_16x16x32_bf16 v[114:117], v[118:121], v[174:177], v[114:117]
	v_mfma_f32_16x16x32_bf16 v[94:97], v[106:109], v[178:181], v[94:97]
	v_mfma_f32_16x16x32_bf16 v[94:97], v[118:121], v[182:185], v[94:97]
	v_mfma_f32_16x16x32_bf16 v[78:81], v[106:109], v[190:193], v[78:81]
	v_mfma_f32_16x16x32_bf16 v[78:81], v[118:121], v[194:197], v[78:81]
	v_mfma_f32_16x16x32_bf16 v[74:77], v[130:133], v[190:193], v[74:77]
	v_mfma_f32_16x16x32_bf16 v[74:77], v[138:141], v[194:197], v[74:77]
	v_mfma_f32_16x16x32_bf16 v[90:93], v[130:133], v[178:181], v[90:93]
	v_mfma_f32_16x16x32_bf16 v[90:93], v[138:141], v[182:185], v[90:93]
	v_mfma_f32_16x16x32_bf16 v[110:113], v[130:133], v[170:173], v[110:113]
	v_mfma_f32_16x16x32_bf16 v[110:113], v[138:141], v[174:177], v[110:113]
	v_mfma_f32_16x16x32_bf16 v[134:137], v[130:133], v[162:165], v[134:137]
	v_mfma_f32_16x16x32_bf16 v[134:137], v[138:141], v[166:169], v[134:137]
	v_mfma_f32_16x16x32_bf16 v[126:129], v[146:149], v[162:165], v[126:129]
	v_mfma_f32_16x16x32_bf16 v[126:129], v[150:153], v[166:169], v[126:129]
	v_mfma_f32_16x16x32_bf16 v[102:105], v[146:149], v[170:173], v[102:105]
	v_mfma_f32_16x16x32_bf16 v[102:105], v[150:153], v[174:177], v[102:105]
	v_mfma_f32_16x16x32_bf16 v[86:89], v[146:149], v[178:181], v[86:89]
	v_mfma_f32_16x16x32_bf16 v[86:89], v[150:153], v[182:185], v[86:89]
	v_mfma_f32_16x16x32_bf16 v[70:73], v[146:149], v[190:193], v[70:73]
	v_mfma_f32_16x16x32_bf16 v[70:73], v[150:153], v[194:197], v[70:73]
	v_mfma_f32_16x16x32_bf16 v[66:69], v[154:157], v[190:193], v[66:69]
	v_mfma_f32_16x16x32_bf16 v[66:69], v[158:161], v[194:197], v[66:69]
	v_mfma_f32_16x16x32_bf16 v[82:85], v[154:157], v[178:181], v[82:85]
	v_mfma_f32_16x16x32_bf16 v[82:85], v[158:161], v[182:185], v[82:85]
	v_mfma_f32_16x16x32_bf16 v[98:101], v[154:157], v[170:173], v[98:101]
	v_mfma_f32_16x16x32_bf16 v[98:101], v[158:161], v[174:177], v[98:101]
	v_mfma_f32_16x16x32_bf16 v[122:125], v[154:157], v[162:165], v[122:125]
	v_mfma_f32_16x16x32_bf16 v[122:125], v[158:161], v[166:169], v[122:125]
	s_setprio 0
	s_barrier
	s_mov_b32 m0, s27
	s_mov_b32 s18, s14
	s_mov_b32 s19, s15
	ds_read_b128 v[162:165], v226 offset:16384
	ds_read_b128 v[166:169], v226 offset:17408
	ds_read_b128 v[170:173], v226 offset:18432
	ds_read_b128 v[174:177], v226 offset:19456
	ds_read_b128 v[178:181], v226 offset:20480
	ds_read_b128 v[182:185], v226 offset:21504
	ds_read_b128 v[190:193], v226 offset:22528
	ds_read_b128 v[194:197], v226 offset:23552
	buffer_load_dwordx4 v223, s[16:19], s77 offen lds
	s_add_i32 s78, s77, 0x80000
	s_mov_b32 m0, s30
	s_nop 0
	buffer_load_dwordx4 v223, s[16:19], s78 offen lds
	s_add_i32 s78, s77, 0x100000
	s_mov_b32 m0, s31
	s_nop 0
	buffer_load_dwordx4 v223, s[16:19], s78 offen lds
	s_add_i32 s78, s77, 0x180000
	s_mov_b32 m0, s41
	s_nop 0
	buffer_load_dwordx4 v223, s[16:19], s78 offen lds
	s_mov_b32 m0, s25
	s_add_i32 s78, s75, 0x80000
	buffer_load_dwordx4 v222, s[12:15], s75 offen lds
	s_mov_b32 m0, s42
	s_nop 0
	buffer_load_dwordx4 v222, s[12:15], s78 offen lds
	s_waitcnt vmcnt(8)
	s_waitcnt lgkmcnt(0)
	s_setprio 1
	v_mfma_f32_16x16x32_bf16 v[62:65], v[106:109], v[162:165], v[62:65]
	s_barrier
	v_mfma_f32_16x16x32_bf16 v[62:65], v[118:121], v[166:169], v[62:65]
	v_mfma_f32_16x16x32_bf16 v[46:49], v[106:109], v[170:173], v[46:49]
	v_mfma_f32_16x16x32_bf16 v[46:49], v[118:121], v[174:177], v[46:49]
	v_mfma_f32_16x16x32_bf16 v[30:33], v[106:109], v[178:181], v[30:33]
	v_mfma_f32_16x16x32_bf16 v[30:33], v[118:121], v[182:185], v[30:33]
	v_mfma_f32_16x16x32_bf16 v[14:17], v[106:109], v[190:193], v[14:17]
	v_mfma_f32_16x16x32_bf16 v[14:17], v[118:121], v[194:197], v[14:17]
	v_mfma_f32_16x16x32_bf16 v[10:13], v[130:133], v[190:193], v[10:13]
	v_mfma_f32_16x16x32_bf16 v[10:13], v[138:141], v[194:197], v[10:13]
	v_mfma_f32_16x16x32_bf16 v[26:29], v[130:133], v[178:181], v[26:29]
	v_mfma_f32_16x16x32_bf16 v[26:29], v[138:141], v[182:185], v[26:29]
	v_mfma_f32_16x16x32_bf16 v[42:45], v[130:133], v[170:173], v[42:45]
	v_mfma_f32_16x16x32_bf16 v[42:45], v[138:141], v[174:177], v[42:45]
	v_mfma_f32_16x16x32_bf16 v[58:61], v[130:133], v[162:165], v[58:61]
	v_mfma_f32_16x16x32_bf16 v[58:61], v[138:141], v[166:169], v[58:61]
	v_mfma_f32_16x16x32_bf16 v[54:57], v[146:149], v[162:165], v[54:57]
	v_mfma_f32_16x16x32_bf16 v[54:57], v[150:153], v[166:169], v[54:57]
	v_mfma_f32_16x16x32_bf16 v[38:41], v[146:149], v[170:173], v[38:41]
	v_mfma_f32_16x16x32_bf16 v[38:41], v[150:153], v[174:177], v[38:41]
	v_mfma_f32_16x16x32_bf16 v[22:25], v[146:149], v[178:181], v[22:25]
	v_mfma_f32_16x16x32_bf16 v[22:25], v[150:153], v[182:185], v[22:25]
	v_mfma_f32_16x16x32_bf16 v[6:9], v[146:149], v[190:193], v[6:9]
	v_mfma_f32_16x16x32_bf16 v[6:9], v[150:153], v[194:197], v[6:9]
	v_mfma_f32_16x16x32_bf16 v[2:5], v[154:157], v[190:193], v[2:5]
	v_mfma_f32_16x16x32_bf16 v[2:5], v[158:161], v[194:197], v[2:5]
	v_mfma_f32_16x16x32_bf16 v[18:21], v[154:157], v[178:181], v[18:21]
	v_mfma_f32_16x16x32_bf16 v[18:21], v[158:161], v[182:185], v[18:21]
	v_mfma_f32_16x16x32_bf16 v[34:37], v[154:157], v[170:173], v[34:37]
	v_mfma_f32_16x16x32_bf16 v[34:37], v[158:161], v[174:177], v[34:37]
	v_mfma_f32_16x16x32_bf16 v[50:53], v[154:157], v[162:165], v[50:53]
	v_mfma_f32_16x16x32_bf16 v[50:53], v[158:161], v[166:169], v[50:53]
	s_setprio 0
	s_barrier
	ds_read_b128 v[106:109], v227
	ds_read_b128 v[118:121], v227 offset:1024
	ds_read_b128 v[130:133], v227 offset:2048
	ds_read_b128 v[138:141], v227 offset:3072
	ds_read_b128 v[146:149], v228
	ds_read_b128 v[150:153], v228 offset:1024
	ds_read_b128 v[154:157], v228 offset:2048
	ds_read_b128 v[158:161], v228 offset:3072
	s_mov_b32 m0, s43
	s_add_i32 s78, s75, 0x100000
	ds_read_b128 v[162:165], v226 offset:32768
	ds_read_b128 v[166:169], v226 offset:33792
	ds_read_b128 v[170:173], v226 offset:34816
	ds_read_b128 v[174:177], v226 offset:35840
	ds_read_b128 v[178:181], v226 offset:36864
	ds_read_b128 v[182:185], v226 offset:37888
	ds_read_b128 v[190:193], v226 offset:38912
	ds_read_b128 v[194:197], v226 offset:39936
	buffer_load_dwordx4 v222, s[12:15], s78 offen lds
	s_add_i32 s78, s75, 0x180000
	s_mov_b32 m0, s44
	s_nop 0
	buffer_load_dwordx4 v222, s[12:15], s78 offen lds
	s_waitcnt vmcnt(8)
	s_waitcnt lgkmcnt(0)
	s_setprio 1
	v_mfma_f32_16x16x32_bf16 v[142:145], v[106:109], v[162:165], v[142:145]
	s_barrier
	v_mfma_f32_16x16x32_bf16 v[142:145], v[118:121], v[166:169], v[142:145]
	v_mfma_f32_16x16x32_bf16 v[114:117], v[106:109], v[170:173], v[114:117]
	v_mfma_f32_16x16x32_bf16 v[114:117], v[118:121], v[174:177], v[114:117]
	v_mfma_f32_16x16x32_bf16 v[94:97], v[106:109], v[178:181], v[94:97]
	v_mfma_f32_16x16x32_bf16 v[94:97], v[118:121], v[182:185], v[94:97]
	v_mfma_f32_16x16x32_bf16 v[78:81], v[106:109], v[190:193], v[78:81]
	v_mfma_f32_16x16x32_bf16 v[78:81], v[118:121], v[194:197], v[78:81]
	v_mfma_f32_16x16x32_bf16 v[74:77], v[130:133], v[190:193], v[74:77]
	v_mfma_f32_16x16x32_bf16 v[74:77], v[138:141], v[194:197], v[74:77]
	v_mfma_f32_16x16x32_bf16 v[90:93], v[130:133], v[178:181], v[90:93]
	v_mfma_f32_16x16x32_bf16 v[90:93], v[138:141], v[182:185], v[90:93]
	v_mfma_f32_16x16x32_bf16 v[110:113], v[130:133], v[170:173], v[110:113]
	v_mfma_f32_16x16x32_bf16 v[110:113], v[138:141], v[174:177], v[110:113]
	v_mfma_f32_16x16x32_bf16 v[134:137], v[130:133], v[162:165], v[134:137]
	v_mfma_f32_16x16x32_bf16 v[134:137], v[138:141], v[166:169], v[134:137]
	v_mfma_f32_16x16x32_bf16 v[126:129], v[146:149], v[162:165], v[126:129]
	v_mfma_f32_16x16x32_bf16 v[126:129], v[150:153], v[166:169], v[126:129]
	v_mfma_f32_16x16x32_bf16 v[102:105], v[146:149], v[170:173], v[102:105]
	v_mfma_f32_16x16x32_bf16 v[102:105], v[150:153], v[174:177], v[102:105]
	v_mfma_f32_16x16x32_bf16 v[86:89], v[146:149], v[178:181], v[86:89]
	v_mfma_f32_16x16x32_bf16 v[86:89], v[150:153], v[182:185], v[86:89]
	v_mfma_f32_16x16x32_bf16 v[70:73], v[146:149], v[190:193], v[70:73]
	v_mfma_f32_16x16x32_bf16 v[70:73], v[150:153], v[194:197], v[70:73]
	v_mfma_f32_16x16x32_bf16 v[66:69], v[154:157], v[190:193], v[66:69]
	v_mfma_f32_16x16x32_bf16 v[66:69], v[158:161], v[194:197], v[66:69]
	v_mfma_f32_16x16x32_bf16 v[82:85], v[154:157], v[178:181], v[82:85]
	v_mfma_f32_16x16x32_bf16 v[82:85], v[158:161], v[182:185], v[82:85]
	v_mfma_f32_16x16x32_bf16 v[98:101], v[154:157], v[170:173], v[98:101]
	v_mfma_f32_16x16x32_bf16 v[98:101], v[158:161], v[174:177], v[98:101]
	v_mfma_f32_16x16x32_bf16 v[122:125], v[154:157], v[162:165], v[122:125]
	v_mfma_f32_16x16x32_bf16 v[122:125], v[158:161], v[166:169], v[122:125]
	s_setprio 0
	s_barrier
	s_mov_b32 m0, s48
	s_or_b32 s78, s77, 0x80
	ds_read_b128 v[162:165], v226 offset:49152
	ds_read_b128 v[166:169], v226 offset:50176
	ds_read_b128 v[170:173], v226 offset:51200
	ds_read_b128 v[174:177], v226 offset:52224
	ds_read_b128 v[178:181], v226 offset:53248
	ds_read_b128 v[182:185], v226 offset:54272
	ds_read_b128 v[190:193], v226 offset:55296
	ds_read_b128 v[194:197], v226 offset:56320
	buffer_load_dwordx4 v223, s[16:19], s78 offen lds
	s_add_i32 s78, s77, 0x80080
	s_mov_b32 m0, s49
	s_add_i32 s75, s75, 0x80080
	buffer_load_dwordx4 v223, s[16:19], s78 offen lds
	s_add_i32 s78, s77, 0x100080
	s_mov_b32 m0, s52
	s_add_i32 s77, s77, 0x180080
	buffer_load_dwordx4 v223, s[16:19], s78 offen lds
	s_mov_b32 m0, s53
	s_nop 0
	buffer_load_dwordx4 v223, s[16:19], s77 offen lds
	s_mov_b32 m0, s50
	s_nop 0
	buffer_load_dwordx4 v222, s[12:15], s76 offen lds
	s_mov_b32 m0, s51
	s_nop 0
	buffer_load_dwordx4 v222, s[12:15], s75 offen lds
	s_waitcnt vmcnt(8)
	s_waitcnt lgkmcnt(0)
	s_setprio 1
	v_mfma_f32_16x16x32_bf16 v[62:65], v[106:109], v[162:165], v[62:65]
	s_barrier
	v_mfma_f32_16x16x32_bf16 v[62:65], v[118:121], v[166:169], v[62:65]
	v_mfma_f32_16x16x32_bf16 v[46:49], v[106:109], v[170:173], v[46:49]
	v_mfma_f32_16x16x32_bf16 v[46:49], v[118:121], v[174:177], v[46:49]
	v_mfma_f32_16x16x32_bf16 v[30:33], v[106:109], v[178:181], v[30:33]
	v_mfma_f32_16x16x32_bf16 v[30:33], v[118:121], v[182:185], v[30:33]
	v_mfma_f32_16x16x32_bf16 v[14:17], v[106:109], v[190:193], v[14:17]
	v_mfma_f32_16x16x32_bf16 v[14:17], v[118:121], v[194:197], v[14:17]
	v_mfma_f32_16x16x32_bf16 v[10:13], v[130:133], v[190:193], v[10:13]
	v_mfma_f32_16x16x32_bf16 v[10:13], v[138:141], v[194:197], v[10:13]
	v_mfma_f32_16x16x32_bf16 v[26:29], v[130:133], v[178:181], v[26:29]
	v_mfma_f32_16x16x32_bf16 v[26:29], v[138:141], v[182:185], v[26:29]
	v_mfma_f32_16x16x32_bf16 v[42:45], v[130:133], v[170:173], v[42:45]
	v_mfma_f32_16x16x32_bf16 v[42:45], v[138:141], v[174:177], v[42:45]
	v_mfma_f32_16x16x32_bf16 v[58:61], v[130:133], v[162:165], v[58:61]
	v_mfma_f32_16x16x32_bf16 v[58:61], v[138:141], v[166:169], v[58:61]
	v_mfma_f32_16x16x32_bf16 v[54:57], v[146:149], v[162:165], v[54:57]
	v_mfma_f32_16x16x32_bf16 v[54:57], v[150:153], v[166:169], v[54:57]
	v_mfma_f32_16x16x32_bf16 v[38:41], v[146:149], v[170:173], v[38:41]
	v_mfma_f32_16x16x32_bf16 v[38:41], v[150:153], v[174:177], v[38:41]
	v_mfma_f32_16x16x32_bf16 v[22:25], v[146:149], v[178:181], v[22:25]
	v_mfma_f32_16x16x32_bf16 v[22:25], v[150:153], v[182:185], v[22:25]
	v_mfma_f32_16x16x32_bf16 v[6:9], v[146:149], v[190:193], v[6:9]
	v_mfma_f32_16x16x32_bf16 v[6:9], v[150:153], v[194:197], v[6:9]
	v_mfma_f32_16x16x32_bf16 v[2:5], v[154:157], v[190:193], v[2:5]
	v_mfma_f32_16x16x32_bf16 v[2:5], v[158:161], v[194:197], v[2:5]
	v_mfma_f32_16x16x32_bf16 v[18:21], v[154:157], v[178:181], v[18:21]
	v_mfma_f32_16x16x32_bf16 v[18:21], v[158:161], v[182:185], v[18:21]
	v_mfma_f32_16x16x32_bf16 v[34:37], v[154:157], v[170:173], v[34:37]
	v_mfma_f32_16x16x32_bf16 v[34:37], v[158:161], v[174:177], v[34:37]
	v_mfma_f32_16x16x32_bf16 v[50:53], v[154:157], v[162:165], v[50:53]
	v_mfma_f32_16x16x32_bf16 v[50:53], v[158:161], v[166:169], v[50:53]
	s_setprio 0
	s_barrier
	s_add_i32 s74, s74, 2
	s_addk_i32 s72, 0x100
	s_addk_i32 s73, 0x100
	s_cmp_ge_i32 s74, s3
	s_cbranch_scc0 .LBB0_1290
	s_and_b64 vcc, exec, s[38:39]
	s_cbranch_vccz .LBB0_1293

.LBB0_1382:
	ds_read_b128 v[144:147], v138
	ds_read_b128 v[148:151], v138 offset:1024
	ds_read_b128 v[152:155], v138 offset:2048
	ds_read_b128 v[156:159], v138 offset:3072
	ds_read_b128 v[160:163], v139
	ds_read_b128 v[164:167], v139 offset:1024
	ds_read_b128 v[168:171], v139 offset:2048
	ds_read_b128 v[172:175], v139 offset:3072
	s_add_i32 s14, s74, 0xffe80080
	s_cmp_eq_u32 s61, s76
	s_cselect_b32 s77, s72, s14
	s_cselect_b32 s79, s73, s75
	s_or_b32 s78, s77, 0x80
	s_add_i32 s14, s74, 0xfff80000
	s_mov_b32 m0, s62
	ds_read_b128 v[176:179], v140
	ds_read_b128 v[180:183], v140 offset:1024
	ds_read_b128 v[184:187], v140 offset:2048
	ds_read_b128 v[188:191], v140 offset:3072
	ds_read_b128 v[192:195], v140 offset:4096
	ds_read_b128 v[196:199], v140 offset:5120
	ds_read_b128 v[200:203], v140 offset:6144
	ds_read_b128 v[204:207], v140 offset:7168
	buffer_load_dwordx4 v136, s[16:19], s14 offen lds
	s_mov_b32 m0, s63
	s_nop 0
	buffer_load_dwordx4 v136, s[16:19], s74 offen lds
	s_waitcnt vmcnt(8)
	s_waitcnt lgkmcnt(0)
	s_setprio 1
	v_mfma_f32_16x16x32_bf16 v[118:121], v[144:147], v[176:179], v[118:121]
	s_barrier
	v_mfma_f32_16x16x32_bf16 v[118:121], v[148:151], v[180:183], v[118:121]
	v_mfma_f32_16x16x32_bf16 v[110:113], v[144:147], v[184:187], v[110:113]
	v_mfma_f32_16x16x32_bf16 v[110:113], v[148:151], v[188:191], v[110:113]
	v_mfma_f32_16x16x32_bf16 v[94:97], v[144:147], v[192:195], v[94:97]
	v_mfma_f32_16x16x32_bf16 v[94:97], v[148:151], v[196:199], v[94:97]
	v_mfma_f32_16x16x32_bf16 v[78:81], v[144:147], v[200:203], v[78:81]
	v_mfma_f32_16x16x32_bf16 v[78:81], v[148:151], v[204:207], v[78:81]
	v_mfma_f32_16x16x32_bf16 v[66:69], v[152:155], v[200:203], v[66:69]
	v_mfma_f32_16x16x32_bf16 v[66:69], v[156:159], v[204:207], v[66:69]
	v_mfma_f32_16x16x32_bf16 v[86:89], v[152:155], v[192:195], v[86:89]
	v_mfma_f32_16x16x32_bf16 v[86:89], v[156:159], v[196:199], v[86:89]
	v_mfma_f32_16x16x32_bf16 v[102:105], v[152:155], v[184:187], v[102:105]
	v_mfma_f32_16x16x32_bf16 v[102:105], v[156:159], v[188:191], v[102:105]
	v_mfma_f32_16x16x32_bf16 v[114:117], v[152:155], v[176:179], v[114:117]
	v_mfma_f32_16x16x32_bf16 v[114:117], v[156:159], v[180:183], v[114:117]
	v_mfma_f32_16x16x32_bf16 v[126:129], v[160:163], v[176:179], v[126:129]
	v_mfma_f32_16x16x32_bf16 v[126:129], v[164:167], v[180:183], v[126:129]
	v_mfma_f32_16x16x32_bf16 v[106:109], v[160:163], v[184:187], v[106:109]
	v_mfma_f32_16x16x32_bf16 v[106:109], v[164:167], v[188:191], v[106:109]
	v_mfma_f32_16x16x32_bf16 v[90:93], v[160:163], v[192:195], v[90:93]
	v_mfma_f32_16x16x32_bf16 v[90:93], v[164:167], v[196:199], v[90:93]
	v_mfma_f32_16x16x32_bf16 v[74:77], v[160:163], v[200:203], v[74:77]
	v_mfma_f32_16x16x32_bf16 v[74:77], v[164:167], v[204:207], v[74:77]
	v_mfma_f32_16x16x32_bf16 v[70:73], v[168:171], v[200:203], v[70:73]
	v_mfma_f32_16x16x32_bf16 v[70:73], v[172:175], v[204:207], v[70:73]
	v_mfma_f32_16x16x32_bf16 v[82:85], v[168:171], v[192:195], v[82:85]
	v_mfma_f32_16x16x32_bf16 v[82:85], v[172:175], v[196:199], v[82:85]
	v_mfma_f32_16x16x32_bf16 v[98:101], v[168:171], v[184:187], v[98:101]
	v_mfma_f32_16x16x32_bf16 v[98:101], v[172:175], v[188:191], v[98:101]
	v_mfma_f32_16x16x32_bf16 v[122:125], v[168:171], v[176:179], v[122:125]
	v_mfma_f32_16x16x32_bf16 v[122:125], v[172:175], v[180:183], v[122:125]
	s_setprio 0
	s_barrier
	s_mov_b32 m0, s45
	s_mov_b32 s14, s18
	s_mov_b32 s15, s19
	ds_read_b128 v[176:179], v140 offset:16384
	ds_read_b128 v[180:183], v140 offset:17408
	ds_read_b128 v[184:187], v140 offset:18432
	ds_read_b128 v[188:191], v140 offset:19456
	ds_read_b128 v[192:195], v140 offset:20480
	ds_read_b128 v[196:199], v140 offset:21504
	ds_read_b128 v[200:203], v140 offset:22528
	ds_read_b128 v[204:207], v140 offset:23552
	buffer_load_dwordx4 v137, s[12:15], s79 offen lds
	s_add_i32 s80, s79, 0x80000
	s_mov_b32 m0, s46
	s_nop 0
	buffer_load_dwordx4 v137, s[12:15], s80 offen lds
	s_add_i32 s80, s79, 0x100000
	s_mov_b32 m0, s47
	s_nop 0
	buffer_load_dwordx4 v137, s[12:15], s80 offen lds
	s_add_i32 s80, s79, 0x180000
	s_mov_b32 m0, s48
	s_nop 0
	buffer_load_dwordx4 v137, s[12:15], s80 offen lds
	s_mov_b32 m0, s44
	s_add_i32 s80, s77, 0x80000
	buffer_load_dwordx4 v136, s[16:19], s77 offen lds
	s_mov_b32 m0, s49
	s_nop 0
	buffer_load_dwordx4 v136, s[16:19], s80 offen lds
	s_waitcnt vmcnt(8)
	s_waitcnt lgkmcnt(0)
	s_setprio 1
	v_mfma_f32_16x16x32_bf16 v[62:65], v[144:147], v[176:179], v[62:65]
	s_barrier
	v_mfma_f32_16x16x32_bf16 v[62:65], v[148:151], v[180:183], v[62:65]
	v_mfma_f32_16x16x32_bf16 v[46:49], v[144:147], v[184:187], v[46:49]
	v_mfma_f32_16x16x32_bf16 v[46:49], v[148:151], v[188:191], v[46:49]
	v_mfma_f32_16x16x32_bf16 v[30:33], v[144:147], v[192:195], v[30:33]
	v_mfma_f32_16x16x32_bf16 v[30:33], v[148:151], v[196:199], v[30:33]
	v_mfma_f32_16x16x32_bf16 v[14:17], v[144:147], v[200:203], v[14:17]
	v_mfma_f32_16x16x32_bf16 v[14:17], v[148:151], v[204:207], v[14:17]
	v_mfma_f32_16x16x32_bf16 v[6:9], v[152:155], v[200:203], v[6:9]
	v_mfma_f32_16x16x32_bf16 v[6:9], v[156:159], v[204:207], v[6:9]
	v_mfma_f32_16x16x32_bf16 v[22:25], v[152:155], v[192:195], v[22:25]
	v_mfma_f32_16x16x32_bf16 v[22:25], v[156:159], v[196:199], v[22:25]
	v_mfma_f32_16x16x32_bf16 v[38:41], v[152:155], v[184:187], v[38:41]
	v_mfma_f32_16x16x32_bf16 v[38:41], v[156:159], v[188:191], v[38:41]
	v_mfma_f32_16x16x32_bf16 v[54:57], v[152:155], v[176:179], v[54:57]
	v_mfma_f32_16x16x32_bf16 v[54:57], v[156:159], v[180:183], v[54:57]
	v_mfma_f32_16x16x32_bf16 v[58:61], v[160:163], v[176:179], v[58:61]
	v_mfma_f32_16x16x32_bf16 v[58:61], v[164:167], v[180:183], v[58:61]
	v_mfma_f32_16x16x32_bf16 v[42:45], v[160:163], v[184:187], v[42:45]
	v_mfma_f32_16x16x32_bf16 v[42:45], v[164:167], v[188:191], v[42:45]
	v_mfma_f32_16x16x32_bf16 v[26:29], v[160:163], v[192:195], v[26:29]
	v_mfma_f32_16x16x32_bf16 v[26:29], v[164:167], v[196:199], v[26:29]
	v_mfma_f32_16x16x32_bf16 v[10:13], v[160:163], v[200:203], v[10:13]
	v_mfma_f32_16x16x32_bf16 v[10:13], v[164:167], v[204:207], v[10:13]
	v_mfma_f32_16x16x32_bf16 v[2:5], v[168:171], v[200:203], v[2:5]
	v_mfma_f32_16x16x32_bf16 v[2:5], v[172:175], v[204:207], v[2:5]
	v_mfma_f32_16x16x32_bf16 v[18:21], v[168:171], v[192:195], v[18:21]
	v_mfma_f32_16x16x32_bf16 v[18:21], v[172:175], v[196:199], v[18:21]
	v_mfma_f32_16x16x32_bf16 v[34:37], v[168:171], v[184:187], v[34:37]
	v_mfma_f32_16x16x32_bf16 v[34:37], v[172:175], v[188:191], v[34:37]
	v_mfma_f32_16x16x32_bf16 v[50:53], v[168:171], v[176:179], v[50:53]
	v_mfma_f32_16x16x32_bf16 v[50:53], v[172:175], v[180:183], v[50:53]
	s_setprio 0
	s_barrier
	ds_read_b128 v[144:147], v141
	ds_read_b128 v[148:151], v141 offset:1024
	ds_read_b128 v[152:155], v141 offset:2048
	ds_read_b128 v[156:159], v141 offset:3072
	ds_read_b128 v[160:163], v142
	ds_read_b128 v[164:167], v142 offset:1024
	ds_read_b128 v[168:171], v142 offset:2048
	ds_read_b128 v[172:175], v142 offset:3072
	s_mov_b32 m0, s50
	s_add_i32 s80, s77, 0x100000
	ds_read_b128 v[176:179], v140 offset:32768
	ds_read_b128 v[180:183], v140 offset:33792
	ds_read_b128 v[184:187], v140 offset:34816
	ds_read_b128 v[188:191], v140 offset:35840
	ds_read_b128 v[192:195], v140 offset:36864
	ds_read_b128 v[196:199], v140 offset:37888
	ds_read_b128 v[200:203], v140 offset:38912
	ds_read_b128 v[204:207], v140 offset:39936
	buffer_load_dwordx4 v136, s[16:19], s80 offen lds
	s_add_i32 s80, s77, 0x180000
	s_mov_b32 m0, s51
	s_nop 0
	buffer_load_dwordx4 v136, s[16:19], s80 offen lds
	s_waitcnt vmcnt(8)
	s_waitcnt lgkmcnt(0)
	s_setprio 1
	v_mfma_f32_16x16x32_bf16 v[118:121], v[144:147], v[176:179], v[118:121]
	s_barrier
	v_mfma_f32_16x16x32_bf16 v[118:121], v[148:151], v[180:183], v[118:121]
	v_mfma_f32_16x16x32_bf16 v[110:113], v[144:147], v[184:187], v[110:113]
	v_mfma_f32_16x16x32_bf16 v[110:113], v[148:151], v[188:191], v[110:113]
	v_mfma_f32_16x16x32_bf16 v[94:97], v[144:147], v[192:195], v[94:97]
	v_mfma_f32_16x16x32_bf16 v[94:97], v[148:151], v[196:199], v[94:97]
	v_mfma_f32_16x16x32_bf16 v[78:81], v[144:147], v[200:203], v[78:81]
	v_mfma_f32_16x16x32_bf16 v[78:81], v[148:151], v[204:207], v[78:81]
	v_mfma_f32_16x16x32_bf16 v[66:69], v[152:155], v[200:203], v[66:69]
	v_mfma_f32_16x16x32_bf16 v[66:69], v[156:159], v[204:207], v[66:69]
	v_mfma_f32_16x16x32_bf16 v[86:89], v[152:155], v[192:195], v[86:89]
	v_mfma_f32_16x16x32_bf16 v[86:89], v[156:159], v[196:199], v[86:89]
	v_mfma_f32_16x16x32_bf16 v[102:105], v[152:155], v[184:187], v[102:105]
	v_mfma_f32_16x16x32_bf16 v[102:105], v[156:159], v[188:191], v[102:105]
	v_mfma_f32_16x16x32_bf16 v[114:117], v[152:155], v[176:179], v[114:117]
	v_mfma_f32_16x16x32_bf16 v[114:117], v[156:159], v[180:183], v[114:117]
	v_mfma_f32_16x16x32_bf16 v[126:129], v[160:163], v[176:179], v[126:129]
	v_mfma_f32_16x16x32_bf16 v[126:129], v[164:167], v[180:183], v[126:129]
	v_mfma_f32_16x16x32_bf16 v[106:109], v[160:163], v[184:187], v[106:109]
	v_mfma_f32_16x16x32_bf16 v[106:109], v[164:167], v[188:191], v[106:109]
	v_mfma_f32_16x16x32_bf16 v[90:93], v[160:163], v[192:195], v[90:93]
	v_mfma_f32_16x16x32_bf16 v[90:93], v[164:167], v[196:199], v[90:93]
	v_mfma_f32_16x16x32_bf16 v[74:77], v[160:163], v[200:203], v[74:77]
	v_mfma_f32_16x16x32_bf16 v[74:77], v[164:167], v[204:207], v[74:77]
	v_mfma_f32_16x16x32_bf16 v[70:73], v[168:171], v[200:203], v[70:73]
	v_mfma_f32_16x16x32_bf16 v[70:73], v[172:175], v[204:207], v[70:73]
	v_mfma_f32_16x16x32_bf16 v[82:85], v[168:171], v[192:195], v[82:85]
	v_mfma_f32_16x16x32_bf16 v[82:85], v[172:175], v[196:199], v[82:85]
	v_mfma_f32_16x16x32_bf16 v[98:101], v[168:171], v[184:187], v[98:101]
	v_mfma_f32_16x16x32_bf16 v[98:101], v[172:175], v[188:191], v[98:101]
	v_mfma_f32_16x16x32_bf16 v[122:125], v[168:171], v[176:179], v[122:125]
	v_mfma_f32_16x16x32_bf16 v[122:125], v[172:175], v[180:183], v[122:125]
	s_setprio 0
	s_barrier
	s_mov_b32 m0, s53
	s_or_b32 s80, s79, 0x80
	ds_read_b128 v[176:179], v140 offset:49152
	ds_read_b128 v[180:183], v140 offset:50176
	ds_read_b128 v[184:187], v140 offset:51200
	ds_read_b128 v[188:191], v140 offset:52224
	ds_read_b128 v[192:195], v140 offset:53248
	ds_read_b128 v[196:199], v140 offset:54272
	ds_read_b128 v[200:203], v140 offset:55296
	ds_read_b128 v[204:207], v140 offset:56320
	buffer_load_dwordx4 v137, s[12:15], s80 offen lds
	s_add_i32 s80, s79, 0x80080
	s_mov_b32 m0, s54
	s_add_i32 s77, s77, 0x80080
	buffer_load_dwordx4 v137, s[12:15], s80 offen lds
	s_add_i32 s80, s79, 0x100080
	s_mov_b32 m0, s57
	s_add_i32 s79, s79, 0x180080
	buffer_load_dwordx4 v137, s[12:15], s80 offen lds
	s_mov_b32 m0, s58
	s_nop 0
	buffer_load_dwordx4 v137, s[12:15], s79 offen lds
	s_mov_b32 m0, s55
	s_nop 0
	buffer_load_dwordx4 v136, s[16:19], s78 offen lds
	s_mov_b32 m0, s56
	s_nop 0
	buffer_load_dwordx4 v136, s[16:19], s77 offen lds
	s_waitcnt vmcnt(8)
	s_waitcnt lgkmcnt(0)
	s_setprio 1
	v_mfma_f32_16x16x32_bf16 v[62:65], v[144:147], v[176:179], v[62:65]
	s_barrier
	v_mfma_f32_16x16x32_bf16 v[62:65], v[148:151], v[180:183], v[62:65]
	v_mfma_f32_16x16x32_bf16 v[46:49], v[144:147], v[184:187], v[46:49]
	v_mfma_f32_16x16x32_bf16 v[46:49], v[148:151], v[188:191], v[46:49]
	v_mfma_f32_16x16x32_bf16 v[30:33], v[144:147], v[192:195], v[30:33]
	v_mfma_f32_16x16x32_bf16 v[30:33], v[148:151], v[196:199], v[30:33]
	v_mfma_f32_16x16x32_bf16 v[14:17], v[144:147], v[200:203], v[14:17]
	v_mfma_f32_16x16x32_bf16 v[14:17], v[148:151], v[204:207], v[14:17]
	v_mfma_f32_16x16x32_bf16 v[6:9], v[152:155], v[200:203], v[6:9]
	v_mfma_f32_16x16x32_bf16 v[6:9], v[156:159], v[204:207], v[6:9]
	v_mfma_f32_16x16x32_bf16 v[22:25], v[152:155], v[192:195], v[22:25]
	v_mfma_f32_16x16x32_bf16 v[22:25], v[156:159], v[196:199], v[22:25]
	v_mfma_f32_16x16x32_bf16 v[38:41], v[152:155], v[184:187], v[38:41]
	v_mfma_f32_16x16x32_bf16 v[38:41], v[156:159], v[188:191], v[38:41]
	v_mfma_f32_16x16x32_bf16 v[54:57], v[152:155], v[176:179], v[54:57]
	v_mfma_f32_16x16x32_bf16 v[54:57], v[156:159], v[180:183], v[54:57]
	v_mfma_f32_16x16x32_bf16 v[58:61], v[160:163], v[176:179], v[58:61]
	v_mfma_f32_16x16x32_bf16 v[58:61], v[164:167], v[180:183], v[58:61]
	v_mfma_f32_16x16x32_bf16 v[42:45], v[160:163], v[184:187], v[42:45]
	v_mfma_f32_16x16x32_bf16 v[42:45], v[164:167], v[188:191], v[42:45]
	v_mfma_f32_16x16x32_bf16 v[26:29], v[160:163], v[192:195], v[26:29]
	v_mfma_f32_16x16x32_bf16 v[26:29], v[164:167], v[196:199], v[26:29]
	v_mfma_f32_16x16x32_bf16 v[10:13], v[160:163], v[200:203], v[10:13]
	v_mfma_f32_16x16x32_bf16 v[10:13], v[164:167], v[204:207], v[10:13]
	v_mfma_f32_16x16x32_bf16 v[2:5], v[168:171], v[200:203], v[2:5]
	v_mfma_f32_16x16x32_bf16 v[2:5], v[172:175], v[204:207], v[2:5]
	v_mfma_f32_16x16x32_bf16 v[18:21], v[168:171], v[192:195], v[18:21]
	v_mfma_f32_16x16x32_bf16 v[18:21], v[172:175], v[196:199], v[18:21]
	v_mfma_f32_16x16x32_bf16 v[34:37], v[168:171], v[184:187], v[34:37]
	v_mfma_f32_16x16x32_bf16 v[34:37], v[172:175], v[188:191], v[34:37]
	v_mfma_f32_16x16x32_bf16 v[50:53], v[168:171], v[176:179], v[50:53]
	v_mfma_f32_16x16x32_bf16 v[50:53], v[172:175], v[180:183], v[50:53]
	s_setprio 0
	s_barrier
	s_add_i32 s76, s76, 2
	s_addk_i32 s74, 0x100
	s_addk_i32 s75, 0x100
	s_cmp_ge_i32 s76, s27
	s_cbranch_scc0 .LBB0_1382
	s_and_b64 vcc, exec, s[42:43]
	s_cbranch_vccz .LBB0_1385

.LBB0_1402:
	ds_read_b128 v[146:149], v138
	ds_read_b128 v[150:153], v138 offset:1024
	ds_read_b128 v[154:157], v138 offset:2048
	ds_read_b128 v[158:161], v138 offset:3072
	ds_read_b128 v[162:165], v139
	ds_read_b128 v[166:169], v139 offset:1024
	ds_read_b128 v[170:173], v139 offset:2048
	ds_read_b128 v[174:177], v139 offset:3072
	s_add_i32 s22, s75, 0xffe80080
	s_cmp_eq_u32 s62, s77
	s_cselect_b32 s78, s73, s22
	s_cselect_b32 s80, s74, s76
	s_or_b32 s79, s78, 0x80
	s_add_i32 s22, s75, 0xfff80000
	s_mov_b32 m0, s63
	ds_read_b128 v[178:181], v140
	ds_read_b128 v[182:185], v140 offset:1024
	ds_read_b128 v[186:189], v140 offset:2048
	ds_read_b128 v[190:193], v140 offset:3072
	ds_read_b128 v[194:197], v140 offset:4096
	ds_read_b128 v[198:201], v140 offset:5120
	ds_read_b128 v[202:205], v140 offset:6144
	ds_read_b128 v[206:209], v140 offset:7168
	buffer_load_dwordx4 v136, s[16:19], s22 offen lds
	s_mov_b32 m0, s64
	s_nop 0
	buffer_load_dwordx4 v136, s[16:19], s75 offen lds
	s_waitcnt vmcnt(8)
	s_waitcnt lgkmcnt(0)
	s_setprio 1
	v_mfma_f32_16x16x32_bf16 v[118:121], v[146:149], v[178:181], v[118:121]
	s_barrier
	v_mfma_f32_16x16x32_bf16 v[118:121], v[150:153], v[182:185], v[118:121]
	v_mfma_f32_16x16x32_bf16 v[110:113], v[146:149], v[186:189], v[110:113]
	v_mfma_f32_16x16x32_bf16 v[110:113], v[150:153], v[190:193], v[110:113]
	v_mfma_f32_16x16x32_bf16 v[94:97], v[146:149], v[194:197], v[94:97]
	v_mfma_f32_16x16x32_bf16 v[94:97], v[150:153], v[198:201], v[94:97]
	v_mfma_f32_16x16x32_bf16 v[78:81], v[146:149], v[202:205], v[78:81]
	v_mfma_f32_16x16x32_bf16 v[78:81], v[150:153], v[206:209], v[78:81]
	v_mfma_f32_16x16x32_bf16 v[66:69], v[154:157], v[202:205], v[66:69]
	v_mfma_f32_16x16x32_bf16 v[66:69], v[158:161], v[206:209], v[66:69]
	v_mfma_f32_16x16x32_bf16 v[86:89], v[154:157], v[194:197], v[86:89]
	v_mfma_f32_16x16x32_bf16 v[86:89], v[158:161], v[198:201], v[86:89]
	v_mfma_f32_16x16x32_bf16 v[102:105], v[154:157], v[186:189], v[102:105]
	v_mfma_f32_16x16x32_bf16 v[102:105], v[158:161], v[190:193], v[102:105]
	v_mfma_f32_16x16x32_bf16 v[114:117], v[154:157], v[178:181], v[114:117]
	v_mfma_f32_16x16x32_bf16 v[114:117], v[158:161], v[182:185], v[114:117]
	v_mfma_f32_16x16x32_bf16 v[126:129], v[162:165], v[178:181], v[126:129]
	v_mfma_f32_16x16x32_bf16 v[126:129], v[166:169], v[182:185], v[126:129]
	v_mfma_f32_16x16x32_bf16 v[106:109], v[162:165], v[186:189], v[106:109]
	v_mfma_f32_16x16x32_bf16 v[106:109], v[166:169], v[190:193], v[106:109]
	v_mfma_f32_16x16x32_bf16 v[90:93], v[162:165], v[194:197], v[90:93]
	v_mfma_f32_16x16x32_bf16 v[90:93], v[166:169], v[198:201], v[90:93]
	v_mfma_f32_16x16x32_bf16 v[74:77], v[162:165], v[202:205], v[74:77]
	v_mfma_f32_16x16x32_bf16 v[74:77], v[166:169], v[206:209], v[74:77]
	v_mfma_f32_16x16x32_bf16 v[70:73], v[170:173], v[202:205], v[70:73]
	v_mfma_f32_16x16x32_bf16 v[70:73], v[174:177], v[206:209], v[70:73]
	v_mfma_f32_16x16x32_bf16 v[82:85], v[170:173], v[194:197], v[82:85]
	v_mfma_f32_16x16x32_bf16 v[82:85], v[174:177], v[198:201], v[82:85]
	v_mfma_f32_16x16x32_bf16 v[98:101], v[170:173], v[186:189], v[98:101]
	v_mfma_f32_16x16x32_bf16 v[98:101], v[174:177], v[190:193], v[98:101]
	v_mfma_f32_16x16x32_bf16 v[122:125], v[170:173], v[178:181], v[122:125]
	v_mfma_f32_16x16x32_bf16 v[122:125], v[174:177], v[182:185], v[122:125]
	s_setprio 0
	s_barrier
	s_mov_b32 m0, s31
	s_mov_b32 s22, s18
	s_mov_b32 s23, s19
	ds_read_b128 v[178:181], v140 offset:16384
	ds_read_b128 v[182:185], v140 offset:17408
	ds_read_b128 v[186:189], v140 offset:18432
	ds_read_b128 v[190:193], v140 offset:19456
	ds_read_b128 v[194:197], v140 offset:20480
	ds_read_b128 v[198:201], v140 offset:21504
	ds_read_b128 v[202:205], v140 offset:22528
	ds_read_b128 v[206:209], v140 offset:23552
	buffer_load_dwordx4 v137, s[20:23], s80 offen lds
	s_add_i32 s81, s80, 0x80000
	s_mov_b32 m0, s48
	s_nop 0
	buffer_load_dwordx4 v137, s[20:23], s81 offen lds
	s_add_i32 s81, s80, 0x100000
	s_mov_b32 m0, s49
	s_nop 0
	buffer_load_dwordx4 v137, s[20:23], s81 offen lds
	s_add_i32 s81, s80, 0x180000
	s_mov_b32 m0, s50
	s_nop 0
	buffer_load_dwordx4 v137, s[20:23], s81 offen lds
	s_mov_b32 m0, s30
	s_add_i32 s81, s78, 0x80000
	buffer_load_dwordx4 v136, s[16:19], s78 offen lds
	s_mov_b32 m0, s51
	s_nop 0
	buffer_load_dwordx4 v136, s[16:19], s81 offen lds
	s_waitcnt vmcnt(8)
	s_waitcnt lgkmcnt(0)
	s_setprio 1
	v_mfma_f32_16x16x32_bf16 v[62:65], v[146:149], v[178:181], v[62:65]
	s_barrier
	v_mfma_f32_16x16x32_bf16 v[62:65], v[150:153], v[182:185], v[62:65]
	v_mfma_f32_16x16x32_bf16 v[46:49], v[146:149], v[186:189], v[46:49]
	v_mfma_f32_16x16x32_bf16 v[46:49], v[150:153], v[190:193], v[46:49]
	v_mfma_f32_16x16x32_bf16 v[30:33], v[146:149], v[194:197], v[30:33]
	v_mfma_f32_16x16x32_bf16 v[30:33], v[150:153], v[198:201], v[30:33]
	v_mfma_f32_16x16x32_bf16 v[14:17], v[146:149], v[202:205], v[14:17]
	v_mfma_f32_16x16x32_bf16 v[14:17], v[150:153], v[206:209], v[14:17]
	v_mfma_f32_16x16x32_bf16 v[6:9], v[154:157], v[202:205], v[6:9]
	v_mfma_f32_16x16x32_bf16 v[6:9], v[158:161], v[206:209], v[6:9]
	v_mfma_f32_16x16x32_bf16 v[22:25], v[154:157], v[194:197], v[22:25]
	v_mfma_f32_16x16x32_bf16 v[22:25], v[158:161], v[198:201], v[22:25]
	v_mfma_f32_16x16x32_bf16 v[38:41], v[154:157], v[186:189], v[38:41]
	v_mfma_f32_16x16x32_bf16 v[38:41], v[158:161], v[190:193], v[38:41]
	v_mfma_f32_16x16x32_bf16 v[54:57], v[154:157], v[178:181], v[54:57]
	v_mfma_f32_16x16x32_bf16 v[54:57], v[158:161], v[182:185], v[54:57]
	v_mfma_f32_16x16x32_bf16 v[58:61], v[162:165], v[178:181], v[58:61]
	v_mfma_f32_16x16x32_bf16 v[58:61], v[166:169], v[182:185], v[58:61]
	v_mfma_f32_16x16x32_bf16 v[42:45], v[162:165], v[186:189], v[42:45]
	v_mfma_f32_16x16x32_bf16 v[42:45], v[166:169], v[190:193], v[42:45]
	v_mfma_f32_16x16x32_bf16 v[26:29], v[162:165], v[194:197], v[26:29]
	v_mfma_f32_16x16x32_bf16 v[26:29], v[166:169], v[198:201], v[26:29]
	v_mfma_f32_16x16x32_bf16 v[10:13], v[162:165], v[202:205], v[10:13]
	v_mfma_f32_16x16x32_bf16 v[10:13], v[166:169], v[206:209], v[10:13]
	v_mfma_f32_16x16x32_bf16 v[2:5], v[170:173], v[202:205], v[2:5]
	v_mfma_f32_16x16x32_bf16 v[2:5], v[174:177], v[206:209], v[2:5]
	v_mfma_f32_16x16x32_bf16 v[18:21], v[170:173], v[194:197], v[18:21]
	v_mfma_f32_16x16x32_bf16 v[18:21], v[174:177], v[198:201], v[18:21]
	v_mfma_f32_16x16x32_bf16 v[34:37], v[170:173], v[186:189], v[34:37]
	v_mfma_f32_16x16x32_bf16 v[34:37], v[174:177], v[190:193], v[34:37]
	v_mfma_f32_16x16x32_bf16 v[50:53], v[170:173], v[178:181], v[50:53]
	v_mfma_f32_16x16x32_bf16 v[50:53], v[174:177], v[182:185], v[50:53]
	s_setprio 0
	s_barrier
	ds_read_b128 v[146:149], v141
	ds_read_b128 v[150:153], v141 offset:1024
	ds_read_b128 v[154:157], v141 offset:2048
	ds_read_b128 v[158:161], v141 offset:3072
	ds_read_b128 v[162:165], v142
	ds_read_b128 v[166:169], v142 offset:1024
	ds_read_b128 v[170:173], v142 offset:2048
	ds_read_b128 v[174:177], v142 offset:3072
	s_mov_b32 m0, s52
	s_add_i32 s81, s78, 0x100000
	ds_read_b128 v[178:181], v140 offset:32768
	ds_read_b128 v[182:185], v140 offset:33792
	ds_read_b128 v[186:189], v140 offset:34816
	ds_read_b128 v[190:193], v140 offset:35840
	ds_read_b128 v[194:197], v140 offset:36864
	ds_read_b128 v[198:201], v140 offset:37888
	ds_read_b128 v[202:205], v140 offset:38912
	ds_read_b128 v[206:209], v140 offset:39936
	buffer_load_dwordx4 v136, s[16:19], s81 offen lds
	s_add_i32 s81, s78, 0x180000
	s_mov_b32 m0, s53
	s_nop 0
	buffer_load_dwordx4 v136, s[16:19], s81 offen lds
	s_waitcnt vmcnt(8)
	s_waitcnt lgkmcnt(0)
	s_setprio 1
	v_mfma_f32_16x16x32_bf16 v[118:121], v[146:149], v[178:181], v[118:121]
	s_barrier
	v_mfma_f32_16x16x32_bf16 v[118:121], v[150:153], v[182:185], v[118:121]
	v_mfma_f32_16x16x32_bf16 v[110:113], v[146:149], v[186:189], v[110:113]
	v_mfma_f32_16x16x32_bf16 v[110:113], v[150:153], v[190:193], v[110:113]
	v_mfma_f32_16x16x32_bf16 v[94:97], v[146:149], v[194:197], v[94:97]
	v_mfma_f32_16x16x32_bf16 v[94:97], v[150:153], v[198:201], v[94:97]
	v_mfma_f32_16x16x32_bf16 v[78:81], v[146:149], v[202:205], v[78:81]
	v_mfma_f32_16x16x32_bf16 v[78:81], v[150:153], v[206:209], v[78:81]
	v_mfma_f32_16x16x32_bf16 v[66:69], v[154:157], v[202:205], v[66:69]
	v_mfma_f32_16x16x32_bf16 v[66:69], v[158:161], v[206:209], v[66:69]
	v_mfma_f32_16x16x32_bf16 v[86:89], v[154:157], v[194:197], v[86:89]
	v_mfma_f32_16x16x32_bf16 v[86:89], v[158:161], v[198:201], v[86:89]
	v_mfma_f32_16x16x32_bf16 v[102:105], v[154:157], v[186:189], v[102:105]
	v_mfma_f32_16x16x32_bf16 v[102:105], v[158:161], v[190:193], v[102:105]
	v_mfma_f32_16x16x32_bf16 v[114:117], v[154:157], v[178:181], v[114:117]
	v_mfma_f32_16x16x32_bf16 v[114:117], v[158:161], v[182:185], v[114:117]
	v_mfma_f32_16x16x32_bf16 v[126:129], v[162:165], v[178:181], v[126:129]
	v_mfma_f32_16x16x32_bf16 v[126:129], v[166:169], v[182:185], v[126:129]
	v_mfma_f32_16x16x32_bf16 v[106:109], v[162:165], v[186:189], v[106:109]
	v_mfma_f32_16x16x32_bf16 v[106:109], v[166:169], v[190:193], v[106:109]
	v_mfma_f32_16x16x32_bf16 v[90:93], v[162:165], v[194:197], v[90:93]
	v_mfma_f32_16x16x32_bf16 v[90:93], v[166:169], v[198:201], v[90:93]
	v_mfma_f32_16x16x32_bf16 v[74:77], v[162:165], v[202:205], v[74:77]
	v_mfma_f32_16x16x32_bf16 v[74:77], v[166:169], v[206:209], v[74:77]
	v_mfma_f32_16x16x32_bf16 v[70:73], v[170:173], v[202:205], v[70:73]
	v_mfma_f32_16x16x32_bf16 v[70:73], v[174:177], v[206:209], v[70:73]
	v_mfma_f32_16x16x32_bf16 v[82:85], v[170:173], v[194:197], v[82:85]
	v_mfma_f32_16x16x32_bf16 v[82:85], v[174:177], v[198:201], v[82:85]
	v_mfma_f32_16x16x32_bf16 v[98:101], v[170:173], v[186:189], v[98:101]
	v_mfma_f32_16x16x32_bf16 v[98:101], v[174:177], v[190:193], v[98:101]
	v_mfma_f32_16x16x32_bf16 v[122:125], v[170:173], v[178:181], v[122:125]
	v_mfma_f32_16x16x32_bf16 v[122:125], v[174:177], v[182:185], v[122:125]
	s_setprio 0
	s_barrier
	s_mov_b32 m0, s54
	s_or_b32 s81, s80, 0x80
	ds_read_b128 v[178:181], v140 offset:49152
	ds_read_b128 v[182:185], v140 offset:50176
	ds_read_b128 v[186:189], v140 offset:51200
	ds_read_b128 v[190:193], v140 offset:52224
	ds_read_b128 v[194:197], v140 offset:53248
	ds_read_b128 v[198:201], v140 offset:54272
	ds_read_b128 v[202:205], v140 offset:55296
	ds_read_b128 v[206:209], v140 offset:56320
	buffer_load_dwordx4 v137, s[20:23], s81 offen lds
	s_add_i32 s81, s80, 0x80080
	s_mov_b32 m0, s55
	s_add_i32 s78, s78, 0x80080
	buffer_load_dwordx4 v137, s[20:23], s81 offen lds
	s_add_i32 s81, s80, 0x100080
	s_mov_b32 m0, s58
	s_add_i32 s80, s80, 0x180080
	buffer_load_dwordx4 v137, s[20:23], s81 offen lds
	s_mov_b32 m0, s59
	s_nop 0
	buffer_load_dwordx4 v137, s[20:23], s80 offen lds
	s_mov_b32 m0, s56
	s_nop 0
	buffer_load_dwordx4 v136, s[16:19], s79 offen lds
	s_mov_b32 m0, s57
	s_nop 0
	buffer_load_dwordx4 v136, s[16:19], s78 offen lds
	s_waitcnt vmcnt(8)
	s_waitcnt lgkmcnt(0)
	s_setprio 1
	v_mfma_f32_16x16x32_bf16 v[62:65], v[146:149], v[178:181], v[62:65]
	s_barrier
	v_mfma_f32_16x16x32_bf16 v[62:65], v[150:153], v[182:185], v[62:65]
	v_mfma_f32_16x16x32_bf16 v[46:49], v[146:149], v[186:189], v[46:49]
	v_mfma_f32_16x16x32_bf16 v[46:49], v[150:153], v[190:193], v[46:49]
	v_mfma_f32_16x16x32_bf16 v[30:33], v[146:149], v[194:197], v[30:33]
	v_mfma_f32_16x16x32_bf16 v[30:33], v[150:153], v[198:201], v[30:33]
	v_mfma_f32_16x16x32_bf16 v[14:17], v[146:149], v[202:205], v[14:17]
	v_mfma_f32_16x16x32_bf16 v[14:17], v[150:153], v[206:209], v[14:17]
	v_mfma_f32_16x16x32_bf16 v[6:9], v[154:157], v[202:205], v[6:9]
	v_mfma_f32_16x16x32_bf16 v[6:9], v[158:161], v[206:209], v[6:9]
	v_mfma_f32_16x16x32_bf16 v[22:25], v[154:157], v[194:197], v[22:25]
	v_mfma_f32_16x16x32_bf16 v[22:25], v[158:161], v[198:201], v[22:25]
	v_mfma_f32_16x16x32_bf16 v[38:41], v[154:157], v[186:189], v[38:41]
	v_mfma_f32_16x16x32_bf16 v[38:41], v[158:161], v[190:193], v[38:41]
	v_mfma_f32_16x16x32_bf16 v[54:57], v[154:157], v[178:181], v[54:57]
	v_mfma_f32_16x16x32_bf16 v[54:57], v[158:161], v[182:185], v[54:57]
	v_mfma_f32_16x16x32_bf16 v[58:61], v[162:165], v[178:181], v[58:61]
	v_mfma_f32_16x16x32_bf16 v[58:61], v[166:169], v[182:185], v[58:61]
	v_mfma_f32_16x16x32_bf16 v[42:45], v[162:165], v[186:189], v[42:45]
	v_mfma_f32_16x16x32_bf16 v[42:45], v[166:169], v[190:193], v[42:45]
	v_mfma_f32_16x16x32_bf16 v[26:29], v[162:165], v[194:197], v[26:29]
	v_mfma_f32_16x16x32_bf16 v[26:29], v[166:169], v[198:201], v[26:29]
	v_mfma_f32_16x16x32_bf16 v[10:13], v[162:165], v[202:205], v[10:13]
	v_mfma_f32_16x16x32_bf16 v[10:13], v[166:169], v[206:209], v[10:13]
	v_mfma_f32_16x16x32_bf16 v[2:5], v[170:173], v[202:205], v[2:5]
	v_mfma_f32_16x16x32_bf16 v[2:5], v[174:177], v[206:209], v[2:5]
	v_mfma_f32_16x16x32_bf16 v[18:21], v[170:173], v[194:197], v[18:21]
	v_mfma_f32_16x16x32_bf16 v[18:21], v[174:177], v[198:201], v[18:21]
	v_mfma_f32_16x16x32_bf16 v[34:37], v[170:173], v[186:189], v[34:37]
	v_mfma_f32_16x16x32_bf16 v[34:37], v[174:177], v[190:193], v[34:37]
	v_mfma_f32_16x16x32_bf16 v[50:53], v[170:173], v[178:181], v[50:53]
	v_mfma_f32_16x16x32_bf16 v[50:53], v[174:177], v[182:185], v[50:53]
	s_setprio 0
	s_barrier
	s_add_i32 s77, s77, 2
	s_addk_i32 s75, 0x100
	s_addk_i32 s76, 0x100
	s_cmp_ge_i32 s77, s13
	s_cbranch_scc0 .LBB0_1402
	s_and_b64 vcc, exec, s[46:47]
	s_cbranch_vccz .LBB0_1405

.LBB0_1519:
	ds_read_b128 v[134:137], v208
	ds_read_b128 v[138:141], v208 offset:1024
	ds_read_b128 v[142:145], v208 offset:2048
	ds_read_b128 v[146:149], v208 offset:3072
	ds_read_b128 v[150:153], v209
	ds_read_b128 v[154:157], v209 offset:1024
	ds_read_b128 v[158:161], v209 offset:2048
	ds_read_b128 v[162:165], v209 offset:3072
	s_add_i32 s18, s80, 0xffbf8080
	s_cmp_eq_u32 s65, s82
	s_cselect_b32 s83, s6, s18
	s_cselect_b32 s85, s7, s81
	s_or_b32 s84, s83, 0x80
	s_add_i32 s18, s80, 0xffea8000
	s_mov_b32 m0, s66
	ds_read_b128 v[166:169], v210
	ds_read_b128 v[170:173], v210 offset:1024
	ds_read_b128 v[174:177], v210 offset:2048
	ds_read_b128 v[178:181], v210 offset:3072
	ds_read_b128 v[182:185], v210 offset:4096
	ds_read_b128 v[186:189], v210 offset:5120
	ds_read_b128 v[190:193], v210 offset:6144
	ds_read_b128 v[194:197], v210 offset:7168
	buffer_load_dwordx4 v206, s[12:15], s18 offen lds
	s_mov_b32 m0, s69
	s_nop 0
	buffer_load_dwordx4 v206, s[12:15], s80 offen lds
	s_waitcnt vmcnt(8)
	s_waitcnt lgkmcnt(0)
	s_setprio 1
	v_mfma_f32_16x16x32_bf16 v[126:129], v[134:137], v[166:169], v[126:129]
	s_barrier
	v_mfma_f32_16x16x32_bf16 v[126:129], v[138:141], v[170:173], v[126:129]
	v_mfma_f32_16x16x32_bf16 v[118:121], v[134:137], v[174:177], v[118:121]
	v_mfma_f32_16x16x32_bf16 v[118:121], v[138:141], v[178:181], v[118:121]
	v_mfma_f32_16x16x32_bf16 v[106:109], v[134:137], v[182:185], v[106:109]
	v_mfma_f32_16x16x32_bf16 v[106:109], v[138:141], v[186:189], v[106:109]
	v_mfma_f32_16x16x32_bf16 v[90:93], v[134:137], v[190:193], v[90:93]
	v_mfma_f32_16x16x32_bf16 v[90:93], v[138:141], v[194:197], v[90:93]
	v_mfma_f32_16x16x32_bf16 v[82:85], v[142:145], v[190:193], v[82:85]
	v_mfma_f32_16x16x32_bf16 v[82:85], v[146:149], v[194:197], v[82:85]
	v_mfma_f32_16x16x32_bf16 v[98:101], v[142:145], v[182:185], v[98:101]
	v_mfma_f32_16x16x32_bf16 v[98:101], v[146:149], v[186:189], v[98:101]
	v_mfma_f32_16x16x32_bf16 v[114:117], v[142:145], v[174:177], v[114:117]
	v_mfma_f32_16x16x32_bf16 v[114:117], v[146:149], v[178:181], v[114:117]
	v_mfma_f32_16x16x32_bf16 v[122:125], v[142:145], v[166:169], v[122:125]
	v_mfma_f32_16x16x32_bf16 v[122:125], v[146:149], v[170:173], v[122:125]
	v_mfma_f32_16x16x32_bf16 v[110:113], v[150:153], v[166:169], v[110:113]
	v_mfma_f32_16x16x32_bf16 v[110:113], v[154:157], v[170:173], v[110:113]
	v_mfma_f32_16x16x32_bf16 v[94:97], v[150:153], v[174:177], v[94:97]
	v_mfma_f32_16x16x32_bf16 v[94:97], v[154:157], v[178:181], v[94:97]
	v_mfma_f32_16x16x32_bf16 v[78:81], v[150:153], v[182:185], v[78:81]
	v_mfma_f32_16x16x32_bf16 v[78:81], v[154:157], v[186:189], v[78:81]
	v_mfma_f32_16x16x32_bf16 v[70:73], v[150:153], v[190:193], v[70:73]
	v_mfma_f32_16x16x32_bf16 v[70:73], v[154:157], v[194:197], v[70:73]
	v_mfma_f32_16x16x32_bf16 v[66:69], v[158:161], v[190:193], v[66:69]
	v_mfma_f32_16x16x32_bf16 v[66:69], v[162:165], v[194:197], v[66:69]
	v_mfma_f32_16x16x32_bf16 v[74:77], v[158:161], v[182:185], v[74:77]
	v_mfma_f32_16x16x32_bf16 v[74:77], v[162:165], v[186:189], v[74:77]
	v_mfma_f32_16x16x32_bf16 v[86:89], v[158:161], v[174:177], v[86:89]
	v_mfma_f32_16x16x32_bf16 v[86:89], v[162:165], v[178:181], v[86:89]
	v_mfma_f32_16x16x32_bf16 v[102:105], v[158:161], v[166:169], v[102:105]
	v_mfma_f32_16x16x32_bf16 v[102:105], v[162:165], v[170:173], v[102:105]
	s_setprio 0
	s_barrier
	s_mov_b32 m0, s27
	s_mov_b32 s18, s14
	s_mov_b32 s19, s15
	ds_read_b128 v[166:169], v210 offset:16384
	ds_read_b128 v[170:173], v210 offset:17408
	ds_read_b128 v[174:177], v210 offset:18432
	ds_read_b128 v[178:181], v210 offset:19456
	ds_read_b128 v[182:185], v210 offset:20480
	ds_read_b128 v[186:189], v210 offset:21504
	ds_read_b128 v[190:193], v210 offset:22528
	ds_read_b128 v[194:197], v210 offset:23552
	buffer_load_dwordx4 v207, s[16:19], s85 offen lds
	s_add_i32 s86, s85, 0x158000
	s_mov_b32 m0, s30
	s_nop 0
	buffer_load_dwordx4 v207, s[16:19], s86 offen lds
	s_add_i32 s86, s85, 0x2b0000
	s_mov_b32 m0, s31
	s_nop 0
	buffer_load_dwordx4 v207, s[16:19], s86 offen lds
	s_add_i32 s86, s85, 0x408000
	s_mov_b32 m0, s50
	s_nop 0
	buffer_load_dwordx4 v207, s[16:19], s86 offen lds
	s_mov_b32 m0, s25
	s_add_i32 s86, s83, 0x158000
	buffer_load_dwordx4 v206, s[12:15], s83 offen lds
	s_mov_b32 m0, s51
	s_nop 0
	buffer_load_dwordx4 v206, s[12:15], s86 offen lds
	s_waitcnt vmcnt(8)
	s_waitcnt lgkmcnt(0)
	s_setprio 1
	v_mfma_f32_16x16x32_bf16 v[62:65], v[134:137], v[166:169], v[62:65]
	s_barrier
	v_mfma_f32_16x16x32_bf16 v[62:65], v[138:141], v[170:173], v[62:65]
	v_mfma_f32_16x16x32_bf16 v[54:57], v[134:137], v[174:177], v[54:57]
	v_mfma_f32_16x16x32_bf16 v[54:57], v[138:141], v[178:181], v[54:57]
	v_mfma_f32_16x16x32_bf16 v[42:45], v[134:137], v[182:185], v[42:45]
	v_mfma_f32_16x16x32_bf16 v[42:45], v[138:141], v[186:189], v[42:45]
	v_mfma_f32_16x16x32_bf16 v[26:29], v[134:137], v[190:193], v[26:29]
	v_mfma_f32_16x16x32_bf16 v[26:29], v[138:141], v[194:197], v[26:29]
	v_mfma_f32_16x16x32_bf16 v[18:21], v[142:145], v[190:193], v[18:21]
	v_mfma_f32_16x16x32_bf16 v[18:21], v[146:149], v[194:197], v[18:21]
	v_mfma_f32_16x16x32_bf16 v[34:37], v[142:145], v[182:185], v[34:37]
	v_mfma_f32_16x16x32_bf16 v[34:37], v[146:149], v[186:189], v[34:37]
	v_mfma_f32_16x16x32_bf16 v[50:53], v[142:145], v[174:177], v[50:53]
	v_mfma_f32_16x16x32_bf16 v[50:53], v[146:149], v[178:181], v[50:53]
	v_mfma_f32_16x16x32_bf16 v[58:61], v[142:145], v[166:169], v[58:61]
	v_mfma_f32_16x16x32_bf16 v[58:61], v[146:149], v[170:173], v[58:61]
	v_mfma_f32_16x16x32_bf16 v[46:49], v[150:153], v[166:169], v[46:49]
	v_mfma_f32_16x16x32_bf16 v[46:49], v[154:157], v[170:173], v[46:49]
	v_mfma_f32_16x16x32_bf16 v[30:33], v[150:153], v[174:177], v[30:33]
	v_mfma_f32_16x16x32_bf16 v[30:33], v[154:157], v[178:181], v[30:33]
	v_mfma_f32_16x16x32_bf16 v[14:17], v[150:153], v[182:185], v[14:17]
	v_mfma_f32_16x16x32_bf16 v[14:17], v[154:157], v[186:189], v[14:17]
	v_mfma_f32_16x16x32_bf16 v[6:9], v[150:153], v[190:193], v[6:9]
	v_mfma_f32_16x16x32_bf16 v[6:9], v[154:157], v[194:197], v[6:9]
	v_mfma_f32_16x16x32_bf16 v[2:5], v[158:161], v[190:193], v[2:5]
	v_mfma_f32_16x16x32_bf16 v[2:5], v[162:165], v[194:197], v[2:5]
	v_mfma_f32_16x16x32_bf16 v[10:13], v[158:161], v[182:185], v[10:13]
	v_mfma_f32_16x16x32_bf16 v[10:13], v[162:165], v[186:189], v[10:13]
	v_mfma_f32_16x16x32_bf16 v[22:25], v[158:161], v[174:177], v[22:25]
	v_mfma_f32_16x16x32_bf16 v[22:25], v[162:165], v[178:181], v[22:25]
	v_mfma_f32_16x16x32_bf16 v[38:41], v[158:161], v[166:169], v[38:41]
	v_mfma_f32_16x16x32_bf16 v[38:41], v[162:165], v[170:173], v[38:41]
	s_setprio 0
	s_barrier
	ds_read_b128 v[134:137], v211
	ds_read_b128 v[138:141], v211 offset:1024
	ds_read_b128 v[142:145], v211 offset:2048
	ds_read_b128 v[146:149], v211 offset:3072
	ds_read_b128 v[150:153], v212
	ds_read_b128 v[154:157], v212 offset:1024
	ds_read_b128 v[158:161], v212 offset:2048
	ds_read_b128 v[162:165], v212 offset:3072
	s_mov_b32 m0, s52
	s_add_i32 s86, s83, 0x2b0000
	ds_read_b128 v[166:169], v210 offset:32768
	ds_read_b128 v[170:173], v210 offset:33792
	ds_read_b128 v[174:177], v210 offset:34816
	ds_read_b128 v[178:181], v210 offset:35840
	ds_read_b128 v[182:185], v210 offset:36864
	ds_read_b128 v[186:189], v210 offset:37888
	ds_read_b128 v[190:193], v210 offset:38912
	ds_read_b128 v[194:197], v210 offset:39936
	buffer_load_dwordx4 v206, s[12:15], s86 offen lds
	s_add_i32 s86, s83, 0x408000
	s_mov_b32 m0, s53
	s_nop 0
	buffer_load_dwordx4 v206, s[12:15], s86 offen lds
	s_waitcnt vmcnt(8)
	s_waitcnt lgkmcnt(0)
	s_setprio 1
	v_mfma_f32_16x16x32_bf16 v[126:129], v[134:137], v[166:169], v[126:129]
	s_barrier
	v_mfma_f32_16x16x32_bf16 v[126:129], v[138:141], v[170:173], v[126:129]
	v_mfma_f32_16x16x32_bf16 v[118:121], v[134:137], v[174:177], v[118:121]
	v_mfma_f32_16x16x32_bf16 v[118:121], v[138:141], v[178:181], v[118:121]
	v_mfma_f32_16x16x32_bf16 v[106:109], v[134:137], v[182:185], v[106:109]
	v_mfma_f32_16x16x32_bf16 v[106:109], v[138:141], v[186:189], v[106:109]
	v_mfma_f32_16x16x32_bf16 v[90:93], v[134:137], v[190:193], v[90:93]
	v_mfma_f32_16x16x32_bf16 v[90:93], v[138:141], v[194:197], v[90:93]
	v_mfma_f32_16x16x32_bf16 v[82:85], v[142:145], v[190:193], v[82:85]
	v_mfma_f32_16x16x32_bf16 v[82:85], v[146:149], v[194:197], v[82:85]
	v_mfma_f32_16x16x32_bf16 v[98:101], v[142:145], v[182:185], v[98:101]
	v_mfma_f32_16x16x32_bf16 v[98:101], v[146:149], v[186:189], v[98:101]
	v_mfma_f32_16x16x32_bf16 v[114:117], v[142:145], v[174:177], v[114:117]
	v_mfma_f32_16x16x32_bf16 v[114:117], v[146:149], v[178:181], v[114:117]
	v_mfma_f32_16x16x32_bf16 v[122:125], v[142:145], v[166:169], v[122:125]
	v_mfma_f32_16x16x32_bf16 v[122:125], v[146:149], v[170:173], v[122:125]
	v_mfma_f32_16x16x32_bf16 v[110:113], v[150:153], v[166:169], v[110:113]
	v_mfma_f32_16x16x32_bf16 v[110:113], v[154:157], v[170:173], v[110:113]
	v_mfma_f32_16x16x32_bf16 v[94:97], v[150:153], v[174:177], v[94:97]
	v_mfma_f32_16x16x32_bf16 v[94:97], v[154:157], v[178:181], v[94:97]
	v_mfma_f32_16x16x32_bf16 v[78:81], v[150:153], v[182:185], v[78:81]
	v_mfma_f32_16x16x32_bf16 v[78:81], v[154:157], v[186:189], v[78:81]
	v_mfma_f32_16x16x32_bf16 v[70:73], v[150:153], v[190:193], v[70:73]
	v_mfma_f32_16x16x32_bf16 v[70:73], v[154:157], v[194:197], v[70:73]
	v_mfma_f32_16x16x32_bf16 v[66:69], v[158:161], v[190:193], v[66:69]
	v_mfma_f32_16x16x32_bf16 v[66:69], v[162:165], v[194:197], v[66:69]
	v_mfma_f32_16x16x32_bf16 v[74:77], v[158:161], v[182:185], v[74:77]
	v_mfma_f32_16x16x32_bf16 v[74:77], v[162:165], v[186:189], v[74:77]
	v_mfma_f32_16x16x32_bf16 v[86:89], v[158:161], v[174:177], v[86:89]
	v_mfma_f32_16x16x32_bf16 v[86:89], v[162:165], v[178:181], v[86:89]
	v_mfma_f32_16x16x32_bf16 v[102:105], v[158:161], v[166:169], v[102:105]
	v_mfma_f32_16x16x32_bf16 v[102:105], v[162:165], v[170:173], v[102:105]
	s_setprio 0
	s_barrier
	s_mov_b32 m0, s57
	s_or_b32 s86, s85, 0x80
	ds_read_b128 v[166:169], v210 offset:49152
	ds_read_b128 v[170:173], v210 offset:50176
	ds_read_b128 v[174:177], v210 offset:51200
	ds_read_b128 v[178:181], v210 offset:52224
	ds_read_b128 v[182:185], v210 offset:53248
	ds_read_b128 v[186:189], v210 offset:54272
	ds_read_b128 v[190:193], v210 offset:55296
	ds_read_b128 v[194:197], v210 offset:56320
	buffer_load_dwordx4 v207, s[16:19], s86 offen lds
	s_add_i32 s86, s85, 0x158080
	s_mov_b32 m0, s58
	s_add_i32 s83, s83, 0x158080
	buffer_load_dwordx4 v207, s[16:19], s86 offen lds
	s_add_i32 s86, s85, 0x2b0080
	s_mov_b32 m0, s61
	s_add_i32 s85, s85, 0x408080
	buffer_load_dwordx4 v207, s[16:19], s86 offen lds
	s_mov_b32 m0, s62
	s_nop 0
	buffer_load_dwordx4 v207, s[16:19], s85 offen lds
	s_mov_b32 m0, s59
	s_nop 0
	buffer_load_dwordx4 v206, s[12:15], s84 offen lds
	s_mov_b32 m0, s60
	s_nop 0
	buffer_load_dwordx4 v206, s[12:15], s83 offen lds
	s_waitcnt vmcnt(8)
	s_waitcnt lgkmcnt(0)
	s_setprio 1
	v_mfma_f32_16x16x32_bf16 v[62:65], v[134:137], v[166:169], v[62:65]
	s_barrier
	v_mfma_f32_16x16x32_bf16 v[62:65], v[138:141], v[170:173], v[62:65]
	v_mfma_f32_16x16x32_bf16 v[54:57], v[134:137], v[174:177], v[54:57]
	v_mfma_f32_16x16x32_bf16 v[54:57], v[138:141], v[178:181], v[54:57]
	v_mfma_f32_16x16x32_bf16 v[42:45], v[134:137], v[182:185], v[42:45]
	v_mfma_f32_16x16x32_bf16 v[42:45], v[138:141], v[186:189], v[42:45]
	v_mfma_f32_16x16x32_bf16 v[26:29], v[134:137], v[190:193], v[26:29]
	v_mfma_f32_16x16x32_bf16 v[26:29], v[138:141], v[194:197], v[26:29]
	v_mfma_f32_16x16x32_bf16 v[18:21], v[142:145], v[190:193], v[18:21]
	v_mfma_f32_16x16x32_bf16 v[18:21], v[146:149], v[194:197], v[18:21]
	v_mfma_f32_16x16x32_bf16 v[34:37], v[142:145], v[182:185], v[34:37]
	v_mfma_f32_16x16x32_bf16 v[34:37], v[146:149], v[186:189], v[34:37]
	v_mfma_f32_16x16x32_bf16 v[50:53], v[142:145], v[174:177], v[50:53]
	v_mfma_f32_16x16x32_bf16 v[50:53], v[146:149], v[178:181], v[50:53]
	v_mfma_f32_16x16x32_bf16 v[58:61], v[142:145], v[166:169], v[58:61]
	v_mfma_f32_16x16x32_bf16 v[58:61], v[146:149], v[170:173], v[58:61]
	v_mfma_f32_16x16x32_bf16 v[46:49], v[150:153], v[166:169], v[46:49]
	v_mfma_f32_16x16x32_bf16 v[46:49], v[154:157], v[170:173], v[46:49]
	v_mfma_f32_16x16x32_bf16 v[30:33], v[150:153], v[174:177], v[30:33]
	v_mfma_f32_16x16x32_bf16 v[30:33], v[154:157], v[178:181], v[30:33]
	v_mfma_f32_16x16x32_bf16 v[14:17], v[150:153], v[182:185], v[14:17]
	v_mfma_f32_16x16x32_bf16 v[14:17], v[154:157], v[186:189], v[14:17]
	v_mfma_f32_16x16x32_bf16 v[6:9], v[150:153], v[190:193], v[6:9]
	v_mfma_f32_16x16x32_bf16 v[6:9], v[154:157], v[194:197], v[6:9]
	v_mfma_f32_16x16x32_bf16 v[2:5], v[158:161], v[190:193], v[2:5]
	v_mfma_f32_16x16x32_bf16 v[2:5], v[162:165], v[194:197], v[2:5]
	v_mfma_f32_16x16x32_bf16 v[10:13], v[158:161], v[182:185], v[10:13]
	v_mfma_f32_16x16x32_bf16 v[10:13], v[162:165], v[186:189], v[10:13]
	v_mfma_f32_16x16x32_bf16 v[22:25], v[158:161], v[174:177], v[22:25]
	v_mfma_f32_16x16x32_bf16 v[22:25], v[162:165], v[178:181], v[22:25]
	v_mfma_f32_16x16x32_bf16 v[38:41], v[158:161], v[166:169], v[38:41]
	v_mfma_f32_16x16x32_bf16 v[38:41], v[162:165], v[170:173], v[38:41]
	s_setprio 0
	s_barrier
	s_add_i32 s82, s82, 2
	s_addk_i32 s80, 0x100
	s_addk_i32 s81, 0x100
	s_cmp_ge_i32 s82, s3
	s_cbranch_scc0 .LBB0_1519
	v_pk_mul_f32 v[182:183], v[128:129], 0.5 op_sel_hi:[1,0]
	v_pk_mul_f32 v[184:185], v[126:127], 0.5 op_sel_hi:[1,0]
	v_pk_mul_f32 v[186:187], v[124:125], 0.5 op_sel_hi:[1,0]
	v_pk_mul_f32 v[188:189], v[122:123], 0.5 op_sel_hi:[1,0]
	v_pk_mul_f32 v[196:197], v[112:113], 0.5 op_sel_hi:[1,0]
	v_pk_mul_f32 v[194:195], v[110:111], 0.5 op_sel_hi:[1,0]
	v_pk_mul_f32 v[192:193], v[104:105], 0.5 op_sel_hi:[1,0]
	v_pk_mul_f32 v[190:191], v[102:103], 0.5 op_sel_hi:[1,0]
	v_pk_mul_f32 v[180:181], v[120:121], 0.5 op_sel_hi:[1,0]
	v_pk_mul_f32 v[178:179], v[118:119], 0.5 op_sel_hi:[1,0]
	v_pk_mul_f32 v[176:177], v[116:117], 0.5 op_sel_hi:[1,0]
	v_pk_mul_f32 v[174:175], v[114:115], 0.5 op_sel_hi:[1,0]
	v_pk_mul_f32 v[170:171], v[96:97], 0.5 op_sel_hi:[1,0]
	v_pk_mul_f32 v[168:169], v[94:95], 0.5 op_sel_hi:[1,0]
	v_pk_mul_f32 v[166:167], v[88:89], 0.5 op_sel_hi:[1,0]
	v_pk_mul_f32 v[164:165], v[86:87], 0.5 op_sel_hi:[1,0]
	v_pk_mul_f32 v[162:163], v[108:109], 0.5 op_sel_hi:[1,0]
	v_pk_mul_f32 v[160:161], v[106:107], 0.5 op_sel_hi:[1,0]
	v_pk_mul_f32 v[158:159], v[100:101], 0.5 op_sel_hi:[1,0]
	v_pk_mul_f32 v[156:157], v[98:99], 0.5 op_sel_hi:[1,0]
	v_pk_mul_f32 v[154:155], v[80:81], 0.5 op_sel_hi:[1,0]
	v_pk_mul_f32 v[152:153], v[78:79], 0.5 op_sel_hi:[1,0]
	v_pk_mul_f32 v[150:151], v[76:77], 0.5 op_sel_hi:[1,0]
	v_pk_mul_f32 v[148:149], v[74:75], 0.5 op_sel_hi:[1,0]
	v_pk_mul_f32 v[144:145], v[92:93], 0.5 op_sel_hi:[1,0]
	v_pk_mul_f32 v[142:143], v[90:91], 0.5 op_sel_hi:[1,0]
	v_pk_mul_f32 v[140:141], v[84:85], 0.5 op_sel_hi:[1,0]
	v_pk_mul_f32 v[138:139], v[82:83], 0.5 op_sel_hi:[1,0]
	v_pk_mul_f32 v[136:137], v[72:73], 0.5 op_sel_hi:[1,0]
	v_pk_mul_f32 v[134:135], v[70:71], 0.5 op_sel_hi:[1,0]
	v_pk_mul_f32 v[128:129], v[68:69], 0.5 op_sel_hi:[1,0]
	v_pk_mul_f32 v[126:127], v[66:67], 0.5 op_sel_hi:[1,0]
	v_pk_mul_f32 v[122:123], v[64:65], 0.5 op_sel_hi:[1,0]
	v_pk_mul_f32 v[120:121], v[62:63], 0.5 op_sel_hi:[1,0]
	v_pk_mul_f32 v[118:119], v[60:61], 0.5 op_sel_hi:[1,0]
	v_pk_mul_f32 v[116:117], v[58:59], 0.5 op_sel_hi:[1,0]
	v_pk_mul_f32 v[112:113], v[48:49], 0.5 op_sel_hi:[1,0]
	v_pk_mul_f32 v[110:111], v[46:47], 0.5 op_sel_hi:[1,0]
	v_pk_mul_f32 v[108:109], v[40:41], 0.5 op_sel_hi:[1,0]
	v_pk_mul_f32 v[106:107], v[38:39], 0.5 op_sel_hi:[1,0]
	v_pk_mul_f32 v[104:105], v[56:57], 0.5 op_sel_hi:[1,0]
	v_pk_mul_f32 v[102:103], v[54:55], 0.5 op_sel_hi:[1,0]
	v_pk_mul_f32 v[100:101], v[52:53], 0.5 op_sel_hi:[1,0]
	v_pk_mul_f32 v[98:99], v[50:51], 0.5 op_sel_hi:[1,0]
	v_pk_mul_f32 v[96:97], v[32:33], 0.5 op_sel_hi:[1,0]
	v_pk_mul_f32 v[94:95], v[30:31], 0.5 op_sel_hi:[1,0]
	v_pk_mul_f32 v[92:93], v[24:25], 0.5 op_sel_hi:[1,0]
	v_pk_mul_f32 v[90:91], v[22:23], 0.5 op_sel_hi:[1,0]
	v_pk_mul_f32 v[88:89], v[44:45], 0.5 op_sel_hi:[1,0]
	v_pk_mul_f32 v[86:87], v[42:43], 0.5 op_sel_hi:[1,0]
	v_pk_mul_f32 v[84:85], v[36:37], 0.5 op_sel_hi:[1,0]
	v_pk_mul_f32 v[82:83], v[34:35], 0.5 op_sel_hi:[1,0]
	v_pk_mul_f32 v[80:81], v[16:17], 0.5 op_sel_hi:[1,0]
	v_pk_mul_f32 v[78:79], v[14:15], 0.5 op_sel_hi:[1,0]
	v_pk_mul_f32 v[76:77], v[12:13], 0.5 op_sel_hi:[1,0]
	v_pk_mul_f32 v[74:75], v[10:11], 0.5 op_sel_hi:[1,0]
	v_pk_mul_f32 v[72:73], v[28:29], 0.5 op_sel_hi:[1,0]
	v_pk_mul_f32 v[70:71], v[26:27], 0.5 op_sel_hi:[1,0]
	v_pk_mul_f32 v[68:69], v[20:21], 0.5 op_sel_hi:[1,0]
	v_pk_mul_f32 v[66:67], v[18:19], 0.5 op_sel_hi:[1,0]
	v_pk_mul_f32 v[64:65], v[8:9], 0.5 op_sel_hi:[1,0]
	v_pk_mul_f32 v[62:63], v[6:7], 0.5 op_sel_hi:[1,0]
	v_pk_mul_f32 v[60:61], v[4:5], 0.5 op_sel_hi:[1,0]
	v_pk_mul_f32 v[58:59], v[2:3], 0.5 op_sel_hi:[1,0]
	s_and_b64 vcc, exec, s[40:41]
	s_cbranch_vccz .LBB0_1522
